# peeled first K-iteration after epilogue in FFN1-in/in-proj/FFN2-in GEMMs (no accumulator zeroing, first two waits vmcnt(8+S)) + NSA tile LDS hoist + WINROWS dead-store removal
# speedup vs baseline: 1.0144x; 1.0144x over previous
; #define PG8_STAGE(bufoff, gbase, voff) do { _Pragma("unroll") for (int _i = 0; _i < 2; ++_i) \
;         __builtin_amdgcn_global_load_lds((const unsigned*)((const char*)(gbase) + (voff)[_i]), (PG8_LAS unsigned*)(lds + (bufoff) + ldsw + _i * 8192), 16, 0, 0); } while (0)
; #define PG8_WAIT_V(n) asm volatile("s_waitcnt vmcnt(" #n ")" ::: "memory")
; #define PG8_BAR __builtin_amdgcn_s_barrier()
; template <class Epi, class Sched, bool ALIGN_EPI = false, bool SP2 = false>
; __device__ __forceinline__ void gemm_phase(PG8_LAS unsigned char* lds, const Gemm g, const Sched& S, const Epi& E) {
;     ...
;     const int aoff = lds_byte(wr * 64 + fr, fq * 8), boff = lds_byte(wc * 32 + fr, fq * 8);
;     ...
;         PG8_STAGE(PG8_SB(0, 0), cB, voffB); PG8_STAGE(PG8_SB(0, 1), cB + hstep, voffB); PG8_STAGE(PG8_SA(0, 0), cA, voffA); PG8_STAGE(PG8_SA(0, 1), cA + hstep, voffA);
;         if (wr == 1) PG8_BAR;
;         PG8_WAIT_V(2); PG8_BAR;
;         PG8_STAGE(PG8_SB(1, 0), cB + kstep, voffB); PG8_STAGE(PG8_SA(1, 0), cA + kstep, voffA); PG8_STAGE(PG8_SB(1, 1), cB + hstep + kstep, voffB);
;         PG8_WAIT_V(6); PG8_BAR;
.LBB0_94:
	s_lshl_b32 s12, s12, 5
	s_and_b32 s18, s12, 0x60
	s_mov_b64 s[12:13], 0x80
	s_add_i32 m0, s53, 0x18000
	v_lshl_add_u64 v[8:9], v[8:9], 0, s[12:13]
	s_lshl_b32 s15, s14, 13
	s_lshl_b32 s19, s18, 7
	s_waitcnt vmcnt(2)
	s_barrier
	global_load_lds_dwordx4 v[8:9], off
	v_lshl_add_u64 v[6:7], v[6:7], 0, s[12:13]
	s_add_i32 m0, s53, 0x1a000
	s_add_i32 s58, s53, 0x8000
	s_add_i32 s59, s53, 0xa000
	global_load_lds_dwordx4 v[6:7], off
	v_lshl_add_u64 v[2:3], v[2:3], 0, s[12:13]
	s_mov_b32 m0, s58
	s_add_u32 s16, s34, 0x80080
	global_load_lds_dwordx4 v[2:3], off
	v_lshl_add_u64 v[2:3], v[4:5], 0, s[12:13]
	s_mov_b32 m0, s59
	s_addc_u32 s17, s35, 0
	global_load_lds_dwordx4 v[2:3], off
	s_add_i32 m0, s53, 0x1c000
	v_lshl_add_u64 v[2:3], s[16:17], 0, v[134:135]
	global_load_lds_dwordx4 v[2:3], off
	v_lshl_add_u64 v[2:3], s[16:17], 0, v[130:131]
	s_add_i32 m0, s53, 0x1e000
	s_cmpk_lt_u32 s1, 0x100
	global_load_lds_dwordx4 v[2:3], off
	v_lshrrev_b32_e32 v3, 1, v12
	v_and_b32_e32 v3, 24, v3
	v_and_b32_e32 v2, 15, v12
	v_lshlrev_b32_e32 v4, 1, v3
	v_lshl_or_b32 v147, s14, 6, v2
	v_lshl_or_b32 v2, v2, 6, v4
	v_lshlrev_b32_e32 v4, 2, v12
	v_and_b32_e32 v4, 32, v4
	v_bitop3_b32 v5, v2, s15, v4 bitop3:0xde
	v_bitop3_b32 v148, v2, s19, v4 bitop3:0xde
	v_lshlrev_b32_e32 v2, 15, v15
	v_and_b32_e32 v2, 0xffff0000, v2
	v_or_b32_e32 v149, s18, v3
	v_lshl_add_u32 v2, v14, 12, v2
	v_and_b32_e32 v3, 1, v15
	v_lshl_or_b32 v2, v3, 6, v2
	v_lshl_add_u32 v138, v16, 1, v2
	v_lshlrev_b32_e32 v2, 15, v10
	v_and_b32_e32 v2, 0xffff0000, v2
	s_waitcnt vmcnt(6)
	v_lshl_add_u32 v2, v11, 12, v2
	v_and_b32_e32 v3, 1, v10
	s_cselect_b64 s[14:15], -1, 0
	v_lshl_or_b32 v2, v3, 6, v2
	s_add_i32 s61, 0, 0x10000
	s_add_i32 s62, 0, 0x14000
	s_sext_i32_i16 s25, s0
	s_ashr_i32 s60, s78, 31
	v_mov_b32_e32 v139, v135
	v_lshl_add_u32 v140, v13, 1, v2
	v_mov_b32_e32 v141, v135
	v_mov_b64_e32 v[142:143], 0xbb0
	v_mov_b64_e32 v[144:145], 0xbaf
	v_add_u32_e32 v150, s61, v148
	v_add_u32_e32 v151, s62, v148
	v_add_u32_e32 v152, 0, v5
	s_movk_i32 s63, 0x2c00
	s_barrier
	s_mov_b32 s98, 0
	s_branch .LBB0_97

; #define PG8_STAGE(bufoff, gbase, voff) do { _Pragma("unroll") for (int _i = 0; _i < 2; ++_i) \
;         __builtin_amdgcn_global_load_lds((const unsigned*)((const char*)(gbase) + (voff)[_i]), (PG8_LAS unsigned*)(lds + (bufoff) + ldsw + _i * 8192), 16, 0, 0); } while (0)
; #define PG8_LDA(dst, b, h) do { _Pragma("unroll") for (int m = 0; m < 4; ++m) _Pragma("unroll") for (int k = 0; k < 2; ++k) dst[m][k] = *(const PG8_LAS bf16x8*)(lds + PG8_SA(b, h) + aoff + m * 2048 + k * 1024); } while (0)
; #define PG8_LDB(dst, b, h) do { _Pragma("unroll") for (int n = 0; n < 2; ++n) _Pragma("unroll") for (int k = 0; k < 2; ++k) dst[n][k] = *(const PG8_LAS bf16x8*)(lds + PG8_SB(b, h) + boff + n * 2048 + k * 1024); } while (0)
; #define PG8_MMA(ai, bj, At, Bt) do { __builtin_amdgcn_s_setprio(1); _Pragma("unroll") for (int m = 0; m < 4; ++m) _Pragma("unroll") for (int n = 0; n < 2; ++n) _Pragma("unroll") for (int k = 0; k < 2; ++k) \
;         acc[ai][bj][m][n] = __builtin_amdgcn_mfma_f32_16x16x32_bf16(Bt[n][k], At[m][k], acc[ai][bj][m][n], 0, 0, 0); __builtin_amdgcn_s_setprio(0); } while (0)
; #define PG8_WAIT_V(n) asm volatile("s_waitcnt vmcnt(" #n ")" ::: "memory")
; #define PG8_WAIT_L(n) asm volatile("s_waitcnt lgkmcnt(" #n ")" ::: "memory")
; template <class Epi, class Sched, bool ALIGN_EPI = false, bool SP2 = false>
; __device__ __forceinline__ void gemm_phase(PG8_LAS unsigned char* lds, const Gemm g, const Sched& S, const Epi& E) {
;     ...
;         const bool has_next = S.next(ui + 1, nxt);
;         const char* nA = has_next ? (const char*)g.A + (size_t)nxt.pm * tstep + nxt.kb : cA; const char* nB = has_next ? (const char*)g.Bt + (size_t)nxt.pn * tstep + nxt.kb : cB;
;         for (int t = 0; t < nt; t += 2) {
;             const bool last = (t == nt - 2);
;             const char* a1 = cA + (size_t)(t + 1) * kstep;
;             const char* a2 = last ? nA : cA + (size_t)(t + 2) * kstep; const char* b2 = last ? nB : cB + (size_t)(t + 2) * kstep;
;             const char* a3 = a2 + kstep; const char* b3 = b2 + kstep;
;             if (last && has_next) S.a_ready(nxt);
;             if constexpr (SP2) {
;             PG8_LDB(B0, 0, 0); PG8_LDB(B1, 0, 1); PG8_SCHED; PG8_LDA(At, 0, 0); PG8_STAGE(PG8_SA(1, 1), a1 + hstep, voffA);
;             PG8_WAIT_V(8); PG8_WAIT_L(0); PG8_BAR; PG8_MMA(0, 0, At, B0); PG8_MMA(0, 1, At, B1); PG8_BAR; PG8_SCHED;
.LBB0_99:
	s_ashr_i32 s19, s18, 31
	s_lshl_b64 s[20:21], s[18:19], 20
	v_readlane_b32 s22, v253, 41
	v_readlane_b32 s23, v253, 42
	s_add_u32 s20, s22, s20
	s_addc_u32 s21, s23, s21
	s_and_b64 s[22:23], s[0:1], exec
	s_cselect_b32 s19, s21, s27
	s_cselect_b32 s64, s20, s26
	s_ashr_i32 s17, s16, 31
	s_lshl_b64 s[22:23], s[16:17], 20
	s_add_u32 s22, s6, s22
	s_addc_u32 s23, s7, s23
	s_and_b64 s[50:51], s[0:1], exec
	s_cselect_b32 s17, s23, s35
	s_cselect_b32 s65, s22, s34
	s_add_u32 s26, s26, 0x80080
	s_addc_u32 s27, s27, 0
	s_add_u32 s66, s34, 0x100
	v_mov_b32_e32 v2, 0
	s_addc_u32 s67, s35, 0
	s_mov_b32 s68, -2
	s_cmp_lg_u32 s98, 0
	s_cbranch_scc1 .Lpeel_0
	v_mov_b32_e32 v3, v2
	v_mov_b32_e32 v4, v2
	v_mov_b32_e32 v5, v2
	v_mov_b32_e32 v10, v2
	v_mov_b32_e32 v11, v2
	v_mov_b32_e32 v12, v2
	v_mov_b32_e32 v13, v2
	v_mov_b32_e32 v18, v2
	v_mov_b32_e32 v19, v2
	v_mov_b32_e32 v20, v2
	v_mov_b32_e32 v21, v2
	v_mov_b32_e32 v26, v2
	v_mov_b32_e32 v27, v2
	v_mov_b32_e32 v28, v2
	v_mov_b32_e32 v29, v2
	v_mov_b32_e32 v34, v2
	v_mov_b32_e32 v35, v2
	v_mov_b32_e32 v36, v2
	v_mov_b32_e32 v37, v2
	v_mov_b32_e32 v42, v2
	v_mov_b32_e32 v43, v2
	v_mov_b32_e32 v44, v2
	v_mov_b32_e32 v45, v2
	v_mov_b32_e32 v50, v2
	v_mov_b32_e32 v51, v2
	v_mov_b32_e32 v52, v2
	v_mov_b32_e32 v53, v2
	v_mov_b32_e32 v58, v2
	v_mov_b32_e32 v59, v2
	v_mov_b32_e32 v60, v2
	v_mov_b32_e32 v61, v2
	v_mov_b32_e32 v6, v2
	v_mov_b32_e32 v7, v2
	v_mov_b32_e32 v8, v2
	v_mov_b32_e32 v9, v2
	v_mov_b32_e32 v14, v2
	v_mov_b32_e32 v15, v2
	v_mov_b32_e32 v16, v2
	v_mov_b32_e32 v17, v2
	v_mov_b32_e32 v22, v2
	v_mov_b32_e32 v23, v2
	v_mov_b32_e32 v24, v2
	v_mov_b32_e32 v25, v2
	v_mov_b32_e32 v30, v2
	v_mov_b32_e32 v31, v2
	v_mov_b32_e32 v32, v2
	v_mov_b32_e32 v33, v2
	v_mov_b32_e32 v38, v2
	v_mov_b32_e32 v39, v2
	v_mov_b32_e32 v40, v2
	v_mov_b32_e32 v41, v2
	v_mov_b32_e32 v46, v2
	v_mov_b32_e32 v47, v2
	v_mov_b32_e32 v48, v2
	v_mov_b32_e32 v49, v2
	v_mov_b32_e32 v54, v2
	v_mov_b32_e32 v55, v2
	v_mov_b32_e32 v56, v2
	v_mov_b32_e32 v57, v2
	v_mov_b32_e32 v62, v2
	v_mov_b32_e32 v63, v2
	v_mov_b32_e32 v64, v2
	v_mov_b32_e32 v65, v2
	v_mov_b32_e32 v66, v2
	v_mov_b32_e32 v67, v2
	v_mov_b32_e32 v68, v2
	v_mov_b32_e32 v69, v2
	v_mov_b32_e32 v74, v2
	v_mov_b32_e32 v75, v2
	v_mov_b32_e32 v76, v2
	v_mov_b32_e32 v77, v2
	v_mov_b32_e32 v82, v2
	v_mov_b32_e32 v83, v2
	v_mov_b32_e32 v84, v2
	v_mov_b32_e32 v85, v2
	v_mov_b32_e32 v90, v2
	v_mov_b32_e32 v91, v2
	v_mov_b32_e32 v92, v2
	v_mov_b32_e32 v93, v2
	v_mov_b32_e32 v98, v2
	v_mov_b32_e32 v99, v2
	v_mov_b32_e32 v100, v2
	v_mov_b32_e32 v101, v2
	v_mov_b32_e32 v106, v2
	v_mov_b32_e32 v107, v2
	v_mov_b32_e32 v108, v2
	v_mov_b32_e32 v109, v2
	v_mov_b32_e32 v114, v2
	v_mov_b32_e32 v115, v2
	v_mov_b32_e32 v116, v2
	v_mov_b32_e32 v117, v2
	v_mov_b32_e32 v122, v2
	v_mov_b32_e32 v123, v2
	v_mov_b32_e32 v124, v2
	v_mov_b32_e32 v125, v2
	v_mov_b32_e32 v70, v2
	v_mov_b32_e32 v71, v2
	v_mov_b32_e32 v72, v2
	v_mov_b32_e32 v73, v2
	v_mov_b32_e32 v78, v2
	v_mov_b32_e32 v79, v2
	v_mov_b32_e32 v80, v2
	v_mov_b32_e32 v81, v2
	v_mov_b32_e32 v86, v2
	v_mov_b32_e32 v87, v2
	v_mov_b32_e32 v88, v2
	v_mov_b32_e32 v89, v2
	v_mov_b32_e32 v94, v2
	v_mov_b32_e32 v95, v2
	v_mov_b32_e32 v96, v2
	v_mov_b32_e32 v97, v2
	v_mov_b32_e32 v102, v2
	v_mov_b32_e32 v103, v2
	v_mov_b32_e32 v104, v2
	v_mov_b32_e32 v105, v2
	v_mov_b32_e32 v110, v2
	v_mov_b32_e32 v111, v2
	v_mov_b32_e32 v112, v2
	v_mov_b32_e32 v113, v2
	v_mov_b32_e32 v118, v2
	v_mov_b32_e32 v119, v2
	v_mov_b32_e32 v120, v2
	v_mov_b32_e32 v121, v2
	v_mov_b32_e32 v126, v2
	v_mov_b32_e32 v127, v2
	v_mov_b32_e32 v128, v2
	v_mov_b32_e32 v129, v2
.LBB0_100:
	ds_read_b128 v[154:157], v150
	ds_read_b128 v[158:161], v150 offset:1024
	ds_read_b128 v[162:165], v150 offset:2048
	ds_read_b128 v[166:169], v150 offset:3072
	ds_read_b128 v[170:173], v151
	ds_read_b128 v[174:177], v151 offset:1024
	ds_read_b128 v[178:181], v151 offset:2048
	ds_read_b128 v[182:185], v151 offset:3072
	s_add_u32 s34, s26, 0xfff80080
	s_addc_u32 s35, s27, -1
	s_cmp_eq_u32 s68, 28
	s_cselect_b32 s51, s19, s35
	s_cselect_b32 s50, s64, s34
	s_cselect_b32 s35, s17, s67
	s_cselect_b32 s34, s65, s66
	v_lshl_add_u64 v[218:219], s[26:27], 0, v[138:139]
	s_add_i32 m0, s53, 0xc000
	ds_read_b128 v[186:189], v152
	ds_read_b128 v[190:193], v152 offset:1024
	ds_read_b128 v[194:197], v152 offset:2048
	ds_read_b128 v[198:201], v152 offset:3072
	ds_read_b128 v[202:205], v152 offset:4096
	ds_read_b128 v[206:209], v152 offset:5120
	ds_read_b128 v[210:213], v152 offset:6144
	ds_read_b128 v[214:217], v152 offset:7168
	global_load_lds_dwordx4 v[218:219], off
	v_lshl_add_u64 v[218:219], s[26:27], 0, v[140:141]
	s_add_i32 m0, s53, 0xe000
	s_nop 0
	global_load_lds_dwordx4 v[218:219], off
	s_waitcnt vmcnt(8)
	s_waitcnt lgkmcnt(0)
	s_barrier
; #define PG8_STAGE(bufoff, gbase, voff) do { _Pragma("unroll") for (int _i = 0; _i < 2; ++_i) \
;         __builtin_amdgcn_global_load_lds((const unsigned*)((const char*)(gbase) + (voff)[_i]), (PG8_LAS unsigned*)(lds + (bufoff) + ldsw + _i * 8192), 16, 0, 0); } while (0)
; #define PG8_LDA(dst, b, h) do { _Pragma("unroll") for (int m = 0; m < 4; ++m) _Pragma("unroll") for (int k = 0; k < 2; ++k) dst[m][k] = *(const PG8_LAS bf16x8*)(lds + PG8_SA(b, h) + aoff + m * 2048 + k * 1024); } while (0)
; #define PG8_MMA(ai, bj, At, Bt) do { __builtin_amdgcn_s_setprio(1); _Pragma("unroll") for (int m = 0; m < 4; ++m) _Pragma("unroll") for (int n = 0; n < 2; ++n) _Pragma("unroll") for (int k = 0; k < 2; ++k) \
;         acc[ai][bj][m][n] = __builtin_amdgcn_mfma_f32_16x16x32_bf16(Bt[n][k], At[m][k], acc[ai][bj][m][n], 0, 0, 0); __builtin_amdgcn_s_setprio(0); } while (0)
; #define PG8_WAIT_V(n) asm volatile("s_waitcnt vmcnt(" #n ")" ::: "memory")
; #define PG8_WAIT_L(n) asm volatile("s_waitcnt lgkmcnt(" #n ")" ::: "memory")
; #define PG8_BAR __builtin_amdgcn_s_barrier()
; #define PG8_SCHED __builtin_amdgcn_sched_barrier(0)
; template <class Epi, class Sched, bool ALIGN_EPI = false, bool SP2 = false>
; __device__ __forceinline__ void gemm_phase(PG8_LAS unsigned char* lds, const Gemm g, const Sched& S, const Epi& E) {
;     ...
;             PG8_WAIT_V(8); PG8_WAIT_L(0); PG8_BAR; PG8_MMA(0, 0, At, B0); PG8_MMA(0, 1, At, B1); PG8_BAR; PG8_SCHED;
;             PG8_LDA(At, 0, 1); PG8_STAGE(PG8_SB(0, 0), b2, voffB); PG8_STAGE(PG8_SB(0, 1), b2 + hstep, voffB); PG8_STAGE(PG8_SA(0, 0), a2, voffA);
;             PG8_WAIT_V(8); PG8_WAIT_L(0); PG8_BAR; PG8_MMA(1, 0, At, B0); PG8_MMA(1, 1, At, B1); PG8_BAR; PG8_SCHED;
	s_setprio 1
	s_waitcnt lgkmcnt(0)
	v_mfma_f32_16x16x32_bf16 v[126:129], v[154:157], v[186:189], v[126:129]
	v_mfma_f32_16x16x32_bf16 v[118:121], v[162:165], v[186:189], v[118:121]
	v_mfma_f32_16x16x32_bf16 v[110:113], v[154:157], v[194:197], v[110:113]
	v_mfma_f32_16x16x32_bf16 v[102:105], v[162:165], v[194:197], v[102:105]
	v_mfma_f32_16x16x32_bf16 v[94:97], v[154:157], v[202:205], v[94:97]
	v_mfma_f32_16x16x32_bf16 v[86:89], v[162:165], v[202:205], v[86:89]
	v_mfma_f32_16x16x32_bf16 v[78:81], v[154:157], v[210:213], v[78:81]
	v_mfma_f32_16x16x32_bf16 v[70:73], v[162:165], v[210:213], v[70:73]
	v_mfma_f32_16x16x32_bf16 v[126:129], v[158:161], v[190:193], v[126:129]
	v_mfma_f32_16x16x32_bf16 v[118:121], v[166:169], v[190:193], v[118:121]
	v_mfma_f32_16x16x32_bf16 v[110:113], v[158:161], v[198:201], v[110:113]
	v_mfma_f32_16x16x32_bf16 v[102:105], v[166:169], v[198:201], v[102:105]
	v_mfma_f32_16x16x32_bf16 v[94:97], v[158:161], v[206:209], v[94:97]
	v_mfma_f32_16x16x32_bf16 v[86:89], v[166:169], v[206:209], v[86:89]
	v_mfma_f32_16x16x32_bf16 v[78:81], v[158:161], v[214:217], v[78:81]
	v_mfma_f32_16x16x32_bf16 v[70:73], v[166:169], v[214:217], v[70:73]
	s_setprio 0
	s_setprio 1
	v_mfma_f32_16x16x32_bf16 v[122:125], v[170:173], v[186:189], v[122:125]
	v_mfma_f32_16x16x32_bf16 v[114:117], v[178:181], v[186:189], v[114:117]
	v_mfma_f32_16x16x32_bf16 v[106:109], v[170:173], v[194:197], v[106:109]
	v_mfma_f32_16x16x32_bf16 v[98:101], v[178:181], v[194:197], v[98:101]
	v_mfma_f32_16x16x32_bf16 v[90:93], v[170:173], v[202:205], v[90:93]
	v_mfma_f32_16x16x32_bf16 v[82:85], v[178:181], v[202:205], v[82:85]
	v_mfma_f32_16x16x32_bf16 v[74:77], v[170:173], v[210:213], v[74:77]
	v_mfma_f32_16x16x32_bf16 v[66:69], v[178:181], v[210:213], v[66:69]
	v_mfma_f32_16x16x32_bf16 v[122:125], v[174:177], v[190:193], v[122:125]
	v_mfma_f32_16x16x32_bf16 v[114:117], v[182:185], v[190:193], v[114:117]
	v_mfma_f32_16x16x32_bf16 v[106:109], v[174:177], v[198:201], v[106:109]
	v_mfma_f32_16x16x32_bf16 v[98:101], v[182:185], v[198:201], v[98:101]
	v_mfma_f32_16x16x32_bf16 v[90:93], v[174:177], v[206:209], v[90:93]
	v_mfma_f32_16x16x32_bf16 v[82:85], v[182:185], v[206:209], v[82:85]
	v_mfma_f32_16x16x32_bf16 v[74:77], v[174:177], v[214:217], v[74:77]
	v_mfma_f32_16x16x32_bf16 v[66:69], v[182:185], v[214:217], v[66:69]
	s_setprio 0
	s_barrier
	s_add_i32 s69, s61, s29
	v_lshl_add_u64 v[218:219], s[34:35], 0, v[134:135]
	s_mov_b32 m0, s69
	ds_read_b128 v[186:189], v152 offset:16384
	ds_read_b128 v[190:193], v152 offset:17408
	ds_read_b128 v[194:197], v152 offset:18432
	ds_read_b128 v[198:201], v152 offset:19456
	ds_read_b128 v[202:205], v152 offset:20480
	ds_read_b128 v[206:209], v152 offset:21504
	ds_read_b128 v[210:213], v152 offset:22528
	ds_read_b128 v[214:217], v152 offset:23552
	global_load_lds_dwordx4 v[218:219], off
	s_add_i32 m0, s69, 0x2000
	s_add_u32 s70, s34, 0x80000
	v_lshl_add_u64 v[220:221], s[34:35], 0, v[130:131]
	s_addc_u32 s71, s35, 0
	s_add_i32 s69, s62, s29
	global_load_lds_dwordx4 v[220:221], off
	v_lshl_add_u64 v[222:223], s[70:71], 0, v[134:135]
	s_mov_b32 m0, s69
	v_lshl_add_u64 v[224:225], s[50:51], 0, v[132:133]
	global_load_lds_dwordx4 v[222:223], off
	v_lshl_add_u64 v[222:223], s[70:71], 0, v[130:131]
	s_add_i32 m0, s69, 0x2000
	s_nop 0
	global_load_lds_dwordx4 v[222:223], off
	v_lshl_add_u64 v[222:223], s[50:51], 0, v[136:137]
	s_mov_b32 m0, s53
	s_nop 0
	global_load_lds_dwordx4 v[222:223], off
	s_mov_b32 m0, s54
	s_nop 0
	global_load_lds_dwordx4 v[224:225], off
	s_waitcnt vmcnt(8)
	s_waitcnt lgkmcnt(0)
	s_barrier
	s_setprio 1
	s_waitcnt lgkmcnt(0)
	v_mfma_f32_16x16x32_bf16 v[62:65], v[154:157], v[186:189], v[62:65]
	v_mfma_f32_16x16x32_bf16 v[54:57], v[162:165], v[186:189], v[54:57]
	v_mfma_f32_16x16x32_bf16 v[46:49], v[154:157], v[194:197], v[46:49]
	v_mfma_f32_16x16x32_bf16 v[38:41], v[162:165], v[194:197], v[38:41]
	v_mfma_f32_16x16x32_bf16 v[30:33], v[154:157], v[202:205], v[30:33]
	v_mfma_f32_16x16x32_bf16 v[22:25], v[162:165], v[202:205], v[22:25]
	v_mfma_f32_16x16x32_bf16 v[14:17], v[154:157], v[210:213], v[14:17]
	v_mfma_f32_16x16x32_bf16 v[6:9], v[162:165], v[210:213], v[6:9]
	v_mfma_f32_16x16x32_bf16 v[62:65], v[158:161], v[190:193], v[62:65]
	v_mfma_f32_16x16x32_bf16 v[54:57], v[166:169], v[190:193], v[54:57]
	v_mfma_f32_16x16x32_bf16 v[46:49], v[158:161], v[198:201], v[46:49]
	v_mfma_f32_16x16x32_bf16 v[38:41], v[166:169], v[198:201], v[38:41]
	v_mfma_f32_16x16x32_bf16 v[30:33], v[158:161], v[206:209], v[30:33]
	v_mfma_f32_16x16x32_bf16 v[22:25], v[166:169], v[206:209], v[22:25]
	v_mfma_f32_16x16x32_bf16 v[14:17], v[158:161], v[214:217], v[14:17]
	v_mfma_f32_16x16x32_bf16 v[6:9], v[166:169], v[214:217], v[6:9]
	s_setprio 0
	s_setprio 1
	v_mfma_f32_16x16x32_bf16 v[58:61], v[170:173], v[186:189], v[58:61]
	v_mfma_f32_16x16x32_bf16 v[50:53], v[178:181], v[186:189], v[50:53]
	v_mfma_f32_16x16x32_bf16 v[42:45], v[170:173], v[194:197], v[42:45]
	v_mfma_f32_16x16x32_bf16 v[34:37], v[178:181], v[194:197], v[34:37]
	v_mfma_f32_16x16x32_bf16 v[26:29], v[170:173], v[202:205], v[26:29]
	v_mfma_f32_16x16x32_bf16 v[18:21], v[178:181], v[202:205], v[18:21]
	v_mfma_f32_16x16x32_bf16 v[10:13], v[170:173], v[210:213], v[10:13]
	v_mfma_f32_16x16x32_bf16 v[2:5], v[178:181], v[210:213], v[2:5]
	v_mfma_f32_16x16x32_bf16 v[58:61], v[174:177], v[190:193], v[58:61]
	v_mfma_f32_16x16x32_bf16 v[50:53], v[182:185], v[190:193], v[50:53]
	v_mfma_f32_16x16x32_bf16 v[42:45], v[174:177], v[198:201], v[42:45]
	v_mfma_f32_16x16x32_bf16 v[34:37], v[182:185], v[198:201], v[34:37]
	v_mfma_f32_16x16x32_bf16 v[26:29], v[174:177], v[206:209], v[26:29]
	v_mfma_f32_16x16x32_bf16 v[18:21], v[182:185], v[206:209], v[18:21]
	v_mfma_f32_16x16x32_bf16 v[10:13], v[174:177], v[214:217], v[10:13]
	v_mfma_f32_16x16x32_bf16 v[2:5], v[182:185], v[214:217], v[2:5]
	s_setprio 0
	s_barrier
; #define PG8_STAGE(bufoff, gbase, voff) do { _Pragma("unroll") for (int _i = 0; _i < 2; ++_i) \
;         __builtin_amdgcn_global_load_lds((const unsigned*)((const char*)(gbase) + (voff)[_i]), (PG8_LAS unsigned*)(lds + (bufoff) + ldsw + _i * 8192), 16, 0, 0); } while (0)
; #define PG8_LDA(dst, b, h) do { _Pragma("unroll") for (int m = 0; m < 4; ++m) _Pragma("unroll") for (int k = 0; k < 2; ++k) dst[m][k] = *(const PG8_LAS bf16x8*)(lds + PG8_SA(b, h) + aoff + m * 2048 + k * 1024); } while (0)
; #define PG8_LDB(dst, b, h) do { _Pragma("unroll") for (int n = 0; n < 2; ++n) _Pragma("unroll") for (int k = 0; k < 2; ++k) dst[n][k] = *(const PG8_LAS bf16x8*)(lds + PG8_SB(b, h) + boff + n * 2048 + k * 1024); } while (0)
; #define PG8_MMA(ai, bj, At, Bt) do { __builtin_amdgcn_s_setprio(1); _Pragma("unroll") for (int m = 0; m < 4; ++m) _Pragma("unroll") for (int n = 0; n < 2; ++n) _Pragma("unroll") for (int k = 0; k < 2; ++k) \
;         acc[ai][bj][m][n] = __builtin_amdgcn_mfma_f32_16x16x32_bf16(Bt[n][k], At[m][k], acc[ai][bj][m][n], 0, 0, 0); __builtin_amdgcn_s_setprio(0); } while (0)
; #define PG8_WAIT_V(n) asm volatile("s_waitcnt vmcnt(" #n ")" ::: "memory")
; #define PG8_WAIT_L(n) asm volatile("s_waitcnt lgkmcnt(" #n ")" ::: "memory")
; #define PG8_BAR __builtin_amdgcn_s_barrier()
; #define PG8_SCHED __builtin_amdgcn_sched_barrier(0)
; template <class Epi, class Sched, bool ALIGN_EPI = false, bool SP2 = false>
; __device__ __forceinline__ void gemm_phase(PG8_LAS unsigned char* lds, const Gemm g, const Sched& S, const Epi& E) {
;     ...
;             PG8_LDB(B0, 1, 0); PG8_LDB(B1, 1, 1); PG8_SCHED; PG8_LDA(At, 1, 0); PG8_STAGE(PG8_SA(0, 1), a2 + hstep, voffA);
;             PG8_WAIT_V(8); PG8_WAIT_L(0); PG8_BAR; PG8_MMA(0, 0, At, B0); PG8_MMA(0, 1, At, B1); PG8_BAR; PG8_SCHED;
;             PG8_LDA(At, 1, 1); PG8_STAGE(PG8_SB(1, 0), b3, voffB); PG8_STAGE(PG8_SB(1, 1), b3 + hstep, voffB); PG8_STAGE(PG8_SA(1, 0), a3, voffA);
;             PG8_WAIT_V(8); PG8_WAIT_L(0); PG8_BAR; PG8_MMA(1, 0, At, B0); PG8_MMA(1, 1, At, B1); PG8_BAR; PG8_SCHED;
	s_add_i32 s69, 0, 0x18000
	v_add_u32_e32 v153, s69, v148
	s_add_i32 s70, 0, 0x1c000
	ds_read_b128 v[154:157], v153
	ds_read_b128 v[158:161], v153 offset:1024
	ds_read_b128 v[162:165], v153 offset:2048
	ds_read_b128 v[166:169], v153 offset:3072
	v_add_u32_e32 v153, s70, v148
	ds_read_b128 v[170:173], v153
	ds_read_b128 v[174:177], v153 offset:1024
	ds_read_b128 v[178:181], v153 offset:2048
	ds_read_b128 v[182:185], v153 offset:3072
	s_add_u32 s50, s50, 0x80000
	s_addc_u32 s51, s51, 0
	s_mov_b32 m0, s55
	v_lshl_add_u64 v[226:227], s[50:51], 0, v[136:137]
	ds_read_b128 v[186:189], v152 offset:32768
	ds_read_b128 v[190:193], v152 offset:33792
	ds_read_b128 v[194:197], v152 offset:34816
	ds_read_b128 v[198:201], v152 offset:35840
	ds_read_b128 v[202:205], v152 offset:36864
	ds_read_b128 v[206:209], v152 offset:37888
	ds_read_b128 v[210:213], v152 offset:38912
	ds_read_b128 v[214:217], v152 offset:39936
	global_load_lds_dwordx4 v[226:227], off
	v_lshl_add_u64 v[226:227], s[50:51], 0, v[132:133]
	s_mov_b32 m0, s56
	s_nop 0
	global_load_lds_dwordx4 v[226:227], off
	s_waitcnt vmcnt(8)
	s_waitcnt lgkmcnt(0)
	s_barrier
	s_setprio 1
	s_waitcnt lgkmcnt(0)
	v_mfma_f32_16x16x32_bf16 v[126:129], v[154:157], v[186:189], v[126:129]
	v_mfma_f32_16x16x32_bf16 v[118:121], v[162:165], v[186:189], v[118:121]
	v_mfma_f32_16x16x32_bf16 v[110:113], v[154:157], v[194:197], v[110:113]
	v_mfma_f32_16x16x32_bf16 v[102:105], v[162:165], v[194:197], v[102:105]
	v_mfma_f32_16x16x32_bf16 v[94:97], v[154:157], v[202:205], v[94:97]
	v_mfma_f32_16x16x32_bf16 v[86:89], v[162:165], v[202:205], v[86:89]
	v_mfma_f32_16x16x32_bf16 v[78:81], v[154:157], v[210:213], v[78:81]
	v_mfma_f32_16x16x32_bf16 v[70:73], v[162:165], v[210:213], v[70:73]
	v_mfma_f32_16x16x32_bf16 v[126:129], v[158:161], v[190:193], v[126:129]
	v_mfma_f32_16x16x32_bf16 v[118:121], v[166:169], v[190:193], v[118:121]
	v_mfma_f32_16x16x32_bf16 v[110:113], v[158:161], v[198:201], v[110:113]
	v_mfma_f32_16x16x32_bf16 v[102:105], v[166:169], v[198:201], v[102:105]
	v_mfma_f32_16x16x32_bf16 v[94:97], v[158:161], v[206:209], v[94:97]
	v_mfma_f32_16x16x32_bf16 v[86:89], v[166:169], v[206:209], v[86:89]
	v_mfma_f32_16x16x32_bf16 v[78:81], v[158:161], v[214:217], v[78:81]
	v_mfma_f32_16x16x32_bf16 v[70:73], v[166:169], v[214:217], v[70:73]
	s_setprio 0
	s_setprio 1
	v_mfma_f32_16x16x32_bf16 v[122:125], v[170:173], v[186:189], v[122:125]
	v_mfma_f32_16x16x32_bf16 v[114:117], v[178:181], v[186:189], v[114:117]
	v_mfma_f32_16x16x32_bf16 v[106:109], v[170:173], v[194:197], v[106:109]
	v_mfma_f32_16x16x32_bf16 v[98:101], v[178:181], v[194:197], v[98:101]
	v_mfma_f32_16x16x32_bf16 v[90:93], v[170:173], v[202:205], v[90:93]
	v_mfma_f32_16x16x32_bf16 v[82:85], v[178:181], v[202:205], v[82:85]
	v_mfma_f32_16x16x32_bf16 v[74:77], v[170:173], v[210:213], v[74:77]
	v_mfma_f32_16x16x32_bf16 v[66:69], v[178:181], v[210:213], v[66:69]
	v_mfma_f32_16x16x32_bf16 v[122:125], v[174:177], v[190:193], v[122:125]
	v_mfma_f32_16x16x32_bf16 v[114:117], v[182:185], v[190:193], v[114:117]
	v_mfma_f32_16x16x32_bf16 v[106:109], v[174:177], v[198:201], v[106:109]
	v_mfma_f32_16x16x32_bf16 v[98:101], v[182:185], v[198:201], v[98:101]
	v_mfma_f32_16x16x32_bf16 v[90:93], v[174:177], v[206:209], v[90:93]
	v_mfma_f32_16x16x32_bf16 v[82:85], v[182:185], v[206:209], v[82:85]
	v_mfma_f32_16x16x32_bf16 v[74:77], v[174:177], v[214:217], v[74:77]
	v_mfma_f32_16x16x32_bf16 v[66:69], v[182:185], v[214:217], v[66:69]
	s_setprio 0
	s_barrier
	s_add_i32 s50, s69, s29
	v_lshl_add_u64 v[218:219], v[218:219], 0, s[12:13]
	s_mov_b32 m0, s50
	ds_read_b128 v[186:189], v152 offset:49152
	ds_read_b128 v[190:193], v152 offset:50176
	ds_read_b128 v[194:197], v152 offset:51200
	ds_read_b128 v[198:201], v152 offset:52224
	ds_read_b128 v[202:205], v152 offset:53248
	ds_read_b128 v[206:209], v152 offset:54272
	ds_read_b128 v[210:213], v152 offset:55296
	ds_read_b128 v[214:217], v152 offset:56320
	global_load_lds_dwordx4 v[218:219], off
	s_add_i32 m0, s50, 0x2000
	s_add_u32 s34, s34, 0x80080
	v_lshl_add_u64 v[218:219], v[220:221], 0, s[12:13]
	s_addc_u32 s35, s35, 0
	s_add_i32 s50, s70, s29
	global_load_lds_dwordx4 v[218:219], off
	v_lshl_add_u64 v[218:219], s[34:35], 0, v[134:135]
	s_mov_b32 m0, s50
	s_nop 0
	global_load_lds_dwordx4 v[218:219], off
	v_lshl_add_u64 v[218:219], s[34:35], 0, v[130:131]
	s_add_i32 m0, s50, 0x2000
	s_nop 0
	global_load_lds_dwordx4 v[218:219], off
	v_lshl_add_u64 v[218:219], v[222:223], 0, s[12:13]
	s_mov_b32 m0, s58
	s_nop 0
	global_load_lds_dwordx4 v[218:219], off
	v_lshl_add_u64 v[218:219], v[224:225], 0, s[12:13]
	s_mov_b32 m0, s59
	s_nop 0
	global_load_lds_dwordx4 v[218:219], off
	s_waitcnt vmcnt(8)
	s_waitcnt lgkmcnt(0)
	s_barrier
; #define PG8_STAGE(bufoff, gbase, voff) do { _Pragma("unroll") for (int _i = 0; _i < 2; ++_i) \
;         __builtin_amdgcn_global_load_lds((const unsigned*)((const char*)(gbase) + (voff)[_i]), (PG8_LAS unsigned*)(lds + (bufoff) + ldsw + _i * 8192), 16, 0, 0); } while (0)
; #define PG8_LDA(dst, b, h) do { _Pragma("unroll") for (int m = 0; m < 4; ++m) _Pragma("unroll") for (int k = 0; k < 2; ++k) dst[m][k] = *(const PG8_LAS bf16x8*)(lds + PG8_SA(b, h) + aoff + m * 2048 + k * 1024); } while (0)
; #define PG8_LDB(dst, b, h) do { _Pragma("unroll") for (int n = 0; n < 2; ++n) _Pragma("unroll") for (int k = 0; k < 2; ++k) dst[n][k] = *(const PG8_LAS bf16x8*)(lds + PG8_SB(b, h) + boff + n * 2048 + k * 1024); } while (0)
; #define PG8_MMA(ai, bj, At, Bt) do { __builtin_amdgcn_s_setprio(1); _Pragma("unroll") for (int m = 0; m < 4; ++m) _Pragma("unroll") for (int n = 0; n < 2; ++n) _Pragma("unroll") for (int k = 0; k < 2; ++k) \
;         acc[ai][bj][m][n] = __builtin_amdgcn_mfma_f32_16x16x32_bf16(Bt[n][k], At[m][k], acc[ai][bj][m][n], 0, 0, 0); __builtin_amdgcn_s_setprio(0); } while (0)
; #define PG8_WAIT_V(n) asm volatile("s_waitcnt vmcnt(" #n ")" ::: "memory")
; #define PG8_WAIT_L(n) asm volatile("s_waitcnt lgkmcnt(" #n ")" ::: "memory")
; #define PG8_BAR __builtin_amdgcn_s_barrier()
; template <class Epi, class Sched, bool ALIGN_EPI = false, bool SP2 = false>
; __device__ __forceinline__ void gemm_phase(PG8_LAS unsigned char* lds, const Gemm g, const Sched& S, const Epi& E) {
;     ...
;             PG8_WAIT_V(8); PG8_WAIT_L(0); PG8_BAR; PG8_MMA(0, 0, At, B0); PG8_MMA(0, 1, At, B1); PG8_BAR; PG8_SCHED;
;             PG8_LDA(At, 0, 1); PG8_STAGE(PG8_SB(0, 0), b2, voffB); PG8_STAGE(PG8_SB(0, 1), b2 + hstep, voffB); PG8_STAGE(PG8_SA(0, 0), a2, voffA);
;             PG8_WAIT_V(8); PG8_WAIT_L(0); PG8_BAR; PG8_MMA(1, 0, At, B0); PG8_MMA(1, 1, At, B1); PG8_BAR; PG8_SCHED;
;             PG8_LDB(B0, 1, 0); PG8_LDB(B1, 1, 1); PG8_SCHED; PG8_LDA(At, 1, 0); PG8_STAGE(PG8_SA(0, 1), a2 + hstep, voffA);
;             PG8_WAIT_V(8); PG8_WAIT_L(0); PG8_BAR; PG8_MMA(0, 0, At, B0); PG8_MMA(0, 1, At, B1); PG8_BAR; PG8_SCHED;
;             PG8_LDA(At, 1, 1); PG8_STAGE(PG8_SB(1, 0), b3, voffB); PG8_STAGE(PG8_SB(1, 1), b3 + hstep, voffB); PG8_STAGE(PG8_SA(1, 0), a3, voffA);
;             PG8_WAIT_V(8); PG8_WAIT_L(0); PG8_BAR; PG8_MMA(1, 0, At, B0); PG8_MMA(1, 1, At, B1); PG8_BAR; PG8_SCHED;
	s_setprio 1
	s_waitcnt lgkmcnt(0)
	v_mfma_f32_16x16x32_bf16 v[62:65], v[154:157], v[186:189], v[62:65]
	v_mfma_f32_16x16x32_bf16 v[54:57], v[162:165], v[186:189], v[54:57]
	v_mfma_f32_16x16x32_bf16 v[46:49], v[154:157], v[194:197], v[46:49]
	v_mfma_f32_16x16x32_bf16 v[38:41], v[162:165], v[194:197], v[38:41]
	v_mfma_f32_16x16x32_bf16 v[30:33], v[154:157], v[202:205], v[30:33]
	v_mfma_f32_16x16x32_bf16 v[22:25], v[162:165], v[202:205], v[22:25]
	v_mfma_f32_16x16x32_bf16 v[14:17], v[154:157], v[210:213], v[14:17]
	v_mfma_f32_16x16x32_bf16 v[6:9], v[162:165], v[210:213], v[6:9]
	v_mfma_f32_16x16x32_bf16 v[62:65], v[158:161], v[190:193], v[62:65]
	v_mfma_f32_16x16x32_bf16 v[54:57], v[166:169], v[190:193], v[54:57]
	v_mfma_f32_16x16x32_bf16 v[46:49], v[158:161], v[198:201], v[46:49]
	v_mfma_f32_16x16x32_bf16 v[38:41], v[166:169], v[198:201], v[38:41]
	v_mfma_f32_16x16x32_bf16 v[30:33], v[158:161], v[206:209], v[30:33]
	v_mfma_f32_16x16x32_bf16 v[22:25], v[166:169], v[206:209], v[22:25]
	v_mfma_f32_16x16x32_bf16 v[14:17], v[158:161], v[214:217], v[14:17]
	v_mfma_f32_16x16x32_bf16 v[6:9], v[166:169], v[214:217], v[6:9]
	s_setprio 0
	s_setprio 1
	v_mfma_f32_16x16x32_bf16 v[58:61], v[170:173], v[186:189], v[58:61]
	v_mfma_f32_16x16x32_bf16 v[50:53], v[178:181], v[186:189], v[50:53]
	v_mfma_f32_16x16x32_bf16 v[42:45], v[170:173], v[194:197], v[42:45]
	v_mfma_f32_16x16x32_bf16 v[34:37], v[178:181], v[194:197], v[34:37]
	v_mfma_f32_16x16x32_bf16 v[26:29], v[170:173], v[202:205], v[26:29]
	v_mfma_f32_16x16x32_bf16 v[18:21], v[178:181], v[202:205], v[18:21]
	v_mfma_f32_16x16x32_bf16 v[10:13], v[170:173], v[210:213], v[10:13]
	v_mfma_f32_16x16x32_bf16 v[2:5], v[178:181], v[210:213], v[2:5]
	v_mfma_f32_16x16x32_bf16 v[58:61], v[174:177], v[190:193], v[58:61]
	v_mfma_f32_16x16x32_bf16 v[50:53], v[182:185], v[190:193], v[50:53]
	v_mfma_f32_16x16x32_bf16 v[42:45], v[174:177], v[198:201], v[42:45]
	v_mfma_f32_16x16x32_bf16 v[34:37], v[182:185], v[198:201], v[34:37]
	v_mfma_f32_16x16x32_bf16 v[26:29], v[174:177], v[206:209], v[26:29]
	v_mfma_f32_16x16x32_bf16 v[18:21], v[182:185], v[206:209], v[18:21]
	v_mfma_f32_16x16x32_bf16 v[10:13], v[174:177], v[214:217], v[10:13]
	v_mfma_f32_16x16x32_bf16 v[2:5], v[182:185], v[214:217], v[2:5]
	s_setprio 0
	s_barrier
	s_add_i32 s68, s68, 2
	s_add_u32 s26, s26, 0x100
	s_addc_u32 s27, s27, 0
	s_add_u32 s66, s66, 0x100
	s_addc_u32 s67, s67, 0
	s_cmp_gt_u32 s68, 29
	s_cbranch_scc0 .LBB0_100
	s_branch .Lpeel_after_0
.Lpeel_0:
	ds_read_b128 v[154:157], v150
	ds_read_b128 v[158:161], v150 offset:1024
	ds_read_b128 v[162:165], v150 offset:2048
	ds_read_b128 v[166:169], v150 offset:3072
	ds_read_b128 v[170:173], v151
	ds_read_b128 v[174:177], v151 offset:1024
	ds_read_b128 v[178:181], v151 offset:2048
	ds_read_b128 v[182:185], v151 offset:3072
	s_add_u32 s34, s26, 0xfff80080
	s_addc_u32 s35, s27, -1
	s_cmp_eq_u32 s68, 28
	s_cselect_b32 s51, s19, s35
	s_cselect_b32 s50, s64, s34
	s_cselect_b32 s35, s17, s67
	s_cselect_b32 s34, s65, s66
	v_lshl_add_u64 v[218:219], s[26:27], 0, v[138:139]
	s_add_i32 m0, s53, 0xc000
	ds_read_b128 v[186:189], v152
	ds_read_b128 v[190:193], v152 offset:1024
	ds_read_b128 v[194:197], v152 offset:2048
	ds_read_b128 v[198:201], v152 offset:3072
	ds_read_b128 v[202:205], v152 offset:4096
	ds_read_b128 v[206:209], v152 offset:5120
	ds_read_b128 v[210:213], v152 offset:6144
	ds_read_b128 v[214:217], v152 offset:7168
	global_load_lds_dwordx4 v[218:219], off
	v_lshl_add_u64 v[218:219], s[26:27], 0, v[140:141]
	s_add_i32 m0, s53, 0xe000
	s_nop 0
	global_load_lds_dwordx4 v[218:219], off
	s_waitcnt vmcnt(16)
	s_waitcnt lgkmcnt(0)
	s_barrier
	s_setprio 1
	s_waitcnt lgkmcnt(0)
	v_mfma_f32_16x16x32_bf16 v[126:129], v[154:157], v[186:189], 0
	v_mfma_f32_16x16x32_bf16 v[118:121], v[162:165], v[186:189], 0
	v_mfma_f32_16x16x32_bf16 v[110:113], v[154:157], v[194:197], 0
	v_mfma_f32_16x16x32_bf16 v[102:105], v[162:165], v[194:197], 0
	v_mfma_f32_16x16x32_bf16 v[94:97], v[154:157], v[202:205], 0
	v_mfma_f32_16x16x32_bf16 v[86:89], v[162:165], v[202:205], 0
	v_mfma_f32_16x16x32_bf16 v[78:81], v[154:157], v[210:213], 0
	v_mfma_f32_16x16x32_bf16 v[70:73], v[162:165], v[210:213], 0
	v_mfma_f32_16x16x32_bf16 v[126:129], v[158:161], v[190:193], v[126:129]
	v_mfma_f32_16x16x32_bf16 v[118:121], v[166:169], v[190:193], v[118:121]
	v_mfma_f32_16x16x32_bf16 v[110:113], v[158:161], v[198:201], v[110:113]
	v_mfma_f32_16x16x32_bf16 v[102:105], v[166:169], v[198:201], v[102:105]
	v_mfma_f32_16x16x32_bf16 v[94:97], v[158:161], v[206:209], v[94:97]
	v_mfma_f32_16x16x32_bf16 v[86:89], v[166:169], v[206:209], v[86:89]
	v_mfma_f32_16x16x32_bf16 v[78:81], v[158:161], v[214:217], v[78:81]
	v_mfma_f32_16x16x32_bf16 v[70:73], v[166:169], v[214:217], v[70:73]
	s_setprio 0
	s_setprio 1
	v_mfma_f32_16x16x32_bf16 v[122:125], v[170:173], v[186:189], 0
	v_mfma_f32_16x16x32_bf16 v[114:117], v[178:181], v[186:189], 0
	v_mfma_f32_16x16x32_bf16 v[106:109], v[170:173], v[194:197], 0
	v_mfma_f32_16x16x32_bf16 v[98:101], v[178:181], v[194:197], 0
	v_mfma_f32_16x16x32_bf16 v[90:93], v[170:173], v[202:205], 0
	v_mfma_f32_16x16x32_bf16 v[82:85], v[178:181], v[202:205], 0
	v_mfma_f32_16x16x32_bf16 v[74:77], v[170:173], v[210:213], 0
	v_mfma_f32_16x16x32_bf16 v[66:69], v[178:181], v[210:213], 0
	v_mfma_f32_16x16x32_bf16 v[122:125], v[174:177], v[190:193], v[122:125]
	v_mfma_f32_16x16x32_bf16 v[114:117], v[182:185], v[190:193], v[114:117]
	v_mfma_f32_16x16x32_bf16 v[106:109], v[174:177], v[198:201], v[106:109]
	v_mfma_f32_16x16x32_bf16 v[98:101], v[182:185], v[198:201], v[98:101]
	v_mfma_f32_16x16x32_bf16 v[90:93], v[174:177], v[206:209], v[90:93]
	v_mfma_f32_16x16x32_bf16 v[82:85], v[182:185], v[206:209], v[82:85]
	v_mfma_f32_16x16x32_bf16 v[74:77], v[174:177], v[214:217], v[74:77]
	v_mfma_f32_16x16x32_bf16 v[66:69], v[182:185], v[214:217], v[66:69]
	s_setprio 0
	s_barrier
; #define PG8_STAGE(bufoff, gbase, voff) do { _Pragma("unroll") for (int _i = 0; _i < 2; ++_i) \
;         __builtin_amdgcn_global_load_lds((const unsigned*)((const char*)(gbase) + (voff)[_i]), (PG8_LAS unsigned*)(lds + (bufoff) + ldsw + _i * 8192), 16, 0, 0); } while (0)
; #define PG8_LDA(dst, b, h) do { _Pragma("unroll") for (int m = 0; m < 4; ++m) _Pragma("unroll") for (int k = 0; k < 2; ++k) dst[m][k] = *(const PG8_LAS bf16x8*)(lds + PG8_SA(b, h) + aoff + m * 2048 + k * 1024); } while (0)
; #define PG8_LDB(dst, b, h) do { _Pragma("unroll") for (int n = 0; n < 2; ++n) _Pragma("unroll") for (int k = 0; k < 2; ++k) dst[n][k] = *(const PG8_LAS bf16x8*)(lds + PG8_SB(b, h) + boff + n * 2048 + k * 1024); } while (0)
; #define PG8_MMA(ai, bj, At, Bt) do { __builtin_amdgcn_s_setprio(1); _Pragma("unroll") for (int m = 0; m < 4; ++m) _Pragma("unroll") for (int n = 0; n < 2; ++n) _Pragma("unroll") for (int k = 0; k < 2; ++k) \
;         acc[ai][bj][m][n] = __builtin_amdgcn_mfma_f32_16x16x32_bf16(Bt[n][k], At[m][k], acc[ai][bj][m][n], 0, 0, 0); __builtin_amdgcn_s_setprio(0); } while (0)
; #define PG8_WAIT_V(n) asm volatile("s_waitcnt vmcnt(" #n ")" ::: "memory")
; #define PG8_WAIT_L(n) asm volatile("s_waitcnt lgkmcnt(" #n ")" ::: "memory")
; #define PG8_BAR __builtin_amdgcn_s_barrier()
; #define PG8_SCHED __builtin_amdgcn_sched_barrier(0)
; template <class Epi, class Sched, bool ALIGN_EPI = false, bool SP2 = false>
; __device__ __forceinline__ void gemm_phase(PG8_LAS unsigned char* lds, const Gemm g, const Sched& S, const Epi& E) {
;     ...
;             PG8_WAIT_V(8); PG8_WAIT_L(0); PG8_BAR; PG8_MMA(0, 0, At, B0); PG8_MMA(0, 1, At, B1); PG8_BAR; PG8_SCHED;
;             PG8_LDA(At, 0, 1); PG8_STAGE(PG8_SB(0, 0), b2, voffB); PG8_STAGE(PG8_SB(0, 1), b2 + hstep, voffB); PG8_STAGE(PG8_SA(0, 0), a2, voffA);
;             PG8_WAIT_V(8); PG8_WAIT_L(0); PG8_BAR; PG8_MMA(1, 0, At, B0); PG8_MMA(1, 1, At, B1); PG8_BAR; PG8_SCHED;
;             PG8_LDB(B0, 1, 0); PG8_LDB(B1, 1, 1); PG8_SCHED; PG8_LDA(At, 1, 0); PG8_STAGE(PG8_SA(0, 1), a2 + hstep, voffA);
;             PG8_WAIT_V(8); PG8_WAIT_L(0); PG8_BAR; PG8_MMA(0, 0, At, B0); PG8_MMA(0, 1, At, B1); PG8_BAR; PG8_SCHED;
	s_add_i32 s69, s61, s29
	v_lshl_add_u64 v[218:219], s[34:35], 0, v[134:135]
	s_mov_b32 m0, s69
	ds_read_b128 v[186:189], v152 offset:16384
	ds_read_b128 v[190:193], v152 offset:17408
	ds_read_b128 v[194:197], v152 offset:18432
	ds_read_b128 v[198:201], v152 offset:19456
	ds_read_b128 v[202:205], v152 offset:20480
	ds_read_b128 v[206:209], v152 offset:21504
	ds_read_b128 v[210:213], v152 offset:22528
	ds_read_b128 v[214:217], v152 offset:23552
	global_load_lds_dwordx4 v[218:219], off
	s_add_i32 m0, s69, 0x2000
	s_add_u32 s70, s34, 0x80000
	v_lshl_add_u64 v[220:221], s[34:35], 0, v[130:131]
	s_addc_u32 s71, s35, 0
	s_add_i32 s69, s62, s29
	global_load_lds_dwordx4 v[220:221], off
	v_lshl_add_u64 v[222:223], s[70:71], 0, v[134:135]
	s_mov_b32 m0, s69
	v_lshl_add_u64 v[224:225], s[50:51], 0, v[132:133]
	global_load_lds_dwordx4 v[222:223], off
	v_lshl_add_u64 v[222:223], s[70:71], 0, v[130:131]
	s_add_i32 m0, s69, 0x2000
	s_nop 0
	global_load_lds_dwordx4 v[222:223], off
	v_lshl_add_u64 v[222:223], s[50:51], 0, v[136:137]
	s_mov_b32 m0, s53
	s_nop 0
	global_load_lds_dwordx4 v[222:223], off
	s_mov_b32 m0, s54
	s_nop 0
	global_load_lds_dwordx4 v[224:225], off
	s_waitcnt vmcnt(16)
	s_waitcnt lgkmcnt(0)
	s_barrier
	s_setprio 1
	s_waitcnt lgkmcnt(0)
	v_mfma_f32_16x16x32_bf16 v[62:65], v[154:157], v[186:189], 0
	v_mfma_f32_16x16x32_bf16 v[54:57], v[162:165], v[186:189], 0
	v_mfma_f32_16x16x32_bf16 v[46:49], v[154:157], v[194:197], 0
	v_mfma_f32_16x16x32_bf16 v[38:41], v[162:165], v[194:197], 0
	v_mfma_f32_16x16x32_bf16 v[30:33], v[154:157], v[202:205], 0
	v_mfma_f32_16x16x32_bf16 v[22:25], v[162:165], v[202:205], 0
	v_mfma_f32_16x16x32_bf16 v[14:17], v[154:157], v[210:213], 0
	v_mfma_f32_16x16x32_bf16 v[6:9], v[162:165], v[210:213], 0
	v_mfma_f32_16x16x32_bf16 v[62:65], v[158:161], v[190:193], v[62:65]
	v_mfma_f32_16x16x32_bf16 v[54:57], v[166:169], v[190:193], v[54:57]
	v_mfma_f32_16x16x32_bf16 v[46:49], v[158:161], v[198:201], v[46:49]
	v_mfma_f32_16x16x32_bf16 v[38:41], v[166:169], v[198:201], v[38:41]
	v_mfma_f32_16x16x32_bf16 v[30:33], v[158:161], v[206:209], v[30:33]
	v_mfma_f32_16x16x32_bf16 v[22:25], v[166:169], v[206:209], v[22:25]
	v_mfma_f32_16x16x32_bf16 v[14:17], v[158:161], v[214:217], v[14:17]
	v_mfma_f32_16x16x32_bf16 v[6:9], v[166:169], v[214:217], v[6:9]
	s_setprio 0
	s_setprio 1
	v_mfma_f32_16x16x32_bf16 v[58:61], v[170:173], v[186:189], 0
	v_mfma_f32_16x16x32_bf16 v[50:53], v[178:181], v[186:189], 0
	v_mfma_f32_16x16x32_bf16 v[42:45], v[170:173], v[194:197], 0
	v_mfma_f32_16x16x32_bf16 v[34:37], v[178:181], v[194:197], 0
	v_mfma_f32_16x16x32_bf16 v[26:29], v[170:173], v[202:205], 0
	v_mfma_f32_16x16x32_bf16 v[18:21], v[178:181], v[202:205], 0
	v_mfma_f32_16x16x32_bf16 v[10:13], v[170:173], v[210:213], 0
	v_mfma_f32_16x16x32_bf16 v[2:5], v[178:181], v[210:213], 0
	v_mfma_f32_16x16x32_bf16 v[58:61], v[174:177], v[190:193], v[58:61]
	v_mfma_f32_16x16x32_bf16 v[50:53], v[182:185], v[190:193], v[50:53]
	v_mfma_f32_16x16x32_bf16 v[42:45], v[174:177], v[198:201], v[42:45]
	v_mfma_f32_16x16x32_bf16 v[34:37], v[182:185], v[198:201], v[34:37]
	v_mfma_f32_16x16x32_bf16 v[26:29], v[174:177], v[206:209], v[26:29]
	v_mfma_f32_16x16x32_bf16 v[18:21], v[182:185], v[206:209], v[18:21]
	v_mfma_f32_16x16x32_bf16 v[10:13], v[174:177], v[214:217], v[10:13]
	v_mfma_f32_16x16x32_bf16 v[2:5], v[182:185], v[214:217], v[2:5]
	s_setprio 0
	s_barrier
	s_add_i32 s69, 0, 0x18000
	v_add_u32_e32 v153, s69, v148
	s_add_i32 s70, 0, 0x1c000
	ds_read_b128 v[154:157], v153
	ds_read_b128 v[158:161], v153 offset:1024
	ds_read_b128 v[162:165], v153 offset:2048
	ds_read_b128 v[166:169], v153 offset:3072
	v_add_u32_e32 v153, s70, v148
	ds_read_b128 v[170:173], v153
	ds_read_b128 v[174:177], v153 offset:1024
	ds_read_b128 v[178:181], v153 offset:2048
	ds_read_b128 v[182:185], v153 offset:3072
	s_add_u32 s50, s50, 0x80000
	s_addc_u32 s51, s51, 0
	s_mov_b32 m0, s55
	v_lshl_add_u64 v[226:227], s[50:51], 0, v[136:137]
	ds_read_b128 v[186:189], v152 offset:32768
	ds_read_b128 v[190:193], v152 offset:33792
	ds_read_b128 v[194:197], v152 offset:34816
	ds_read_b128 v[198:201], v152 offset:35840
	ds_read_b128 v[202:205], v152 offset:36864
	ds_read_b128 v[206:209], v152 offset:37888
	ds_read_b128 v[210:213], v152 offset:38912
	ds_read_b128 v[214:217], v152 offset:39936
	global_load_lds_dwordx4 v[226:227], off
	v_lshl_add_u64 v[226:227], s[50:51], 0, v[132:133]
	s_mov_b32 m0, s56
	s_nop 0
	global_load_lds_dwordx4 v[226:227], off
	s_waitcnt vmcnt(8)
	s_waitcnt lgkmcnt(0)
	s_barrier
; #define PG8_STAGE(bufoff, gbase, voff) do { _Pragma("unroll") for (int _i = 0; _i < 2; ++_i) \
;         __builtin_amdgcn_global_load_lds((const unsigned*)((const char*)(gbase) + (voff)[_i]), (PG8_LAS unsigned*)(lds + (bufoff) + ldsw + _i * 8192), 16, 0, 0); } while (0)
; #define PG8_LDA(dst, b, h) do { _Pragma("unroll") for (int m = 0; m < 4; ++m) _Pragma("unroll") for (int k = 0; k < 2; ++k) dst[m][k] = *(const PG8_LAS bf16x8*)(lds + PG8_SA(b, h) + aoff + m * 2048 + k * 1024); } while (0)
; #define PG8_MMA(ai, bj, At, Bt) do { __builtin_amdgcn_s_setprio(1); _Pragma("unroll") for (int m = 0; m < 4; ++m) _Pragma("unroll") for (int n = 0; n < 2; ++n) _Pragma("unroll") for (int k = 0; k < 2; ++k) \
;         acc[ai][bj][m][n] = __builtin_amdgcn_mfma_f32_16x16x32_bf16(Bt[n][k], At[m][k], acc[ai][bj][m][n], 0, 0, 0); __builtin_amdgcn_s_setprio(0); } while (0)
; #define PG8_WAIT_V(n) asm volatile("s_waitcnt vmcnt(" #n ")" ::: "memory")
; #define PG8_WAIT_L(n) asm volatile("s_waitcnt lgkmcnt(" #n ")" ::: "memory")
; #define PG8_BAR __builtin_amdgcn_s_barrier()
; #define PG8_SCHED __builtin_amdgcn_sched_barrier(0)
; template <class Epi, class Sched, bool ALIGN_EPI = false, bool SP2 = false>
; __device__ __forceinline__ void gemm_phase(PG8_LAS unsigned char* lds, const Gemm g, const Sched& S, const Epi& E) {
;     ...
;             PG8_WAIT_V(8); PG8_WAIT_L(0); PG8_BAR; PG8_MMA(0, 0, At, B0); PG8_MMA(0, 1, At, B1); PG8_BAR; PG8_SCHED;
;             PG8_LDA(At, 1, 1); PG8_STAGE(PG8_SB(1, 0), b3, voffB); PG8_STAGE(PG8_SB(1, 1), b3 + hstep, voffB); PG8_STAGE(PG8_SA(1, 0), a3, voffA);
;             PG8_WAIT_V(8); PG8_WAIT_L(0); PG8_BAR; PG8_MMA(1, 0, At, B0); PG8_MMA(1, 1, At, B1); PG8_BAR; PG8_SCHED;
	s_setprio 1
	s_waitcnt lgkmcnt(0)
	v_mfma_f32_16x16x32_bf16 v[126:129], v[154:157], v[186:189], v[126:129]
	v_mfma_f32_16x16x32_bf16 v[118:121], v[162:165], v[186:189], v[118:121]
	v_mfma_f32_16x16x32_bf16 v[110:113], v[154:157], v[194:197], v[110:113]
	v_mfma_f32_16x16x32_bf16 v[102:105], v[162:165], v[194:197], v[102:105]
	v_mfma_f32_16x16x32_bf16 v[94:97], v[154:157], v[202:205], v[94:97]
	v_mfma_f32_16x16x32_bf16 v[86:89], v[162:165], v[202:205], v[86:89]
	v_mfma_f32_16x16x32_bf16 v[78:81], v[154:157], v[210:213], v[78:81]
	v_mfma_f32_16x16x32_bf16 v[70:73], v[162:165], v[210:213], v[70:73]
	v_mfma_f32_16x16x32_bf16 v[126:129], v[158:161], v[190:193], v[126:129]
	v_mfma_f32_16x16x32_bf16 v[118:121], v[166:169], v[190:193], v[118:121]
	v_mfma_f32_16x16x32_bf16 v[110:113], v[158:161], v[198:201], v[110:113]
	v_mfma_f32_16x16x32_bf16 v[102:105], v[166:169], v[198:201], v[102:105]
	v_mfma_f32_16x16x32_bf16 v[94:97], v[158:161], v[206:209], v[94:97]
	v_mfma_f32_16x16x32_bf16 v[86:89], v[166:169], v[206:209], v[86:89]
	v_mfma_f32_16x16x32_bf16 v[78:81], v[158:161], v[214:217], v[78:81]
	v_mfma_f32_16x16x32_bf16 v[70:73], v[166:169], v[214:217], v[70:73]
	s_setprio 0
	s_setprio 1
	v_mfma_f32_16x16x32_bf16 v[122:125], v[170:173], v[186:189], v[122:125]
	v_mfma_f32_16x16x32_bf16 v[114:117], v[178:181], v[186:189], v[114:117]
	v_mfma_f32_16x16x32_bf16 v[106:109], v[170:173], v[194:197], v[106:109]
	v_mfma_f32_16x16x32_bf16 v[98:101], v[178:181], v[194:197], v[98:101]
	v_mfma_f32_16x16x32_bf16 v[90:93], v[170:173], v[202:205], v[90:93]
	v_mfma_f32_16x16x32_bf16 v[82:85], v[178:181], v[202:205], v[82:85]
	v_mfma_f32_16x16x32_bf16 v[74:77], v[170:173], v[210:213], v[74:77]
	v_mfma_f32_16x16x32_bf16 v[66:69], v[178:181], v[210:213], v[66:69]
	v_mfma_f32_16x16x32_bf16 v[122:125], v[174:177], v[190:193], v[122:125]
	v_mfma_f32_16x16x32_bf16 v[114:117], v[182:185], v[190:193], v[114:117]
	v_mfma_f32_16x16x32_bf16 v[106:109], v[174:177], v[198:201], v[106:109]
	v_mfma_f32_16x16x32_bf16 v[98:101], v[182:185], v[198:201], v[98:101]
	v_mfma_f32_16x16x32_bf16 v[90:93], v[174:177], v[206:209], v[90:93]
	v_mfma_f32_16x16x32_bf16 v[82:85], v[182:185], v[206:209], v[82:85]
	v_mfma_f32_16x16x32_bf16 v[74:77], v[174:177], v[214:217], v[74:77]
	v_mfma_f32_16x16x32_bf16 v[66:69], v[182:185], v[214:217], v[66:69]
	s_setprio 0
	s_barrier
	s_add_i32 s50, s69, s29
	v_lshl_add_u64 v[218:219], v[218:219], 0, s[12:13]
	s_mov_b32 m0, s50
	ds_read_b128 v[186:189], v152 offset:49152
	ds_read_b128 v[190:193], v152 offset:50176
	ds_read_b128 v[194:197], v152 offset:51200
	ds_read_b128 v[198:201], v152 offset:52224
	ds_read_b128 v[202:205], v152 offset:53248
	ds_read_b128 v[206:209], v152 offset:54272
	ds_read_b128 v[210:213], v152 offset:55296
	ds_read_b128 v[214:217], v152 offset:56320
	global_load_lds_dwordx4 v[218:219], off
	s_add_i32 m0, s50, 0x2000
	s_add_u32 s34, s34, 0x80080
	v_lshl_add_u64 v[218:219], v[220:221], 0, s[12:13]
	s_addc_u32 s35, s35, 0
	s_add_i32 s50, s70, s29
	global_load_lds_dwordx4 v[218:219], off
	v_lshl_add_u64 v[218:219], s[34:35], 0, v[134:135]
	s_mov_b32 m0, s50
	s_nop 0
	global_load_lds_dwordx4 v[218:219], off
	v_lshl_add_u64 v[218:219], s[34:35], 0, v[130:131]
	s_add_i32 m0, s50, 0x2000
	s_nop 0
	global_load_lds_dwordx4 v[218:219], off
	v_lshl_add_u64 v[218:219], v[222:223], 0, s[12:13]
	s_mov_b32 m0, s58
	s_nop 0
	global_load_lds_dwordx4 v[218:219], off
	v_lshl_add_u64 v[218:219], v[224:225], 0, s[12:13]
	s_mov_b32 m0, s59
	s_nop 0
	global_load_lds_dwordx4 v[218:219], off
	s_waitcnt vmcnt(8)
	s_waitcnt lgkmcnt(0)
	s_barrier
	s_setprio 1
	s_waitcnt lgkmcnt(0)
	v_mfma_f32_16x16x32_bf16 v[62:65], v[154:157], v[186:189], v[62:65]
	v_mfma_f32_16x16x32_bf16 v[54:57], v[162:165], v[186:189], v[54:57]
	v_mfma_f32_16x16x32_bf16 v[46:49], v[154:157], v[194:197], v[46:49]
	v_mfma_f32_16x16x32_bf16 v[38:41], v[162:165], v[194:197], v[38:41]
	v_mfma_f32_16x16x32_bf16 v[30:33], v[154:157], v[202:205], v[30:33]
	v_mfma_f32_16x16x32_bf16 v[22:25], v[162:165], v[202:205], v[22:25]
	v_mfma_f32_16x16x32_bf16 v[14:17], v[154:157], v[210:213], v[14:17]
	v_mfma_f32_16x16x32_bf16 v[6:9], v[162:165], v[210:213], v[6:9]
	v_mfma_f32_16x16x32_bf16 v[62:65], v[158:161], v[190:193], v[62:65]
	v_mfma_f32_16x16x32_bf16 v[54:57], v[166:169], v[190:193], v[54:57]
	v_mfma_f32_16x16x32_bf16 v[46:49], v[158:161], v[198:201], v[46:49]
	v_mfma_f32_16x16x32_bf16 v[38:41], v[166:169], v[198:201], v[38:41]
	v_mfma_f32_16x16x32_bf16 v[30:33], v[158:161], v[206:209], v[30:33]
	v_mfma_f32_16x16x32_bf16 v[22:25], v[166:169], v[206:209], v[22:25]
	v_mfma_f32_16x16x32_bf16 v[14:17], v[158:161], v[214:217], v[14:17]
	v_mfma_f32_16x16x32_bf16 v[6:9], v[166:169], v[214:217], v[6:9]
	s_setprio 0
	s_setprio 1
	v_mfma_f32_16x16x32_bf16 v[58:61], v[170:173], v[186:189], v[58:61]
	v_mfma_f32_16x16x32_bf16 v[50:53], v[178:181], v[186:189], v[50:53]
	v_mfma_f32_16x16x32_bf16 v[42:45], v[170:173], v[194:197], v[42:45]
	v_mfma_f32_16x16x32_bf16 v[34:37], v[178:181], v[194:197], v[34:37]
	v_mfma_f32_16x16x32_bf16 v[26:29], v[170:173], v[202:205], v[26:29]
	v_mfma_f32_16x16x32_bf16 v[18:21], v[178:181], v[202:205], v[18:21]
	v_mfma_f32_16x16x32_bf16 v[10:13], v[170:173], v[210:213], v[10:13]
	v_mfma_f32_16x16x32_bf16 v[2:5], v[178:181], v[210:213], v[2:5]
	v_mfma_f32_16x16x32_bf16 v[58:61], v[174:177], v[190:193], v[58:61]
	v_mfma_f32_16x16x32_bf16 v[50:53], v[182:185], v[190:193], v[50:53]
	v_mfma_f32_16x16x32_bf16 v[42:45], v[174:177], v[198:201], v[42:45]
	v_mfma_f32_16x16x32_bf16 v[34:37], v[182:185], v[198:201], v[34:37]
	v_mfma_f32_16x16x32_bf16 v[26:29], v[174:177], v[206:209], v[26:29]
	v_mfma_f32_16x16x32_bf16 v[18:21], v[182:185], v[206:209], v[18:21]
	v_mfma_f32_16x16x32_bf16 v[10:13], v[174:177], v[214:217], v[10:13]
	v_mfma_f32_16x16x32_bf16 v[2:5], v[182:185], v[214:217], v[2:5]
	s_setprio 0
	s_barrier
	s_add_i32 s68, s68, 2
	s_add_u32 s26, s26, 0x100
	s_addc_u32 s27, s27, 0
	s_add_u32 s66, s66, 0x100
	s_addc_u32 s67, s67, 0
	s_cmp_gt_u32 s68, 29
	s_branch .LBB0_100
; #define PG8_BAR __builtin_amdgcn_s_barrier()
; DI unsigned pk2(float lo, float hi) { f32x2 v = {lo, hi}; bf16x2_t b = __builtin_convertvector(v, bf16x2_t); return __builtin_bit_cast(unsigned, b); }
; DI float siluf_(float x) { return x * sigmoidf_(x); }
; template <class Epi, class Sched, bool ALIGN_EPI = false, bool SP2 = false>
; __device__ __forceinline__ void gemm_phase(PG8_LAS unsigned char* lds, const Gemm g, const Sched& S, const Epi& E) {
;     ...
;         if constexpr (ALIGN_EPI) { if (wr == 0) PG8_BAR; }
;     DI void operator()(const f32x4 (&acc)[2][2][4][2], const pg8::Unit& u, int wr, int wc, int fr, int fq) const {
;         const int row0 = u.pm * 256 + wr * 64 + fr, col0 = u.pn * 128 + wc * 32 + 8 * fq;
; #pragma unroll
;         for (int ai = 0; ai < 2; ++ai)
; #pragma unroll
;             for (int m = 0; m < 4; ++m) {
;                 const f32x4 g0 = acc[ai][0][m][0], g1 = acc[ai][0][m][1], u0 = acc[ai][1][m][0], u1 = acc[ai][1][m][1];
;                 u32x4 w;
;                 w.x = pk2(siluf_(g0[0]) * u0[0], siluf_(g0[1]) * u0[1]); w.y = pk2(siluf_(g0[2]) * u0[2], siluf_(g0[3]) * u0[3]);
;                 w.z = pk2(siluf_(g1[0]) * u1[0], siluf_(g1[1]) * u1[1]); w.w = pk2(siluf_(g1[2]) * u1[2], siluf_(g1[3]) * u1[3]);
;                 *(u32x4*)(H + (size_t)(row0 + ai * 128 + m * 16) * DFF + col0) = w;
;             }
;     }
.Lpeel_after_0:
	s_and_b64 vcc, exec, s[14:15]
	s_cbranch_vccz .LBB0_103
	s_barrier
.LBB0_103:
	v_mul_f32_e32 v156, 0xbfb8aa3b, v126
	v_mul_f32_e32 v157, 0xbfb8aa3b, v127
	v_exp_f32_e32 v156, v156
	v_exp_f32_e32 v157, v157
	v_lshl_add_u32 v153, s24, 8, v147
	v_lshl_or_b32 v154, s25, 7, v149
	v_add_f32_e32 v156, 1.0, v156
	v_add_f32_e32 v157, 1.0, v157
	v_rcp_f32_e32 v156, v156
	v_rcp_f32_e32 v157, v157
	v_readlane_b32 s24, v253, 45
	v_readlane_b32 s25, v253, 46
	v_ashrrev_i32_e32 v155, 31, v154
	v_pk_mul_f32 v[126:127], v[126:127], v[156:157]
	s_andn2_b64 vcc, exec, s[0:1]
	v_pk_mul_f32 v[122:123], v[126:127], v[122:123]
	v_readlane_b32 s66, v253, 47
	v_cvt_pk_bf16_f32 v122, v122, v123
	v_mul_f32_e32 v123, 0xbfb8aa3b, v128
	v_exp_f32_e32 v123, v123
	v_readlane_b32 s67, v253, 48
	v_add_f32_e32 v123, 1.0, v123
	v_rcp_f32_e32 v126, v123
	v_mul_f32_e32 v123, 0xbfb8aa3b, v129
	v_exp_f32_e32 v123, v123
	s_nop 0
	v_add_f32_e32 v123, 1.0, v123
	v_rcp_f32_e32 v127, v123
	s_nop 0
	v_pk_mul_f32 v[126:127], v[128:129], v[126:127]
	s_nop 0
	v_pk_mul_f32 v[124:125], v[126:127], v[124:125]
	s_nop 0
	v_cvt_pk_bf16_f32 v123, v124, v125
	v_mul_f32_e32 v124, 0xbfb8aa3b, v118
	v_mul_f32_e32 v125, 0xbfb8aa3b, v119
	v_exp_f32_e32 v124, v124
	v_exp_f32_e32 v125, v125
	v_add_f32_e32 v124, 1.0, v124
	v_add_f32_e32 v125, 1.0, v125
	v_rcp_f32_e32 v124, v124
	v_rcp_f32_e32 v125, v125
	s_nop 0
	v_pk_mul_f32 v[118:119], v[118:119], v[124:125]
	s_nop 0
	v_pk_mul_f32 v[114:115], v[118:119], v[114:115]
	s_nop 0
	v_cvt_pk_bf16_f32 v124, v114, v115
	v_mul_f32_e32 v114, 0xbfb8aa3b, v120
	v_mul_f32_e32 v115, 0xbfb8aa3b, v121
	v_exp_f32_e32 v114, v114
	v_exp_f32_e32 v115, v115
	v_add_f32_e32 v114, 1.0, v114
	v_add_f32_e32 v115, 1.0, v115
	v_rcp_f32_e32 v114, v114
	v_rcp_f32_e32 v115, v115
	s_nop 0
	v_pk_mul_f32 v[114:115], v[120:121], v[114:115]
	s_nop 0
	v_pk_mul_f32 v[114:115], v[114:115], v[116:117]
	v_lshlrev_b64 v[116:117], 1, v[154:155]
	v_cvt_pk_bf16_f32 v125, v114, v115
	v_mov_b64_e32 v[114:115], s[24:25]
	v_mad_i64_i32 v[118:119], s[24:25], v153, s63, v[114:115]
	v_lshl_add_u64 v[118:119], v[118:119], 0, v[116:117]
	global_store_dwordx4 v[118:119], v[122:125], off
	v_mul_f32_e32 v118, 0xbfb8aa3b, v110
	v_mul_f32_e32 v119, 0xbfb8aa3b, v111
	v_exp_f32_e32 v118, v118
	v_exp_f32_e32 v119, v119
	v_add_f32_e32 v118, 1.0, v118
	v_add_f32_e32 v119, 1.0, v119
	v_rcp_f32_e32 v118, v118
	v_rcp_f32_e32 v119, v119
	s_nop 0
	v_pk_mul_f32 v[110:111], v[110:111], v[118:119]
	s_nop 0
	v_pk_mul_f32 v[106:107], v[110:111], v[106:107]
	s_nop 0
	v_cvt_pk_bf16_f32 v106, v106, v107
	v_mul_f32_e32 v107, 0xbfb8aa3b, v112
	v_exp_f32_e32 v107, v107
	s_nop 0
	v_add_f32_e32 v107, 1.0, v107
	v_rcp_f32_e32 v110, v107
	v_mul_f32_e32 v107, 0xbfb8aa3b, v113
	v_exp_f32_e32 v107, v107
	s_nop 0
	v_add_f32_e32 v107, 1.0, v107
	v_rcp_f32_e32 v111, v107
	s_nop 0
	v_pk_mul_f32 v[110:111], v[112:113], v[110:111]
	s_nop 0
	v_pk_mul_f32 v[108:109], v[110:111], v[108:109]
	s_nop 0
	v_cvt_pk_bf16_f32 v107, v108, v109
	v_mul_f32_e32 v108, 0xbfb8aa3b, v102
	v_mul_f32_e32 v109, 0xbfb8aa3b, v103
	v_exp_f32_e32 v108, v108
	v_exp_f32_e32 v109, v109
	v_add_f32_e32 v108, 1.0, v108
	v_add_f32_e32 v109, 1.0, v109
	v_rcp_f32_e32 v108, v108
	v_rcp_f32_e32 v109, v109
	s_nop 0
	v_pk_mul_f32 v[102:103], v[102:103], v[108:109]
	s_nop 0
	v_pk_mul_f32 v[98:99], v[102:103], v[98:99]
	s_nop 0
	v_cvt_pk_bf16_f32 v108, v98, v99
	v_mul_f32_e32 v98, 0xbfb8aa3b, v104
	v_mul_f32_e32 v99, 0xbfb8aa3b, v105
	v_exp_f32_e32 v98, v98
	v_exp_f32_e32 v99, v99
	v_add_f32_e32 v98, 1.0, v98
	v_add_f32_e32 v99, 1.0, v99
	v_rcp_f32_e32 v98, v98
	v_rcp_f32_e32 v99, v99
	s_nop 0
	v_pk_mul_f32 v[98:99], v[104:105], v[98:99]
	s_nop 0
	v_pk_mul_f32 v[98:99], v[98:99], v[100:101]
	s_nop 0
	v_cvt_pk_bf16_f32 v109, v98, v99
	v_or_b32_e32 v98, 16, v153
	v_mad_i64_i32 v[98:99], s[24:25], v98, s63, v[114:115]
	v_lshl_add_u64 v[98:99], v[98:99], 0, v[116:117]
	global_store_dwordx4 v[98:99], v[106:109], off
	v_mul_f32_e32 v98, 0xbfb8aa3b, v94
	v_mul_f32_e32 v99, 0xbfb8aa3b, v95
	v_exp_f32_e32 v98, v98
	v_exp_f32_e32 v99, v99
	v_add_f32_e32 v98, 1.0, v98
	v_add_f32_e32 v99, 1.0, v99
	v_rcp_f32_e32 v98, v98
	v_rcp_f32_e32 v99, v99
	s_nop 0
	v_pk_mul_f32 v[94:95], v[94:95], v[98:99]
	s_nop 0
	v_pk_mul_f32 v[90:91], v[94:95], v[90:91]
	s_nop 0
	v_cvt_pk_bf16_f32 v90, v90, v91
	v_mul_f32_e32 v91, 0xbfb8aa3b, v96
	v_exp_f32_e32 v91, v91
	s_nop 0
	v_add_f32_e32 v91, 1.0, v91
	v_rcp_f32_e32 v94, v91
	v_mul_f32_e32 v91, 0xbfb8aa3b, v97
	v_exp_f32_e32 v91, v91
	s_nop 0
	v_add_f32_e32 v91, 1.0, v91
	v_rcp_f32_e32 v95, v91
	s_nop 0
	v_pk_mul_f32 v[94:95], v[96:97], v[94:95]
	s_nop 0
	v_pk_mul_f32 v[92:93], v[94:95], v[92:93]
	s_nop 0
	v_cvt_pk_bf16_f32 v91, v92, v93
	v_mul_f32_e32 v92, 0xbfb8aa3b, v86
	v_mul_f32_e32 v93, 0xbfb8aa3b, v87
	v_exp_f32_e32 v92, v92
	v_exp_f32_e32 v93, v93
	v_add_f32_e32 v92, 1.0, v92
	v_add_f32_e32 v93, 1.0, v93
	v_rcp_f32_e32 v92, v92
	v_rcp_f32_e32 v93, v93
	s_nop 0
	v_pk_mul_f32 v[86:87], v[86:87], v[92:93]
	s_nop 0
	v_pk_mul_f32 v[82:83], v[86:87], v[82:83]
	s_nop 0
	v_cvt_pk_bf16_f32 v92, v82, v83
	v_mul_f32_e32 v82, 0xbfb8aa3b, v88
	v_mul_f32_e32 v83, 0xbfb8aa3b, v89
	v_exp_f32_e32 v82, v82
	v_exp_f32_e32 v83, v83
	v_add_f32_e32 v82, 1.0, v82
	v_add_f32_e32 v83, 1.0, v83
	v_rcp_f32_e32 v82, v82
	v_rcp_f32_e32 v83, v83
	s_nop 0
	v_pk_mul_f32 v[82:83], v[88:89], v[82:83]
	s_nop 0
	v_pk_mul_f32 v[82:83], v[82:83], v[84:85]
	s_nop 0
	v_cvt_pk_bf16_f32 v93, v82, v83
	v_or_b32_e32 v82, 32, v153
	v_mad_i64_i32 v[82:83], s[24:25], v82, s63, v[114:115]
	v_lshl_add_u64 v[82:83], v[82:83], 0, v[116:117]
	global_store_dwordx4 v[82:83], v[90:93], off
; DI unsigned pk2(float lo, float hi) { f32x2 v = {lo, hi}; bf16x2_t b = __builtin_convertvector(v, bf16x2_t); return __builtin_bit_cast(unsigned, b); }
; DI float siluf_(float x) { return x * sigmoidf_(x); }
;     DI void operator()(const f32x4 (&acc)[2][2][4][2], const pg8::Unit& u, int wr, int wc, int fr, int fq) const {
;         const int row0 = u.pm * 256 + wr * 64 + fr, col0 = u.pn * 128 + wc * 32 + 8 * fq;
; #pragma unroll
;         for (int ai = 0; ai < 2; ++ai)
; #pragma unroll
;             for (int m = 0; m < 4; ++m) {
;                 const f32x4 g0 = acc[ai][0][m][0], g1 = acc[ai][0][m][1], u0 = acc[ai][1][m][0], u1 = acc[ai][1][m][1];
;                 u32x4 w;
;                 w.x = pk2(siluf_(g0[0]) * u0[0], siluf_(g0[1]) * u0[1]); w.y = pk2(siluf_(g0[2]) * u0[2], siluf_(g0[3]) * u0[3]);
;                 w.z = pk2(siluf_(g1[0]) * u1[0], siluf_(g1[1]) * u1[1]); w.w = pk2(siluf_(g1[2]) * u1[2], siluf_(g1[3]) * u1[3]);
;                 *(u32x4*)(H + (size_t)(row0 + ai * 128 + m * 16) * DFF + col0) = w;
;             }
;     }
	v_mul_f32_e32 v82, 0xbfb8aa3b, v78
	v_mul_f32_e32 v83, 0xbfb8aa3b, v79
	v_exp_f32_e32 v82, v82
	v_exp_f32_e32 v83, v83
	v_add_f32_e32 v82, 1.0, v82
	v_add_f32_e32 v83, 1.0, v83
	v_rcp_f32_e32 v82, v82
	v_rcp_f32_e32 v83, v83
	s_nop 0
	v_pk_mul_f32 v[78:79], v[78:79], v[82:83]
	s_nop 0
	v_pk_mul_f32 v[74:75], v[78:79], v[74:75]
	s_nop 0
	v_cvt_pk_bf16_f32 v74, v74, v75
	v_mul_f32_e32 v75, 0xbfb8aa3b, v80
	v_exp_f32_e32 v75, v75
	s_nop 0
	v_add_f32_e32 v75, 1.0, v75
	v_rcp_f32_e32 v78, v75
	v_mul_f32_e32 v75, 0xbfb8aa3b, v81
	v_exp_f32_e32 v75, v75
	s_nop 0
	v_add_f32_e32 v75, 1.0, v75
	v_rcp_f32_e32 v79, v75
	s_nop 0
	v_pk_mul_f32 v[78:79], v[80:81], v[78:79]
	s_nop 0
	v_pk_mul_f32 v[76:77], v[78:79], v[76:77]
	s_nop 0
	v_cvt_pk_bf16_f32 v75, v76, v77
	v_mul_f32_e32 v76, 0xbfb8aa3b, v70
	v_mul_f32_e32 v77, 0xbfb8aa3b, v71
	v_exp_f32_e32 v76, v76
	v_exp_f32_e32 v77, v77
	v_add_f32_e32 v76, 1.0, v76
	v_add_f32_e32 v77, 1.0, v77
	v_rcp_f32_e32 v76, v76
	v_rcp_f32_e32 v77, v77
	s_nop 0
	v_pk_mul_f32 v[70:71], v[70:71], v[76:77]
	s_nop 0
	v_pk_mul_f32 v[66:67], v[70:71], v[66:67]
	s_nop 0
	v_cvt_pk_bf16_f32 v76, v66, v67
	v_mul_f32_e32 v66, 0xbfb8aa3b, v72
	v_mul_f32_e32 v67, 0xbfb8aa3b, v73
	v_exp_f32_e32 v66, v66
	v_exp_f32_e32 v67, v67
	v_add_f32_e32 v66, 1.0, v66
	v_add_f32_e32 v67, 1.0, v67
	v_rcp_f32_e32 v66, v66
	v_rcp_f32_e32 v67, v67
	s_nop 0
	v_pk_mul_f32 v[66:67], v[72:73], v[66:67]
	s_nop 0
	v_pk_mul_f32 v[66:67], v[66:67], v[68:69]
	v_add_u32_e32 v68, 0x80, v153
	v_cvt_pk_bf16_f32 v77, v66, v67
	v_or_b32_e32 v66, 48, v153
	v_mad_i64_i32 v[66:67], s[24:25], v66, s63, v[114:115]
	v_lshl_add_u64 v[66:67], v[66:67], 0, v[116:117]
	global_store_dwordx4 v[66:67], v[74:77], off
	v_mul_f32_e32 v66, 0xbfb8aa3b, v62
	v_mul_f32_e32 v67, 0xbfb8aa3b, v63
	v_exp_f32_e32 v66, v66
	v_exp_f32_e32 v67, v67
	v_add_f32_e32 v66, 1.0, v66
	v_add_f32_e32 v67, 1.0, v67
	v_rcp_f32_e32 v66, v66
	v_rcp_f32_e32 v67, v67
	s_nop 0
	v_pk_mul_f32 v[62:63], v[62:63], v[66:67]
	s_nop 0
	v_pk_mul_f32 v[58:59], v[62:63], v[58:59]
	s_nop 0
	v_cvt_pk_bf16_f32 v58, v58, v59
	v_mul_f32_e32 v59, 0xbfb8aa3b, v64
	v_exp_f32_e32 v59, v59
	s_nop 0
	v_add_f32_e32 v59, 1.0, v59
	v_rcp_f32_e32 v62, v59
	v_mul_f32_e32 v59, 0xbfb8aa3b, v65
	v_exp_f32_e32 v59, v59
	s_nop 0
	v_add_f32_e32 v59, 1.0, v59
	v_rcp_f32_e32 v63, v59
	s_nop 0
	v_pk_mul_f32 v[62:63], v[64:65], v[62:63]
	s_nop 0
	v_pk_mul_f32 v[60:61], v[62:63], v[60:61]
	s_nop 0
	v_cvt_pk_bf16_f32 v59, v60, v61
	v_mul_f32_e32 v60, 0xbfb8aa3b, v54
	v_mul_f32_e32 v61, 0xbfb8aa3b, v55
	v_exp_f32_e32 v60, v60
	v_exp_f32_e32 v61, v61
	v_add_f32_e32 v60, 1.0, v60
	v_add_f32_e32 v61, 1.0, v61
	v_rcp_f32_e32 v60, v60
	v_rcp_f32_e32 v61, v61
	s_nop 0
	v_pk_mul_f32 v[54:55], v[54:55], v[60:61]
	s_nop 0
	v_pk_mul_f32 v[50:51], v[54:55], v[50:51]
	s_nop 0
	v_cvt_pk_bf16_f32 v60, v50, v51
	v_mul_f32_e32 v50, 0xbfb8aa3b, v56
	v_mul_f32_e32 v51, 0xbfb8aa3b, v57
	v_exp_f32_e32 v50, v50
	v_exp_f32_e32 v51, v51
	v_add_f32_e32 v50, 1.0, v50
	v_add_f32_e32 v51, 1.0, v51
	v_rcp_f32_e32 v50, v50
	v_rcp_f32_e32 v51, v51
	s_nop 0
	v_pk_mul_f32 v[50:51], v[56:57], v[50:51]
	s_nop 0
	v_pk_mul_f32 v[50:51], v[50:51], v[52:53]
	s_nop 0
	v_cvt_pk_bf16_f32 v61, v50, v51
	v_mad_i64_i32 v[50:51], s[24:25], v68, s63, v[114:115]
	v_lshl_add_u64 v[50:51], v[50:51], 0, v[116:117]
	global_store_dwordx4 v[50:51], v[58:61], off
	v_mul_f32_e32 v50, 0xbfb8aa3b, v46
	v_mul_f32_e32 v51, 0xbfb8aa3b, v47
	v_exp_f32_e32 v50, v50
	v_exp_f32_e32 v51, v51
	v_add_f32_e32 v50, 1.0, v50
	v_add_f32_e32 v51, 1.0, v51
	v_rcp_f32_e32 v50, v50
	v_rcp_f32_e32 v51, v51
	s_nop 0
	v_pk_mul_f32 v[46:47], v[46:47], v[50:51]
	s_nop 0
	v_pk_mul_f32 v[42:43], v[46:47], v[42:43]
	s_nop 0
	v_cvt_pk_bf16_f32 v42, v42, v43
	v_mul_f32_e32 v43, 0xbfb8aa3b, v48
	v_exp_f32_e32 v43, v43
	s_nop 0
	v_add_f32_e32 v43, 1.0, v43
	v_rcp_f32_e32 v46, v43
	v_mul_f32_e32 v43, 0xbfb8aa3b, v49
	v_exp_f32_e32 v43, v43
	s_nop 0
	v_add_f32_e32 v43, 1.0, v43
	v_rcp_f32_e32 v47, v43
	s_nop 0
	v_pk_mul_f32 v[46:47], v[48:49], v[46:47]
	s_nop 0
	v_pk_mul_f32 v[44:45], v[46:47], v[44:45]
	s_nop 0
	v_cvt_pk_bf16_f32 v43, v44, v45
	v_mul_f32_e32 v44, 0xbfb8aa3b, v38
	v_mul_f32_e32 v45, 0xbfb8aa3b, v39
	v_exp_f32_e32 v44, v44
	v_exp_f32_e32 v45, v45
	v_add_f32_e32 v44, 1.0, v44
; #define PG8_BAR __builtin_amdgcn_s_barrier()
; DI unsigned pk2(float lo, float hi) { f32x2 v = {lo, hi}; bf16x2_t b = __builtin_convertvector(v, bf16x2_t); return __builtin_bit_cast(unsigned, b); }
; DI float siluf_(float x) { return x * sigmoidf_(x); }
; template <class Epi, class Sched, bool ALIGN_EPI = false, bool SP2 = false>
; __device__ __forceinline__ void gemm_phase(PG8_LAS unsigned char* lds, const Gemm g, const Sched& S, const Epi& E) {
;     ...
;         if constexpr (ALIGN_EPI) { if (wr == 0) PG8_BAR; }
;         if constexpr (!Epi::AFTER_DRAIN) { E(acc, cur, wr, wc, fr, fq); S.done(cur); }
;         if (!has_next) break;
; #pragma unroll
;         for (int a = 0; a < 2; ++a)
; #pragma unroll
;             for (int b = 0; b < 2; ++b)
; #pragma unroll
;                 for (int m = 0; m < 4; ++m)
; #pragma unroll
;                     for (int n = 0; n < 2; ++n) acc[a][b][m][n] = (f32x4){0.f, 0.f, 0.f, 0.f};
;         cur = nxt; cA = nA; cB = nB; ++ui;
;         if constexpr (ALIGN_EPI) { if (wr == 1) PG8_BAR; }
;     }
;     DI void operator()(const f32x4 (&acc)[2][2][4][2], const pg8::Unit& u, int wr, int wc, int fr, int fq) const {
;         const int row0 = u.pm * 256 + wr * 64 + fr, col0 = u.pn * 128 + wc * 32 + 8 * fq;
; #pragma unroll
;         for (int ai = 0; ai < 2; ++ai)
; #pragma unroll
;             for (int m = 0; m < 4; ++m) {
;                 const f32x4 g0 = acc[ai][0][m][0], g1 = acc[ai][0][m][1], u0 = acc[ai][1][m][0], u1 = acc[ai][1][m][1];
;                 u32x4 w;
;                 w.x = pk2(siluf_(g0[0]) * u0[0], siluf_(g0[1]) * u0[1]); w.y = pk2(siluf_(g0[2]) * u0[2], siluf_(g0[3]) * u0[3]);
;                 w.z = pk2(siluf_(g1[0]) * u1[0], siluf_(g1[1]) * u1[1]); w.w = pk2(siluf_(g1[2]) * u1[2], siluf_(g1[3]) * u1[3]);
;                 *(u32x4*)(H + (size_t)(row0 + ai * 128 + m * 16) * DFF + col0) = w;
;             }
;     }
	v_add_f32_e32 v45, 1.0, v45
	v_rcp_f32_e32 v44, v44
	v_rcp_f32_e32 v45, v45
	s_nop 0
	v_pk_mul_f32 v[38:39], v[38:39], v[44:45]
	s_nop 0
	v_pk_mul_f32 v[34:35], v[38:39], v[34:35]
	s_nop 0
	v_cvt_pk_bf16_f32 v44, v34, v35
	v_mul_f32_e32 v34, 0xbfb8aa3b, v40
	v_mul_f32_e32 v35, 0xbfb8aa3b, v41
	v_exp_f32_e32 v34, v34
	v_exp_f32_e32 v35, v35
	v_add_f32_e32 v34, 1.0, v34
	v_add_f32_e32 v35, 1.0, v35
	v_rcp_f32_e32 v34, v34
	v_rcp_f32_e32 v35, v35
	s_nop 0
	v_pk_mul_f32 v[34:35], v[40:41], v[34:35]
	s_nop 0
	v_pk_mul_f32 v[34:35], v[34:35], v[36:37]
	s_nop 0
	v_cvt_pk_bf16_f32 v45, v34, v35
	v_add_u32_e32 v34, 0x90, v153
	v_mad_i64_i32 v[34:35], s[24:25], v34, s63, v[114:115]
	v_lshl_add_u64 v[34:35], v[34:35], 0, v[116:117]
	global_store_dwordx4 v[34:35], v[42:45], off
	v_mul_f32_e32 v34, 0xbfb8aa3b, v30
	v_mul_f32_e32 v35, 0xbfb8aa3b, v31
	v_exp_f32_e32 v34, v34
	v_exp_f32_e32 v35, v35
	v_add_f32_e32 v34, 1.0, v34
	v_add_f32_e32 v35, 1.0, v35
	v_rcp_f32_e32 v34, v34
	v_rcp_f32_e32 v35, v35
	s_nop 0
	v_pk_mul_f32 v[30:31], v[30:31], v[34:35]
	s_nop 0
	v_pk_mul_f32 v[26:27], v[30:31], v[26:27]
	s_nop 0
	v_cvt_pk_bf16_f32 v26, v26, v27
	v_mul_f32_e32 v27, 0xbfb8aa3b, v32
	v_exp_f32_e32 v27, v27
	s_nop 0
	v_add_f32_e32 v27, 1.0, v27
	v_rcp_f32_e32 v30, v27
	v_mul_f32_e32 v27, 0xbfb8aa3b, v33
	v_exp_f32_e32 v27, v27
	s_nop 0
	v_add_f32_e32 v27, 1.0, v27
	v_rcp_f32_e32 v31, v27
	s_nop 0
	v_pk_mul_f32 v[30:31], v[32:33], v[30:31]
	s_nop 0
	v_pk_mul_f32 v[28:29], v[30:31], v[28:29]
	s_nop 0
	v_cvt_pk_bf16_f32 v27, v28, v29
	v_mul_f32_e32 v28, 0xbfb8aa3b, v22
	v_mul_f32_e32 v29, 0xbfb8aa3b, v23
	v_exp_f32_e32 v28, v28
	v_exp_f32_e32 v29, v29
	v_add_f32_e32 v28, 1.0, v28
	v_add_f32_e32 v29, 1.0, v29
	v_rcp_f32_e32 v28, v28
	v_rcp_f32_e32 v29, v29
	s_nop 0
	v_pk_mul_f32 v[22:23], v[22:23], v[28:29]
	s_nop 0
	v_pk_mul_f32 v[18:19], v[22:23], v[18:19]
	s_nop 0
	v_cvt_pk_bf16_f32 v28, v18, v19
	v_mul_f32_e32 v18, 0xbfb8aa3b, v24
	v_mul_f32_e32 v19, 0xbfb8aa3b, v25
	v_exp_f32_e32 v18, v18
	v_exp_f32_e32 v19, v19
	v_add_f32_e32 v18, 1.0, v18
	v_add_f32_e32 v19, 1.0, v19
	v_rcp_f32_e32 v18, v18
	v_rcp_f32_e32 v19, v19
	s_nop 0
	v_pk_mul_f32 v[18:19], v[24:25], v[18:19]
	s_nop 0
	v_pk_mul_f32 v[18:19], v[18:19], v[20:21]
	s_nop 0
	v_cvt_pk_bf16_f32 v29, v18, v19
	v_add_u32_e32 v18, 0xa0, v153
	v_mad_i64_i32 v[18:19], s[24:25], v18, s63, v[114:115]
	v_lshl_add_u64 v[18:19], v[18:19], 0, v[116:117]
	global_store_dwordx4 v[18:19], v[26:29], off
	v_mul_f32_e32 v18, 0xbfb8aa3b, v14
	v_mul_f32_e32 v19, 0xbfb8aa3b, v15
	v_exp_f32_e32 v18, v18
	v_exp_f32_e32 v19, v19
	v_add_f32_e32 v18, 1.0, v18
	v_add_f32_e32 v19, 1.0, v19
	v_rcp_f32_e32 v18, v18
	v_rcp_f32_e32 v19, v19
	s_nop 0
	v_pk_mul_f32 v[14:15], v[14:15], v[18:19]
	s_nop 0
	v_pk_mul_f32 v[10:11], v[14:15], v[10:11]
	s_nop 0
	v_cvt_pk_bf16_f32 v10, v10, v11
	v_mul_f32_e32 v11, 0xbfb8aa3b, v16
	v_exp_f32_e32 v11, v11
	s_nop 0
	v_add_f32_e32 v11, 1.0, v11
	v_rcp_f32_e32 v14, v11
	v_mul_f32_e32 v11, 0xbfb8aa3b, v17
	v_exp_f32_e32 v11, v11
	s_nop 0
	v_add_f32_e32 v11, 1.0, v11
	v_rcp_f32_e32 v15, v11
	s_nop 0
	v_pk_mul_f32 v[14:15], v[16:17], v[14:15]
	s_nop 0
	v_pk_mul_f32 v[12:13], v[14:15], v[12:13]
	s_nop 0
	v_cvt_pk_bf16_f32 v11, v12, v13
	v_mul_f32_e32 v12, 0xbfb8aa3b, v6
	v_mul_f32_e32 v13, 0xbfb8aa3b, v7
	v_exp_f32_e32 v12, v12
	v_exp_f32_e32 v13, v13
	v_add_f32_e32 v12, 1.0, v12
	v_add_f32_e32 v13, 1.0, v13
	v_rcp_f32_e32 v12, v12
	v_rcp_f32_e32 v13, v13
	s_nop 0
	v_pk_mul_f32 v[6:7], v[6:7], v[12:13]
	s_nop 0
	v_pk_mul_f32 v[2:3], v[6:7], v[2:3]
	s_nop 0
	v_cvt_pk_bf16_f32 v12, v2, v3
	v_mul_f32_e32 v2, 0xbfb8aa3b, v8
	v_mul_f32_e32 v3, 0xbfb8aa3b, v9
	v_exp_f32_e32 v2, v2
	v_exp_f32_e32 v3, v3
	v_add_f32_e32 v2, 1.0, v2
	v_add_f32_e32 v3, 1.0, v3
	v_rcp_f32_e32 v2, v2
	v_rcp_f32_e32 v3, v3
	s_nop 0
	v_pk_mul_f32 v[2:3], v[8:9], v[2:3]
	s_nop 0
	v_pk_mul_f32 v[2:3], v[2:3], v[4:5]
	s_nop 0
	v_cvt_pk_bf16_f32 v13, v2, v3
	v_add_u32_e32 v2, 0xb0, v153
	v_mad_i64_i32 v[2:3], s[24:25], v2, s63, v[114:115]
	v_lshl_add_u64 v[2:3], v[2:3], 0, v[116:117]
	s_mov_b64 s[24:25], -1
	global_store_dwordx4 v[2:3], v[10:13], off
	s_mov_b32 s98, 1
	s_cbranch_vccnz .LBB0_96
	s_andn2_b64 vcc, exec, s[10:11]
	s_cbranch_vccnz .LBB0_95
	s_barrier
	s_branch .LBB0_95

; #define PG8_STAGE(bufoff, gbase, voff) do { _Pragma("unroll") for (int _i = 0; _i < 2; ++_i) \
;         __builtin_amdgcn_global_load_lds((const unsigned*)((const char*)(gbase) + (voff)[_i]), (PG8_LAS unsigned*)(lds + (bufoff) + ldsw + _i * 8192), 16, 0, 0); } while (0)
; #define PG8_WAIT_V(n) asm volatile("s_waitcnt vmcnt(" #n ")" ::: "memory")
; #define PG8_BAR __builtin_amdgcn_s_barrier()
; DI float fexp2(float x) { return __builtin_amdgcn_exp2f(x); }
; template <class Epi, class Sched, bool ALIGN_EPI = false, bool SP2 = false>
; __device__ __forceinline__ void gemm_phase(PG8_LAS unsigned char* lds, const Gemm g, const Sched& S, const Epi& E) {
;     ...
;         PG8_STAGE(PG8_SB(0, 0), cB, voffB); PG8_STAGE(PG8_SB(0, 1), cB + hstep, voffB); PG8_STAGE(PG8_SA(0, 0), cA, voffA); PG8_STAGE(PG8_SA(0, 1), cA + hstep, voffA);
;         if (wr == 1) PG8_BAR;
;         PG8_WAIT_V(2); PG8_BAR;
;         PG8_STAGE(PG8_SB(1, 0), cB + kstep, voffB); PG8_STAGE(PG8_SA(1, 0), cA + kstep, voffA); PG8_STAGE(PG8_SB(1, 1), cB + hstep + kstep, voffB);
;         PG8_WAIT_V(6); PG8_BAR;
;     DI void operator()(const f32x4 (&acc)[2][2][4][2], const pg8::Unit& u, int wr, int wc, int fr, int fq) const {
;     ...
;         const int dlo = 16 * (wc & 1) + 4 * fq;
;         float frev[4];
; #pragma unroll
;         for (int i = 0; i < 4; ++i) frev[i] = fexp2(-(float)(dlo + i) * (13.287712379549449f / 32.f)) * 0.15915494309189535f;
.LBB0_486:
	v_and_b32_e32 v147, 15, v10
	v_bfe_u32 v17, v10, 4, 2
	v_lshlrev_b32_e32 v144, 6, v147
	v_lshlrev_b32_e32 v19, 2, v10
	s_and_b32 s3, s0, 3
	s_lshl_b32 s23, s1, 6
	v_lshl_or_b32 v18, v17, 4, v144
	s_lshl_b32 s1, s1, 13
	v_and_b32_e32 v19, 32, v19
	v_bitop3_b32 v20, v18, s1, v19 bitop3:0xde
	s_lshl_b32 s1, s3, 12
	v_readlane_b32 s10, v253, 17
	v_readlane_b32 s11, v253, 18
	s_add_u32 s10, s10, 0x32000000
	s_mov_b64 s[24:25], 0x80
	s_addc_u32 s11, s11, 0
	s_add_i32 m0, s61, 0x18000
	v_lshl_add_u64 v[8:9], v[8:9], 0, s[24:25]
	v_writelane_b32 v254, s10, 17
	s_waitcnt vmcnt(2)
	s_barrier
	global_load_lds_dwordx4 v[8:9], off
	v_lshl_add_u64 v[6:7], v[6:7], 0, s[24:25]
	s_add_i32 m0, s61, 0x1a000
	s_add_i32 s29, s61, 0x8000
	s_add_i32 s20, s61, 0xa000
	v_writelane_b32 v254, s11, 18
	global_load_lds_dwordx4 v[6:7], off
	v_lshl_add_u64 v[4:5], v[4:5], 0, s[24:25]
	s_mov_b32 m0, s29
	s_add_u32 s10, s6, 0x80080
	global_load_lds_dwordx4 v[4:5], off
	v_lshl_add_u64 v[2:3], v[2:3], 0, s[24:25]
	s_mov_b32 m0, s20
	s_addc_u32 s11, s7, 0
	global_load_lds_dwordx4 v[2:3], off
	s_add_i32 m0, s61, 0x1c000
	v_lshl_add_u64 v[2:3], s[10:11], 0, v[138:139]
	global_load_lds_dwordx4 v[2:3], off
	v_lshl_add_u64 v[2:3], s[10:11], 0, v[140:141]
	s_add_i32 m0, s61, 0x1e000
	s_cmpk_lt_u32 s8, 0x100
	global_load_lds_dwordx4 v[2:3], off
	v_bitop3_b32 v149, v18, s1, v19 bitop3:0xde
	s_cselect_b64 s[8:9], -1, 0
	s_lshl_b32 s1, s0, 4
	v_lshlrev_b32_e32 v2, 2, v17
	v_and_or_b32 v146, s1, 16, v2
	v_cvt_f32_ubyte0_e32 v3, v146
	v_mul_f32_e32 v3, 0xbed49a78, v3
	v_exp_f32_e32 v3, v3
	v_writelane_b32 v254, s8, 19
	s_bfe_u32 s34, s0, 0x10001
	v_lshl_or_b32 v195, s3, 5, v2
	v_mul_f32_e32 v190, 0.15915494, v3
	v_mov_b32_e32 v3, 0x800
	v_lshlrev_b32_e32 v2, 15, v11
	v_writelane_b32 v254, s9, 20
	v_or_b32_e32 v4, 1, v146
	v_or_b32_e32 v5, 2, v146
	v_or_b32_e32 v6, 3, v146
	v_and_or_b32 v194, v10, 7, v3
	s_or_b32 s36, s34, 2
	v_mov_b32_e32 v3, 0x3f000
	v_readlane_b32 s8, v253, 3
	v_and_b32_e32 v2, 0xffff0000, v2
	v_cvt_f32_ubyte0_e32 v4, v4
	v_cvt_f32_ubyte0_e32 v5, v5
	v_cvt_f32_ubyte0_e32 v6, v6
	s_lshl_b32 s21, s34, 6
	s_lshl_b32 s28, s36, 6
	v_lshl_or_b32 v148, v147, 9, v3
	s_ashr_i32 s27, s78, 31
	s_ashr_i32 s26, s66, 31
	v_readlane_b32 s10, v253, 5
	v_lshl_add_u32 v2, v12, 12, v2
	v_and_b32_e32 v3, 1, v11
	v_mul_f32_e32 v4, 0xbed49a78, v4
	v_mul_f32_e32 v5, 0xbed49a78, v5
	v_mul_f32_e32 v6, 0xbed49a78, v6
	v_readlane_b32 s11, v253, 6
	s_add_u32 s0, s10, 0xd800000
	v_lshl_or_b32 v2, v3, 6, v2
	v_exp_f32_e32 v4, v4
	v_exp_f32_e32 v5, v5
	v_exp_f32_e32 v6, v6
	s_addc_u32 s1, s11, 0
	v_lshl_add_u32 v150, v13, 1, v2
	v_lshlrev_b32_e32 v2, 15, v14
	v_writelane_b32 v254, s0, 21
	v_and_b32_e32 v2, 0xffff0000, v2
	s_waitcnt vmcnt(6)
	s_add_u32 s40, s10, 0xc500000
	v_writelane_b32 v254, s1, 22
	v_lshl_add_u32 v2, v15, 12, v2
	v_and_b32_e32 v3, 1, v14
	s_addc_u32 s41, s11, 0
	v_lshl_or_b32 v2, v3, 6, v2
	s_add_i32 s38, 0, 0x10000
	s_add_i32 s39, 0, 0x14000
	v_writelane_b32 v254, s78, 23
	v_mul_f32_e32 v191, 0.15915494, v4
	v_mul_f32_e32 v192, 0.15915494, v5
	v_mul_f32_e32 v193, 0.15915494, v6
	s_mov_b32 s35, s19
	s_mov_b32 s37, s19
	v_mov_b32_e32 v151, v143
	v_lshl_add_u32 v152, v16, 1, v2
	v_mov_b32_e32 v153, v143
	v_mov_b64_e32 v[154:155], 0x5d8
	v_mov_b64_e32 v[156:157], 0x5d7
	v_add_u32_e32 v196, s38, v149
	v_add_u32_e32 v197, s39, v149
	v_add_u32_e32 v198, 0, v20
	s_mov_b64 s[50:51], 0x2a00000
	s_mov_b64 s[52:53], 0x3580000
	s_mov_b64 s[54:55], 0x2200000
	s_mov_b64 s[56:57], 0x3500000
	s_movk_i32 s13, 0x5ff
	s_mov_b32 s58, 0x3e000000
	s_movk_i32 s14, 0x1800
	v_mov_b32_e32 v199, 0x3db504f3
	s_mov_b32 s15, 0
	v_writelane_b32 v254, s79, 24
	s_barrier
	v_readlane_b32 s9, v253, 4
	s_mov_b32 s98, 0
	s_branch .LBB0_489

; #define PG8_STAGE(bufoff, gbase, voff) do { _Pragma("unroll") for (int _i = 0; _i < 2; ++_i) \
;         __builtin_amdgcn_global_load_lds((const unsigned*)((const char*)(gbase) + (voff)[_i]), (PG8_LAS unsigned*)(lds + (bufoff) + ldsw + _i * 8192), 16, 0, 0); } while (0)
; #define PG8_LDA(dst, b, h) do { _Pragma("unroll") for (int m = 0; m < 4; ++m) _Pragma("unroll") for (int k = 0; k < 2; ++k) dst[m][k] = *(const PG8_LAS bf16x8*)(lds + PG8_SA(b, h) + aoff + m * 2048 + k * 1024); } while (0)
; #define PG8_LDB(dst, b, h) do { _Pragma("unroll") for (int n = 0; n < 2; ++n) _Pragma("unroll") for (int k = 0; k < 2; ++k) dst[n][k] = *(const PG8_LAS bf16x8*)(lds + PG8_SB(b, h) + boff + n * 2048 + k * 1024); } while (0)
; #define PG8_WAIT_V(n) asm volatile("s_waitcnt vmcnt(" #n ")" ::: "memory")
; #define PG8_WAIT_L(n) asm volatile("s_waitcnt lgkmcnt(" #n ")" ::: "memory")
; #define PG8_BAR __builtin_amdgcn_s_barrier()
; #define PG8_SCHED __builtin_amdgcn_sched_barrier(0)
; template <class Epi, class Sched, bool ALIGN_EPI = false, bool SP2 = false>
; __device__ __forceinline__ void gemm_phase(PG8_LAS unsigned char* lds, const Gemm g, const Sched& S, const Epi& E) {
;     ...
;         const char* nA = has_next ? (const char*)g.A + (size_t)nxt.pm * tstep + nxt.kb : cA; const char* nB = has_next ? (const char*)g.Bt + (size_t)nxt.pn * tstep + nxt.kb : cB;
;         for (int t = 0; t < nt; t += 2) {
;             const bool last = (t == nt - 2);
;             const char* a1 = cA + (size_t)(t + 1) * kstep;
;             const char* a2 = last ? nA : cA + (size_t)(t + 2) * kstep; const char* b2 = last ? nB : cB + (size_t)(t + 2) * kstep;
;             const char* a3 = a2 + kstep; const char* b3 = b2 + kstep;
;             if (last && has_next) S.a_ready(nxt);
;             if constexpr (SP2) {
;             PG8_LDB(B0, 0, 0); PG8_LDB(B1, 0, 1); PG8_SCHED; PG8_LDA(At, 0, 0); PG8_STAGE(PG8_SA(1, 1), a1 + hstep, voffA);
;             PG8_WAIT_V(8); PG8_WAIT_L(0); PG8_BAR; PG8_MMA(0, 0, At, B0); PG8_MMA(0, 1, At, B1); PG8_BAR; PG8_SCHED;
;     ...
; #pragma unroll
;         for (int a = 0; a < 2; ++a)
; #pragma unroll
;             for (int b = 0; b < 2; ++b)
; #pragma unroll
;                 for (int m = 0; m < 4; ++m)
; #pragma unroll
;                     for (int n = 0; n < 2; ++n) acc[a][b][m][n] = (f32x4){0.f, 0.f, 0.f, 0.f};
.LBB0_491:
	s_ashr_i32 s65, s64, 31
	s_lshl_b64 s[8:9], s[64:65], 20
	v_readlane_b32 s10, v253, 41
	v_readlane_b32 s11, v253, 42
	s_add_u32 s66, s10, s8
	s_addc_u32 s67, s11, s9
	s_and_b64 s[8:9], s[0:1], exec
	s_cselect_b32 s3, s67, s5
	s_cselect_b32 s10, s66, s4
	s_ashr_i32 s63, s62, 31
	s_lshl_b64 s[8:9], s[62:63], 20
	s_add_u32 s68, s80, s8
	s_addc_u32 s69, s81, s9
	s_and_b64 s[8:9], s[0:1], exec
	s_cselect_b32 s11, s69, s7
	s_cselect_b32 s12, s68, s6
	s_add_u32 s4, s4, 0x80080
	s_addc_u32 s5, s5, 0
	s_add_u32 s18, s6, 0x100
	v_mov_b32_e32 v2, 0
	s_addc_u32 s63, s7, 0
	s_mov_b32 s65, -2
	s_cmp_lg_u32 s98, 0
	s_cbranch_scc1 .Lpeel_1
	v_mov_b32_e32 v3, v2
	v_mov_b32_e32 v4, v2
	v_mov_b32_e32 v5, v2
	v_mov_b32_e32 v6, v2
	v_mov_b32_e32 v7, v2
	v_mov_b32_e32 v8, v2
	v_mov_b32_e32 v9, v2
	v_mov_b32_e32 v10, v2
	v_mov_b32_e32 v11, v2
	v_mov_b32_e32 v12, v2
	v_mov_b32_e32 v13, v2
	v_mov_b32_e32 v18, v2
	v_mov_b32_e32 v19, v2
	v_mov_b32_e32 v20, v2
	v_mov_b32_e32 v21, v2
	v_mov_b32_e32 v26, v2
	v_mov_b32_e32 v27, v2
	v_mov_b32_e32 v28, v2
	v_mov_b32_e32 v29, v2
	v_mov_b32_e32 v34, v2
	v_mov_b32_e32 v35, v2
	v_mov_b32_e32 v36, v2
	v_mov_b32_e32 v37, v2
	v_mov_b32_e32 v42, v2
	v_mov_b32_e32 v43, v2
	v_mov_b32_e32 v44, v2
	v_mov_b32_e32 v45, v2
	v_mov_b32_e32 v50, v2
	v_mov_b32_e32 v51, v2
	v_mov_b32_e32 v52, v2
	v_mov_b32_e32 v53, v2
	v_mov_b32_e32 v14, v2
	v_mov_b32_e32 v15, v2
	v_mov_b32_e32 v16, v2
	v_mov_b32_e32 v17, v2
	v_mov_b32_e32 v22, v2
	v_mov_b32_e32 v23, v2
	v_mov_b32_e32 v24, v2
	v_mov_b32_e32 v25, v2
	v_mov_b32_e32 v30, v2
	v_mov_b32_e32 v31, v2
	v_mov_b32_e32 v32, v2
	v_mov_b32_e32 v33, v2
	v_mov_b32_e32 v38, v2
	v_mov_b32_e32 v39, v2
	v_mov_b32_e32 v40, v2
	v_mov_b32_e32 v41, v2
	v_mov_b32_e32 v46, v2
	v_mov_b32_e32 v47, v2
	v_mov_b32_e32 v48, v2
	v_mov_b32_e32 v49, v2
	v_mov_b32_e32 v54, v2
	v_mov_b32_e32 v55, v2
	v_mov_b32_e32 v56, v2
	v_mov_b32_e32 v57, v2
	v_mov_b32_e32 v58, v2
	v_mov_b32_e32 v59, v2
	v_mov_b32_e32 v60, v2
	v_mov_b32_e32 v61, v2
	v_mov_b32_e32 v62, v2
	v_mov_b32_e32 v63, v2
	v_mov_b32_e32 v64, v2
	v_mov_b32_e32 v65, v2
	v_mov_b32_e32 v66, v2
	v_mov_b32_e32 v67, v2
	v_mov_b32_e32 v68, v2
	v_mov_b32_e32 v69, v2
	v_mov_b32_e32 v70, v2
	v_mov_b32_e32 v71, v2
	v_mov_b32_e32 v72, v2
	v_mov_b32_e32 v73, v2
	v_mov_b32_e32 v74, v2
	v_mov_b32_e32 v75, v2
	v_mov_b32_e32 v76, v2
	v_mov_b32_e32 v77, v2
	v_mov_b32_e32 v82, v2
	v_mov_b32_e32 v83, v2
	v_mov_b32_e32 v84, v2
	v_mov_b32_e32 v85, v2
	v_mov_b32_e32 v90, v2
	v_mov_b32_e32 v91, v2
	v_mov_b32_e32 v92, v2
	v_mov_b32_e32 v93, v2
	v_mov_b32_e32 v98, v2
	v_mov_b32_e32 v99, v2
	v_mov_b32_e32 v100, v2
	v_mov_b32_e32 v101, v2
	v_mov_b32_e32 v106, v2
	v_mov_b32_e32 v107, v2
	v_mov_b32_e32 v108, v2
	v_mov_b32_e32 v109, v2
	v_mov_b32_e32 v114, v2
	v_mov_b32_e32 v115, v2
	v_mov_b32_e32 v116, v2
	v_mov_b32_e32 v117, v2
	v_mov_b32_e32 v78, v2
	v_mov_b32_e32 v79, v2
	v_mov_b32_e32 v80, v2
	v_mov_b32_e32 v81, v2
	v_mov_b32_e32 v86, v2
	v_mov_b32_e32 v87, v2
	v_mov_b32_e32 v88, v2
	v_mov_b32_e32 v89, v2
	v_mov_b32_e32 v94, v2
	v_mov_b32_e32 v95, v2
	v_mov_b32_e32 v96, v2
	v_mov_b32_e32 v97, v2
	v_mov_b32_e32 v102, v2
	v_mov_b32_e32 v103, v2
	v_mov_b32_e32 v104, v2
	v_mov_b32_e32 v105, v2
	v_mov_b32_e32 v110, v2
	v_mov_b32_e32 v111, v2
	v_mov_b32_e32 v112, v2
	v_mov_b32_e32 v113, v2
	v_mov_b32_e32 v118, v2
	v_mov_b32_e32 v119, v2
	v_mov_b32_e32 v120, v2
	v_mov_b32_e32 v121, v2
	v_mov_b32_e32 v122, v2
	v_mov_b32_e32 v123, v2
	v_mov_b32_e32 v124, v2
	v_mov_b32_e32 v125, v2
	v_mov_b32_e32 v126, v2
	v_mov_b32_e32 v127, v2
	v_mov_b32_e32 v128, v2
	v_mov_b32_e32 v129, v2
.LBB0_492:
	ds_read_b128 v[130:133], v196
	ds_read_b128 v[134:137], v196 offset:1024
	ds_read_b128 v[158:161], v196 offset:2048
	ds_read_b128 v[162:165], v196 offset:3072
	ds_read_b128 v[166:169], v197
	ds_read_b128 v[170:173], v197 offset:1024
	ds_read_b128 v[174:177], v197 offset:2048
	ds_read_b128 v[178:181], v197 offset:3072
	s_add_u32 s6, s4, 0xfff80080
	s_addc_u32 s7, s5, -1
	s_cmp_eq_u32 s65, 28
	s_cselect_b32 s9, s3, s7
	s_cselect_b32 s8, s10, s6
	s_cselect_b32 s7, s11, s63
	s_cselect_b32 s6, s12, s18
	v_lshl_add_u64 v[224:225], s[4:5], 0, v[150:151]
	s_add_i32 m0, s61, 0xc000
	ds_read_b128 v[182:185], v198
	ds_read_b128 v[186:189], v198 offset:1024
	ds_read_b128 v[200:203], v198 offset:2048
	ds_read_b128 v[204:207], v198 offset:3072
	ds_read_b128 v[208:211], v198 offset:4096
	ds_read_b128 v[212:215], v198 offset:5120
	ds_read_b128 v[216:219], v198 offset:6144
	ds_read_b128 v[220:223], v198 offset:7168
	global_load_lds_dwordx4 v[224:225], off
	v_lshl_add_u64 v[224:225], s[4:5], 0, v[152:153]
	s_add_i32 m0, s61, 0xe000
	s_nop 0
	global_load_lds_dwordx4 v[224:225], off
	s_waitcnt vmcnt(8)
	s_waitcnt lgkmcnt(0)
	s_barrier
; #define PG8_STAGE(bufoff, gbase, voff) do { _Pragma("unroll") for (int _i = 0; _i < 2; ++_i) \
;         __builtin_amdgcn_global_load_lds((const unsigned*)((const char*)(gbase) + (voff)[_i]), (PG8_LAS unsigned*)(lds + (bufoff) + ldsw + _i * 8192), 16, 0, 0); } while (0)
; #define PG8_LDA(dst, b, h) do { _Pragma("unroll") for (int m = 0; m < 4; ++m) _Pragma("unroll") for (int k = 0; k < 2; ++k) dst[m][k] = *(const PG8_LAS bf16x8*)(lds + PG8_SA(b, h) + aoff + m * 2048 + k * 1024); } while (0)
; #define PG8_MMA(ai, bj, At, Bt) do { __builtin_amdgcn_s_setprio(1); _Pragma("unroll") for (int m = 0; m < 4; ++m) _Pragma("unroll") for (int n = 0; n < 2; ++n) _Pragma("unroll") for (int k = 0; k < 2; ++k) \
;         acc[ai][bj][m][n] = __builtin_amdgcn_mfma_f32_16x16x32_bf16(Bt[n][k], At[m][k], acc[ai][bj][m][n], 0, 0, 0); __builtin_amdgcn_s_setprio(0); } while (0)
; #define PG8_WAIT_V(n) asm volatile("s_waitcnt vmcnt(" #n ")" ::: "memory")
; #define PG8_WAIT_L(n) asm volatile("s_waitcnt lgkmcnt(" #n ")" ::: "memory")
; #define PG8_BAR __builtin_amdgcn_s_barrier()
; #define PG8_SCHED __builtin_amdgcn_sched_barrier(0)
; template <class Epi, class Sched, bool ALIGN_EPI = false, bool SP2 = false>
; __device__ __forceinline__ void gemm_phase(PG8_LAS unsigned char* lds, const Gemm g, const Sched& S, const Epi& E) {
;     ...
;             PG8_WAIT_V(8); PG8_WAIT_L(0); PG8_BAR; PG8_MMA(0, 0, At, B0); PG8_MMA(0, 1, At, B1); PG8_BAR; PG8_SCHED;
;             PG8_LDA(At, 0, 1); PG8_STAGE(PG8_SB(0, 0), b2, voffB); PG8_STAGE(PG8_SB(0, 1), b2 + hstep, voffB); PG8_STAGE(PG8_SA(0, 0), a2, voffA);
;             PG8_WAIT_V(8); PG8_WAIT_L(0); PG8_BAR; PG8_MMA(1, 0, At, B0); PG8_MMA(1, 1, At, B1); PG8_BAR; PG8_SCHED;
	s_setprio 1
	s_waitcnt lgkmcnt(0)
	v_mfma_f32_16x16x32_bf16 v[126:129], v[130:133], v[182:185], v[126:129]
	v_mfma_f32_16x16x32_bf16 v[122:125], v[158:161], v[182:185], v[122:125]
	v_mfma_f32_16x16x32_bf16 v[118:121], v[130:133], v[200:203], v[118:121]
	v_mfma_f32_16x16x32_bf16 v[110:113], v[158:161], v[200:203], v[110:113]
	v_mfma_f32_16x16x32_bf16 v[102:105], v[130:133], v[208:211], v[102:105]
	v_mfma_f32_16x16x32_bf16 v[94:97], v[158:161], v[208:211], v[94:97]
	v_mfma_f32_16x16x32_bf16 v[86:89], v[130:133], v[216:219], v[86:89]
	v_mfma_f32_16x16x32_bf16 v[78:81], v[158:161], v[216:219], v[78:81]
	v_mfma_f32_16x16x32_bf16 v[126:129], v[134:137], v[186:189], v[126:129]
	v_mfma_f32_16x16x32_bf16 v[122:125], v[162:165], v[186:189], v[122:125]
	v_mfma_f32_16x16x32_bf16 v[118:121], v[134:137], v[204:207], v[118:121]
	v_mfma_f32_16x16x32_bf16 v[110:113], v[162:165], v[204:207], v[110:113]
	v_mfma_f32_16x16x32_bf16 v[102:105], v[134:137], v[212:215], v[102:105]
	v_mfma_f32_16x16x32_bf16 v[94:97], v[162:165], v[212:215], v[94:97]
	v_mfma_f32_16x16x32_bf16 v[86:89], v[134:137], v[220:223], v[86:89]
	v_mfma_f32_16x16x32_bf16 v[78:81], v[162:165], v[220:223], v[78:81]
	s_setprio 0
	s_setprio 1
	v_mfma_f32_16x16x32_bf16 v[114:117], v[166:169], v[182:185], v[114:117]
	v_mfma_f32_16x16x32_bf16 v[106:109], v[174:177], v[182:185], v[106:109]
	v_mfma_f32_16x16x32_bf16 v[98:101], v[166:169], v[200:203], v[98:101]
	v_mfma_f32_16x16x32_bf16 v[90:93], v[174:177], v[200:203], v[90:93]
	v_mfma_f32_16x16x32_bf16 v[82:85], v[166:169], v[208:211], v[82:85]
	v_mfma_f32_16x16x32_bf16 v[74:77], v[174:177], v[208:211], v[74:77]
	v_mfma_f32_16x16x32_bf16 v[70:73], v[166:169], v[216:219], v[70:73]
	v_mfma_f32_16x16x32_bf16 v[66:69], v[174:177], v[216:219], v[66:69]
	v_mfma_f32_16x16x32_bf16 v[114:117], v[170:173], v[186:189], v[114:117]
	v_mfma_f32_16x16x32_bf16 v[106:109], v[178:181], v[186:189], v[106:109]
	v_mfma_f32_16x16x32_bf16 v[98:101], v[170:173], v[204:207], v[98:101]
	v_mfma_f32_16x16x32_bf16 v[90:93], v[178:181], v[204:207], v[90:93]
	v_mfma_f32_16x16x32_bf16 v[82:85], v[170:173], v[212:215], v[82:85]
	v_mfma_f32_16x16x32_bf16 v[74:77], v[178:181], v[212:215], v[74:77]
	v_mfma_f32_16x16x32_bf16 v[70:73], v[170:173], v[220:223], v[70:73]
	v_mfma_f32_16x16x32_bf16 v[66:69], v[178:181], v[220:223], v[66:69]
	s_setprio 0
	s_barrier
	s_add_i32 s70, s38, s59
	v_lshl_add_u64 v[224:225], s[6:7], 0, v[138:139]
	s_mov_b32 m0, s70
	ds_read_b128 v[182:185], v198 offset:16384
	ds_read_b128 v[186:189], v198 offset:17408
	ds_read_b128 v[200:203], v198 offset:18432
	ds_read_b128 v[204:207], v198 offset:19456
	ds_read_b128 v[208:211], v198 offset:20480
	ds_read_b128 v[212:215], v198 offset:21504
	ds_read_b128 v[216:219], v198 offset:22528
	ds_read_b128 v[220:223], v198 offset:23552
	global_load_lds_dwordx4 v[224:225], off
	s_add_i32 m0, s70, 0x2000
	s_add_u32 s70, s6, 0x80000
	v_lshl_add_u64 v[226:227], s[6:7], 0, v[140:141]
	s_addc_u32 s71, s7, 0
	s_add_i32 s72, s39, s59
	global_load_lds_dwordx4 v[226:227], off
	v_lshl_add_u64 v[228:229], s[70:71], 0, v[138:139]
	s_mov_b32 m0, s72
	v_lshl_add_u64 v[230:231], s[8:9], 0, v[140:141]
	global_load_lds_dwordx4 v[228:229], off
	v_lshl_add_u64 v[228:229], s[70:71], 0, v[140:141]
	s_add_i32 m0, s72, 0x2000
	s_nop 0
	global_load_lds_dwordx4 v[228:229], off
	v_lshl_add_u64 v[228:229], s[8:9], 0, v[138:139]
	s_mov_b32 m0, s61
	s_nop 0
	global_load_lds_dwordx4 v[228:229], off
	s_mov_b32 m0, s16
	s_nop 0
	global_load_lds_dwordx4 v[230:231], off
	s_waitcnt vmcnt(8)
	s_waitcnt lgkmcnt(0)
	s_barrier
	s_setprio 1
	s_waitcnt lgkmcnt(0)
	v_mfma_f32_16x16x32_bf16 v[62:65], v[130:133], v[182:185], v[62:65]
	v_mfma_f32_16x16x32_bf16 v[58:61], v[158:161], v[182:185], v[58:61]
	v_mfma_f32_16x16x32_bf16 v[54:57], v[130:133], v[200:203], v[54:57]
	v_mfma_f32_16x16x32_bf16 v[46:49], v[158:161], v[200:203], v[46:49]
	v_mfma_f32_16x16x32_bf16 v[38:41], v[130:133], v[208:211], v[38:41]
	v_mfma_f32_16x16x32_bf16 v[30:33], v[158:161], v[208:211], v[30:33]
	v_mfma_f32_16x16x32_bf16 v[22:25], v[130:133], v[216:219], v[22:25]
	v_mfma_f32_16x16x32_bf16 v[14:17], v[158:161], v[216:219], v[14:17]
	v_mfma_f32_16x16x32_bf16 v[62:65], v[134:137], v[186:189], v[62:65]
	v_mfma_f32_16x16x32_bf16 v[58:61], v[162:165], v[186:189], v[58:61]
	v_mfma_f32_16x16x32_bf16 v[54:57], v[134:137], v[204:207], v[54:57]
	v_mfma_f32_16x16x32_bf16 v[46:49], v[162:165], v[204:207], v[46:49]
	v_mfma_f32_16x16x32_bf16 v[38:41], v[134:137], v[212:215], v[38:41]
	v_mfma_f32_16x16x32_bf16 v[30:33], v[162:165], v[212:215], v[30:33]
	v_mfma_f32_16x16x32_bf16 v[22:25], v[134:137], v[220:223], v[22:25]
	v_mfma_f32_16x16x32_bf16 v[14:17], v[162:165], v[220:223], v[14:17]
	s_setprio 0
	s_setprio 1
	v_mfma_f32_16x16x32_bf16 v[50:53], v[166:169], v[182:185], v[50:53]
	v_mfma_f32_16x16x32_bf16 v[42:45], v[174:177], v[182:185], v[42:45]
	v_mfma_f32_16x16x32_bf16 v[34:37], v[166:169], v[200:203], v[34:37]
	v_mfma_f32_16x16x32_bf16 v[26:29], v[174:177], v[200:203], v[26:29]
	v_mfma_f32_16x16x32_bf16 v[18:21], v[166:169], v[208:211], v[18:21]
	v_mfma_f32_16x16x32_bf16 v[10:13], v[174:177], v[208:211], v[10:13]
	v_mfma_f32_16x16x32_bf16 v[6:9], v[166:169], v[216:219], v[6:9]
	v_mfma_f32_16x16x32_bf16 v[2:5], v[174:177], v[216:219], v[2:5]
	v_mfma_f32_16x16x32_bf16 v[50:53], v[170:173], v[186:189], v[50:53]
	v_mfma_f32_16x16x32_bf16 v[42:45], v[178:181], v[186:189], v[42:45]
	v_mfma_f32_16x16x32_bf16 v[34:37], v[170:173], v[204:207], v[34:37]
	v_mfma_f32_16x16x32_bf16 v[26:29], v[178:181], v[204:207], v[26:29]
	v_mfma_f32_16x16x32_bf16 v[18:21], v[170:173], v[212:215], v[18:21]
	v_mfma_f32_16x16x32_bf16 v[10:13], v[178:181], v[212:215], v[10:13]
	v_mfma_f32_16x16x32_bf16 v[6:9], v[170:173], v[220:223], v[6:9]
	v_mfma_f32_16x16x32_bf16 v[2:5], v[178:181], v[220:223], v[2:5]
	s_setprio 0
	s_barrier
; #define PG8_STAGE(bufoff, gbase, voff) do { _Pragma("unroll") for (int _i = 0; _i < 2; ++_i) \
;         __builtin_amdgcn_global_load_lds((const unsigned*)((const char*)(gbase) + (voff)[_i]), (PG8_LAS unsigned*)(lds + (bufoff) + ldsw + _i * 8192), 16, 0, 0); } while (0)
; #define PG8_LDA(dst, b, h) do { _Pragma("unroll") for (int m = 0; m < 4; ++m) _Pragma("unroll") for (int k = 0; k < 2; ++k) dst[m][k] = *(const PG8_LAS bf16x8*)(lds + PG8_SA(b, h) + aoff + m * 2048 + k * 1024); } while (0)
; #define PG8_LDB(dst, b, h) do { _Pragma("unroll") for (int n = 0; n < 2; ++n) _Pragma("unroll") for (int k = 0; k < 2; ++k) dst[n][k] = *(const PG8_LAS bf16x8*)(lds + PG8_SB(b, h) + boff + n * 2048 + k * 1024); } while (0)
; #define PG8_MMA(ai, bj, At, Bt) do { __builtin_amdgcn_s_setprio(1); _Pragma("unroll") for (int m = 0; m < 4; ++m) _Pragma("unroll") for (int n = 0; n < 2; ++n) _Pragma("unroll") for (int k = 0; k < 2; ++k) \
;         acc[ai][bj][m][n] = __builtin_amdgcn_mfma_f32_16x16x32_bf16(Bt[n][k], At[m][k], acc[ai][bj][m][n], 0, 0, 0); __builtin_amdgcn_s_setprio(0); } while (0)
; #define PG8_WAIT_V(n) asm volatile("s_waitcnt vmcnt(" #n ")" ::: "memory")
; #define PG8_WAIT_L(n) asm volatile("s_waitcnt lgkmcnt(" #n ")" ::: "memory")
; #define PG8_BAR __builtin_amdgcn_s_barrier()
; #define PG8_SCHED __builtin_amdgcn_sched_barrier(0)
; template <class Epi, class Sched, bool ALIGN_EPI = false, bool SP2 = false>
; __device__ __forceinline__ void gemm_phase(PG8_LAS unsigned char* lds, const Gemm g, const Sched& S, const Epi& E) {
;     ...
;             PG8_LDB(B0, 1, 0); PG8_LDB(B1, 1, 1); PG8_SCHED; PG8_LDA(At, 1, 0); PG8_STAGE(PG8_SA(0, 1), a2 + hstep, voffA);
;             PG8_WAIT_V(8); PG8_WAIT_L(0); PG8_BAR; PG8_MMA(0, 0, At, B0); PG8_MMA(0, 1, At, B1); PG8_BAR; PG8_SCHED;
;             PG8_LDA(At, 1, 1); PG8_STAGE(PG8_SB(1, 0), b3, voffB); PG8_STAGE(PG8_SB(1, 1), b3 + hstep, voffB); PG8_STAGE(PG8_SA(1, 0), a3, voffA);
;             PG8_WAIT_V(8); PG8_WAIT_L(0); PG8_BAR; PG8_MMA(1, 0, At, B0); PG8_MMA(1, 1, At, B1); PG8_BAR; PG8_SCHED;
	s_add_i32 s70, 0, 0x18000
	v_add_u32_e32 v142, s70, v149
	s_add_i32 s71, 0, 0x1c000
	ds_read_b128 v[130:133], v142
	ds_read_b128 v[134:137], v142 offset:1024
	ds_read_b128 v[158:161], v142 offset:2048
	ds_read_b128 v[162:165], v142 offset:3072
	v_add_u32_e32 v142, s71, v149
	ds_read_b128 v[166:169], v142
	ds_read_b128 v[170:173], v142 offset:1024
	ds_read_b128 v[174:177], v142 offset:2048
	ds_read_b128 v[178:181], v142 offset:3072
	s_add_u32 s8, s8, 0x80000
	s_addc_u32 s9, s9, 0
	s_mov_b32 m0, s17
	v_lshl_add_u64 v[232:233], s[8:9], 0, v[138:139]
	ds_read_b128 v[182:185], v198 offset:32768
	ds_read_b128 v[186:189], v198 offset:33792
	ds_read_b128 v[200:203], v198 offset:34816
	ds_read_b128 v[204:207], v198 offset:35840
	ds_read_b128 v[208:211], v198 offset:36864
	ds_read_b128 v[212:215], v198 offset:37888
	ds_read_b128 v[216:219], v198 offset:38912
	ds_read_b128 v[220:223], v198 offset:39936
	global_load_lds_dwordx4 v[232:233], off
	v_lshl_add_u64 v[232:233], s[8:9], 0, v[140:141]
	s_mov_b32 m0, s33
	s_nop 0
	global_load_lds_dwordx4 v[232:233], off
	s_waitcnt vmcnt(8)
	s_waitcnt lgkmcnt(0)
	s_barrier
	s_setprio 1
	s_waitcnt lgkmcnt(0)
	v_mfma_f32_16x16x32_bf16 v[126:129], v[130:133], v[182:185], v[126:129]
	v_mfma_f32_16x16x32_bf16 v[122:125], v[158:161], v[182:185], v[122:125]
	v_mfma_f32_16x16x32_bf16 v[118:121], v[130:133], v[200:203], v[118:121]
	v_mfma_f32_16x16x32_bf16 v[110:113], v[158:161], v[200:203], v[110:113]
	v_mfma_f32_16x16x32_bf16 v[102:105], v[130:133], v[208:211], v[102:105]
	v_mfma_f32_16x16x32_bf16 v[94:97], v[158:161], v[208:211], v[94:97]
	v_mfma_f32_16x16x32_bf16 v[86:89], v[130:133], v[216:219], v[86:89]
	v_mfma_f32_16x16x32_bf16 v[78:81], v[158:161], v[216:219], v[78:81]
	v_mfma_f32_16x16x32_bf16 v[126:129], v[134:137], v[186:189], v[126:129]
	v_mfma_f32_16x16x32_bf16 v[122:125], v[162:165], v[186:189], v[122:125]
	v_mfma_f32_16x16x32_bf16 v[118:121], v[134:137], v[204:207], v[118:121]
	v_mfma_f32_16x16x32_bf16 v[110:113], v[162:165], v[204:207], v[110:113]
	v_mfma_f32_16x16x32_bf16 v[102:105], v[134:137], v[212:215], v[102:105]
	v_mfma_f32_16x16x32_bf16 v[94:97], v[162:165], v[212:215], v[94:97]
	v_mfma_f32_16x16x32_bf16 v[86:89], v[134:137], v[220:223], v[86:89]
	v_mfma_f32_16x16x32_bf16 v[78:81], v[162:165], v[220:223], v[78:81]
	s_setprio 0
	s_setprio 1
	v_mfma_f32_16x16x32_bf16 v[114:117], v[166:169], v[182:185], v[114:117]
	v_mfma_f32_16x16x32_bf16 v[106:109], v[174:177], v[182:185], v[106:109]
	v_mfma_f32_16x16x32_bf16 v[98:101], v[166:169], v[200:203], v[98:101]
	v_mfma_f32_16x16x32_bf16 v[90:93], v[174:177], v[200:203], v[90:93]
	v_mfma_f32_16x16x32_bf16 v[82:85], v[166:169], v[208:211], v[82:85]
	v_mfma_f32_16x16x32_bf16 v[74:77], v[174:177], v[208:211], v[74:77]
	v_mfma_f32_16x16x32_bf16 v[70:73], v[166:169], v[216:219], v[70:73]
	v_mfma_f32_16x16x32_bf16 v[66:69], v[174:177], v[216:219], v[66:69]
	v_mfma_f32_16x16x32_bf16 v[114:117], v[170:173], v[186:189], v[114:117]
	v_mfma_f32_16x16x32_bf16 v[106:109], v[178:181], v[186:189], v[106:109]
	v_mfma_f32_16x16x32_bf16 v[98:101], v[170:173], v[204:207], v[98:101]
	v_mfma_f32_16x16x32_bf16 v[90:93], v[178:181], v[204:207], v[90:93]
	v_mfma_f32_16x16x32_bf16 v[82:85], v[170:173], v[212:215], v[82:85]
	v_mfma_f32_16x16x32_bf16 v[74:77], v[178:181], v[212:215], v[74:77]
	v_mfma_f32_16x16x32_bf16 v[70:73], v[170:173], v[220:223], v[70:73]
	v_mfma_f32_16x16x32_bf16 v[66:69], v[178:181], v[220:223], v[66:69]
	s_setprio 0
	s_barrier
	s_add_i32 s8, s70, s59
	v_lshl_add_u64 v[224:225], v[224:225], 0, s[24:25]
	s_mov_b32 m0, s8
	ds_read_b128 v[182:185], v198 offset:49152
	ds_read_b128 v[186:189], v198 offset:50176
	ds_read_b128 v[200:203], v198 offset:51200
	ds_read_b128 v[204:207], v198 offset:52224
	ds_read_b128 v[208:211], v198 offset:53248
	ds_read_b128 v[212:215], v198 offset:54272
	ds_read_b128 v[216:219], v198 offset:55296
	ds_read_b128 v[220:223], v198 offset:56320
	global_load_lds_dwordx4 v[224:225], off
	s_add_i32 m0, s8, 0x2000
	s_add_u32 s6, s6, 0x80080
	v_lshl_add_u64 v[224:225], v[226:227], 0, s[24:25]
	s_addc_u32 s7, s7, 0
	s_add_i32 s8, s71, s59
	global_load_lds_dwordx4 v[224:225], off
	v_lshl_add_u64 v[224:225], s[6:7], 0, v[138:139]
	s_mov_b32 m0, s8
	s_nop 0
	global_load_lds_dwordx4 v[224:225], off
	v_lshl_add_u64 v[224:225], s[6:7], 0, v[140:141]
	s_add_i32 m0, s8, 0x2000
	s_nop 0
	global_load_lds_dwordx4 v[224:225], off
	v_lshl_add_u64 v[224:225], v[228:229], 0, s[24:25]
	s_mov_b32 m0, s29
	s_nop 0
	global_load_lds_dwordx4 v[224:225], off
	v_lshl_add_u64 v[224:225], v[230:231], 0, s[24:25]
	s_mov_b32 m0, s20
	s_nop 0
	global_load_lds_dwordx4 v[224:225], off
	s_waitcnt vmcnt(8)
	s_waitcnt lgkmcnt(0)
	s_barrier
; #define PG8_STAGE(bufoff, gbase, voff) do { _Pragma("unroll") for (int _i = 0; _i < 2; ++_i) \
;         __builtin_amdgcn_global_load_lds((const unsigned*)((const char*)(gbase) + (voff)[_i]), (PG8_LAS unsigned*)(lds + (bufoff) + ldsw + _i * 8192), 16, 0, 0); } while (0)
; #define PG8_LDA(dst, b, h) do { _Pragma("unroll") for (int m = 0; m < 4; ++m) _Pragma("unroll") for (int k = 0; k < 2; ++k) dst[m][k] = *(const PG8_LAS bf16x8*)(lds + PG8_SA(b, h) + aoff + m * 2048 + k * 1024); } while (0)
; #define PG8_LDB(dst, b, h) do { _Pragma("unroll") for (int n = 0; n < 2; ++n) _Pragma("unroll") for (int k = 0; k < 2; ++k) dst[n][k] = *(const PG8_LAS bf16x8*)(lds + PG8_SB(b, h) + boff + n * 2048 + k * 1024); } while (0)
; #define PG8_MMA(ai, bj, At, Bt) do { __builtin_amdgcn_s_setprio(1); _Pragma("unroll") for (int m = 0; m < 4; ++m) _Pragma("unroll") for (int n = 0; n < 2; ++n) _Pragma("unroll") for (int k = 0; k < 2; ++k) \
;         acc[ai][bj][m][n] = __builtin_amdgcn_mfma_f32_16x16x32_bf16(Bt[n][k], At[m][k], acc[ai][bj][m][n], 0, 0, 0); __builtin_amdgcn_s_setprio(0); } while (0)
; #define PG8_WAIT_V(n) asm volatile("s_waitcnt vmcnt(" #n ")" ::: "memory")
; template <class Epi, class Sched, bool ALIGN_EPI = false, bool SP2 = false>
; __device__ __forceinline__ void gemm_phase(PG8_LAS unsigned char* lds, const Gemm g, const Sched& S, const Epi& E) {
;     ...
;             PG8_LDB(B0, 0, 0); PG8_LDB(B1, 0, 1); PG8_SCHED; PG8_LDA(At, 0, 0); PG8_STAGE(PG8_SA(1, 1), a1 + hstep, voffA);
;             PG8_WAIT_V(8); PG8_WAIT_L(0); PG8_BAR; PG8_MMA(0, 0, At, B0); PG8_MMA(0, 1, At, B1); PG8_BAR; PG8_SCHED;
;             PG8_LDA(At, 0, 1); PG8_STAGE(PG8_SB(0, 0), b2, voffB); PG8_STAGE(PG8_SB(0, 1), b2 + hstep, voffB); PG8_STAGE(PG8_SA(0, 0), a2, voffA);
;             PG8_WAIT_V(8); PG8_WAIT_L(0); PG8_BAR; PG8_MMA(1, 0, At, B0); PG8_MMA(1, 1, At, B1); PG8_BAR; PG8_SCHED;
;             PG8_LDB(B0, 1, 0); PG8_LDB(B1, 1, 1); PG8_SCHED; PG8_LDA(At, 1, 0); PG8_STAGE(PG8_SA(0, 1), a2 + hstep, voffA);
;             PG8_WAIT_V(8); PG8_WAIT_L(0); PG8_BAR; PG8_MMA(0, 0, At, B0); PG8_MMA(0, 1, At, B1); PG8_BAR; PG8_SCHED;
;             PG8_LDA(At, 1, 1); PG8_STAGE(PG8_SB(1, 0), b3, voffB); PG8_STAGE(PG8_SB(1, 1), b3 + hstep, voffB); PG8_STAGE(PG8_SA(1, 0), a3, voffA);
;             PG8_WAIT_V(8); PG8_WAIT_L(0); PG8_BAR; PG8_MMA(1, 0, At, B0); PG8_MMA(1, 1, At, B1); PG8_BAR; PG8_SCHED;
	s_setprio 1
	s_waitcnt lgkmcnt(0)
	v_mfma_f32_16x16x32_bf16 v[62:65], v[130:133], v[182:185], v[62:65]
	v_mfma_f32_16x16x32_bf16 v[58:61], v[158:161], v[182:185], v[58:61]
	v_mfma_f32_16x16x32_bf16 v[54:57], v[130:133], v[200:203], v[54:57]
	v_mfma_f32_16x16x32_bf16 v[46:49], v[158:161], v[200:203], v[46:49]
	v_mfma_f32_16x16x32_bf16 v[38:41], v[130:133], v[208:211], v[38:41]
	v_mfma_f32_16x16x32_bf16 v[30:33], v[158:161], v[208:211], v[30:33]
	v_mfma_f32_16x16x32_bf16 v[22:25], v[130:133], v[216:219], v[22:25]
	v_mfma_f32_16x16x32_bf16 v[14:17], v[158:161], v[216:219], v[14:17]
	v_mfma_f32_16x16x32_bf16 v[62:65], v[134:137], v[186:189], v[62:65]
	v_mfma_f32_16x16x32_bf16 v[58:61], v[162:165], v[186:189], v[58:61]
	v_mfma_f32_16x16x32_bf16 v[54:57], v[134:137], v[204:207], v[54:57]
	v_mfma_f32_16x16x32_bf16 v[46:49], v[162:165], v[204:207], v[46:49]
	v_mfma_f32_16x16x32_bf16 v[38:41], v[134:137], v[212:215], v[38:41]
	v_mfma_f32_16x16x32_bf16 v[30:33], v[162:165], v[212:215], v[30:33]
	v_mfma_f32_16x16x32_bf16 v[22:25], v[134:137], v[220:223], v[22:25]
	v_mfma_f32_16x16x32_bf16 v[14:17], v[162:165], v[220:223], v[14:17]
	s_setprio 0
	s_setprio 1
	v_mfma_f32_16x16x32_bf16 v[50:53], v[166:169], v[182:185], v[50:53]
	v_mfma_f32_16x16x32_bf16 v[42:45], v[174:177], v[182:185], v[42:45]
	v_mfma_f32_16x16x32_bf16 v[34:37], v[166:169], v[200:203], v[34:37]
	v_mfma_f32_16x16x32_bf16 v[26:29], v[174:177], v[200:203], v[26:29]
	v_mfma_f32_16x16x32_bf16 v[18:21], v[166:169], v[208:211], v[18:21]
	v_mfma_f32_16x16x32_bf16 v[10:13], v[174:177], v[208:211], v[10:13]
	v_mfma_f32_16x16x32_bf16 v[6:9], v[166:169], v[216:219], v[6:9]
	v_mfma_f32_16x16x32_bf16 v[2:5], v[174:177], v[216:219], v[2:5]
	v_mfma_f32_16x16x32_bf16 v[50:53], v[170:173], v[186:189], v[50:53]
	v_mfma_f32_16x16x32_bf16 v[42:45], v[178:181], v[186:189], v[42:45]
	v_mfma_f32_16x16x32_bf16 v[34:37], v[170:173], v[204:207], v[34:37]
	v_mfma_f32_16x16x32_bf16 v[26:29], v[178:181], v[204:207], v[26:29]
	v_mfma_f32_16x16x32_bf16 v[18:21], v[170:173], v[212:215], v[18:21]
	v_mfma_f32_16x16x32_bf16 v[10:13], v[178:181], v[212:215], v[10:13]
	v_mfma_f32_16x16x32_bf16 v[6:9], v[170:173], v[220:223], v[6:9]
	v_mfma_f32_16x16x32_bf16 v[2:5], v[178:181], v[220:223], v[2:5]
	s_setprio 0
	s_barrier
	s_add_i32 s65, s65, 2
	s_add_u32 s4, s4, 0x100
	s_addc_u32 s5, s5, 0
	s_add_u32 s18, s18, 0x100
	s_addc_u32 s63, s63, 0
	s_cmp_gt_u32 s65, 29
	s_cbranch_scc0 .LBB0_492
	s_branch .Lpeel_after_1
.Lpeel_1:
	ds_read_b128 v[130:133], v196
	ds_read_b128 v[134:137], v196 offset:1024
	ds_read_b128 v[158:161], v196 offset:2048
	ds_read_b128 v[162:165], v196 offset:3072
	ds_read_b128 v[166:169], v197
	ds_read_b128 v[170:173], v197 offset:1024
	ds_read_b128 v[174:177], v197 offset:2048
	ds_read_b128 v[178:181], v197 offset:3072
	s_add_u32 s6, s4, 0xfff80080
	s_addc_u32 s7, s5, -1
	s_cmp_eq_u32 s65, 28
	s_cselect_b32 s9, s3, s7
	s_cselect_b32 s8, s10, s6
	s_cselect_b32 s7, s11, s63
	s_cselect_b32 s6, s12, s18
	v_lshl_add_u64 v[224:225], s[4:5], 0, v[150:151]
	s_add_i32 m0, s61, 0xc000
	ds_read_b128 v[182:185], v198
	ds_read_b128 v[186:189], v198 offset:1024
	ds_read_b128 v[200:203], v198 offset:2048
	ds_read_b128 v[204:207], v198 offset:3072
	ds_read_b128 v[208:211], v198 offset:4096
	ds_read_b128 v[212:215], v198 offset:5120
	ds_read_b128 v[216:219], v198 offset:6144
	ds_read_b128 v[220:223], v198 offset:7168
	global_load_lds_dwordx4 v[224:225], off
	v_lshl_add_u64 v[224:225], s[4:5], 0, v[152:153]
	s_add_i32 m0, s61, 0xe000
	s_nop 0
	global_load_lds_dwordx4 v[224:225], off
	s_waitcnt vmcnt(40)
	s_waitcnt lgkmcnt(0)
	s_barrier
	s_setprio 1
	s_waitcnt lgkmcnt(0)
	v_mfma_f32_16x16x32_bf16 v[126:129], v[130:133], v[182:185], 0
	v_mfma_f32_16x16x32_bf16 v[122:125], v[158:161], v[182:185], 0
	v_mfma_f32_16x16x32_bf16 v[118:121], v[130:133], v[200:203], 0
	v_mfma_f32_16x16x32_bf16 v[110:113], v[158:161], v[200:203], 0
	v_mfma_f32_16x16x32_bf16 v[102:105], v[130:133], v[208:211], 0
	v_mfma_f32_16x16x32_bf16 v[94:97], v[158:161], v[208:211], 0
	v_mfma_f32_16x16x32_bf16 v[86:89], v[130:133], v[216:219], 0
	v_mfma_f32_16x16x32_bf16 v[78:81], v[158:161], v[216:219], 0
	v_mfma_f32_16x16x32_bf16 v[126:129], v[134:137], v[186:189], v[126:129]
	v_mfma_f32_16x16x32_bf16 v[122:125], v[162:165], v[186:189], v[122:125]
	v_mfma_f32_16x16x32_bf16 v[118:121], v[134:137], v[204:207], v[118:121]
	v_mfma_f32_16x16x32_bf16 v[110:113], v[162:165], v[204:207], v[110:113]
	v_mfma_f32_16x16x32_bf16 v[102:105], v[134:137], v[212:215], v[102:105]
	v_mfma_f32_16x16x32_bf16 v[94:97], v[162:165], v[212:215], v[94:97]
	v_mfma_f32_16x16x32_bf16 v[86:89], v[134:137], v[220:223], v[86:89]
	v_mfma_f32_16x16x32_bf16 v[78:81], v[162:165], v[220:223], v[78:81]
	s_setprio 0
	s_setprio 1
	v_mfma_f32_16x16x32_bf16 v[114:117], v[166:169], v[182:185], 0
	v_mfma_f32_16x16x32_bf16 v[106:109], v[174:177], v[182:185], 0
	v_mfma_f32_16x16x32_bf16 v[98:101], v[166:169], v[200:203], 0
	v_mfma_f32_16x16x32_bf16 v[90:93], v[174:177], v[200:203], 0
	v_mfma_f32_16x16x32_bf16 v[82:85], v[166:169], v[208:211], 0
	v_mfma_f32_16x16x32_bf16 v[74:77], v[174:177], v[208:211], 0
	v_mfma_f32_16x16x32_bf16 v[70:73], v[166:169], v[216:219], 0
	v_mfma_f32_16x16x32_bf16 v[66:69], v[174:177], v[216:219], 0
	v_mfma_f32_16x16x32_bf16 v[114:117], v[170:173], v[186:189], v[114:117]
	v_mfma_f32_16x16x32_bf16 v[106:109], v[178:181], v[186:189], v[106:109]
	v_mfma_f32_16x16x32_bf16 v[98:101], v[170:173], v[204:207], v[98:101]
	v_mfma_f32_16x16x32_bf16 v[90:93], v[178:181], v[204:207], v[90:93]
	v_mfma_f32_16x16x32_bf16 v[82:85], v[170:173], v[212:215], v[82:85]
	v_mfma_f32_16x16x32_bf16 v[74:77], v[178:181], v[212:215], v[74:77]
	v_mfma_f32_16x16x32_bf16 v[70:73], v[170:173], v[220:223], v[70:73]
	v_mfma_f32_16x16x32_bf16 v[66:69], v[178:181], v[220:223], v[66:69]
	s_setprio 0
	s_barrier
; #define PG8_STAGE(bufoff, gbase, voff) do { _Pragma("unroll") for (int _i = 0; _i < 2; ++_i) \
;         __builtin_amdgcn_global_load_lds((const unsigned*)((const char*)(gbase) + (voff)[_i]), (PG8_LAS unsigned*)(lds + (bufoff) + ldsw + _i * 8192), 16, 0, 0); } while (0)
; #define PG8_LDA(dst, b, h) do { _Pragma("unroll") for (int m = 0; m < 4; ++m) _Pragma("unroll") for (int k = 0; k < 2; ++k) dst[m][k] = *(const PG8_LAS bf16x8*)(lds + PG8_SA(b, h) + aoff + m * 2048 + k * 1024); } while (0)
; #define PG8_LDB(dst, b, h) do { _Pragma("unroll") for (int n = 0; n < 2; ++n) _Pragma("unroll") for (int k = 0; k < 2; ++k) dst[n][k] = *(const PG8_LAS bf16x8*)(lds + PG8_SB(b, h) + boff + n * 2048 + k * 1024); } while (0)
; #define PG8_MMA(ai, bj, At, Bt) do { __builtin_amdgcn_s_setprio(1); _Pragma("unroll") for (int m = 0; m < 4; ++m) _Pragma("unroll") for (int n = 0; n < 2; ++n) _Pragma("unroll") for (int k = 0; k < 2; ++k) \
;         acc[ai][bj][m][n] = __builtin_amdgcn_mfma_f32_16x16x32_bf16(Bt[n][k], At[m][k], acc[ai][bj][m][n], 0, 0, 0); __builtin_amdgcn_s_setprio(0); } while (0)
; #define PG8_WAIT_V(n) asm volatile("s_waitcnt vmcnt(" #n ")" ::: "memory")
; #define PG8_WAIT_L(n) asm volatile("s_waitcnt lgkmcnt(" #n ")" ::: "memory")
; #define PG8_BAR __builtin_amdgcn_s_barrier()
; #define PG8_SCHED __builtin_amdgcn_sched_barrier(0)
; template <class Epi, class Sched, bool ALIGN_EPI = false, bool SP2 = false>
; __device__ __forceinline__ void gemm_phase(PG8_LAS unsigned char* lds, const Gemm g, const Sched& S, const Epi& E) {
;     ...
;             PG8_LDA(At, 0, 1); PG8_STAGE(PG8_SB(0, 0), b2, voffB); PG8_STAGE(PG8_SB(0, 1), b2 + hstep, voffB); PG8_STAGE(PG8_SA(0, 0), a2, voffA);
;             PG8_WAIT_V(8); PG8_WAIT_L(0); PG8_BAR; PG8_MMA(1, 0, At, B0); PG8_MMA(1, 1, At, B1); PG8_BAR; PG8_SCHED;
;             PG8_LDB(B0, 1, 0); PG8_LDB(B1, 1, 1); PG8_SCHED; PG8_LDA(At, 1, 0); PG8_STAGE(PG8_SA(0, 1), a2 + hstep, voffA);
;             PG8_WAIT_V(8); PG8_WAIT_L(0); PG8_BAR; PG8_MMA(0, 0, At, B0); PG8_MMA(0, 1, At, B1); PG8_BAR; PG8_SCHED;
	s_add_i32 s70, s38, s59
	v_lshl_add_u64 v[224:225], s[6:7], 0, v[138:139]
	s_mov_b32 m0, s70
	ds_read_b128 v[182:185], v198 offset:16384
	ds_read_b128 v[186:189], v198 offset:17408
	ds_read_b128 v[200:203], v198 offset:18432
	ds_read_b128 v[204:207], v198 offset:19456
	ds_read_b128 v[208:211], v198 offset:20480
	ds_read_b128 v[212:215], v198 offset:21504
	ds_read_b128 v[216:219], v198 offset:22528
	ds_read_b128 v[220:223], v198 offset:23552
	global_load_lds_dwordx4 v[224:225], off
	s_add_i32 m0, s70, 0x2000
	s_add_u32 s70, s6, 0x80000
	v_lshl_add_u64 v[226:227], s[6:7], 0, v[140:141]
	s_addc_u32 s71, s7, 0
	s_add_i32 s72, s39, s59
	global_load_lds_dwordx4 v[226:227], off
	v_lshl_add_u64 v[228:229], s[70:71], 0, v[138:139]
	s_mov_b32 m0, s72
	v_lshl_add_u64 v[230:231], s[8:9], 0, v[140:141]
	global_load_lds_dwordx4 v[228:229], off
	v_lshl_add_u64 v[228:229], s[70:71], 0, v[140:141]
	s_add_i32 m0, s72, 0x2000
	s_nop 0
	global_load_lds_dwordx4 v[228:229], off
	v_lshl_add_u64 v[228:229], s[8:9], 0, v[138:139]
	s_mov_b32 m0, s61
	s_nop 0
	global_load_lds_dwordx4 v[228:229], off
	s_mov_b32 m0, s16
	s_nop 0
	global_load_lds_dwordx4 v[230:231], off
	s_waitcnt vmcnt(40)
	s_waitcnt lgkmcnt(0)
	s_barrier
	s_setprio 1
	s_waitcnt lgkmcnt(0)
	v_mfma_f32_16x16x32_bf16 v[62:65], v[130:133], v[182:185], 0
	v_mfma_f32_16x16x32_bf16 v[58:61], v[158:161], v[182:185], 0
	v_mfma_f32_16x16x32_bf16 v[54:57], v[130:133], v[200:203], 0
	v_mfma_f32_16x16x32_bf16 v[46:49], v[158:161], v[200:203], 0
	v_mfma_f32_16x16x32_bf16 v[38:41], v[130:133], v[208:211], 0
	v_mfma_f32_16x16x32_bf16 v[30:33], v[158:161], v[208:211], 0
	v_mfma_f32_16x16x32_bf16 v[22:25], v[130:133], v[216:219], 0
	v_mfma_f32_16x16x32_bf16 v[14:17], v[158:161], v[216:219], 0
	v_mfma_f32_16x16x32_bf16 v[62:65], v[134:137], v[186:189], v[62:65]
	v_mfma_f32_16x16x32_bf16 v[58:61], v[162:165], v[186:189], v[58:61]
	v_mfma_f32_16x16x32_bf16 v[54:57], v[134:137], v[204:207], v[54:57]
	v_mfma_f32_16x16x32_bf16 v[46:49], v[162:165], v[204:207], v[46:49]
	v_mfma_f32_16x16x32_bf16 v[38:41], v[134:137], v[212:215], v[38:41]
	v_mfma_f32_16x16x32_bf16 v[30:33], v[162:165], v[212:215], v[30:33]
	v_mfma_f32_16x16x32_bf16 v[22:25], v[134:137], v[220:223], v[22:25]
	v_mfma_f32_16x16x32_bf16 v[14:17], v[162:165], v[220:223], v[14:17]
	s_setprio 0
	s_setprio 1
	v_mfma_f32_16x16x32_bf16 v[50:53], v[166:169], v[182:185], 0
	v_mfma_f32_16x16x32_bf16 v[42:45], v[174:177], v[182:185], 0
	v_mfma_f32_16x16x32_bf16 v[34:37], v[166:169], v[200:203], 0
	v_mfma_f32_16x16x32_bf16 v[26:29], v[174:177], v[200:203], 0
	v_mfma_f32_16x16x32_bf16 v[18:21], v[166:169], v[208:211], 0
	v_mfma_f32_16x16x32_bf16 v[10:13], v[174:177], v[208:211], 0
	v_mfma_f32_16x16x32_bf16 v[6:9], v[166:169], v[216:219], 0
	v_mfma_f32_16x16x32_bf16 v[2:5], v[174:177], v[216:219], 0
	v_mfma_f32_16x16x32_bf16 v[50:53], v[170:173], v[186:189], v[50:53]
	v_mfma_f32_16x16x32_bf16 v[42:45], v[178:181], v[186:189], v[42:45]
	v_mfma_f32_16x16x32_bf16 v[34:37], v[170:173], v[204:207], v[34:37]
	v_mfma_f32_16x16x32_bf16 v[26:29], v[178:181], v[204:207], v[26:29]
	v_mfma_f32_16x16x32_bf16 v[18:21], v[170:173], v[212:215], v[18:21]
	v_mfma_f32_16x16x32_bf16 v[10:13], v[178:181], v[212:215], v[10:13]
	v_mfma_f32_16x16x32_bf16 v[6:9], v[170:173], v[220:223], v[6:9]
	v_mfma_f32_16x16x32_bf16 v[2:5], v[178:181], v[220:223], v[2:5]
	s_setprio 0
	s_barrier
	s_add_i32 s70, 0, 0x18000
	v_add_u32_e32 v142, s70, v149
	s_add_i32 s71, 0, 0x1c000
	ds_read_b128 v[130:133], v142
	ds_read_b128 v[134:137], v142 offset:1024
	ds_read_b128 v[158:161], v142 offset:2048
	ds_read_b128 v[162:165], v142 offset:3072
	v_add_u32_e32 v142, s71, v149
	ds_read_b128 v[166:169], v142
	ds_read_b128 v[170:173], v142 offset:1024
	ds_read_b128 v[174:177], v142 offset:2048
	ds_read_b128 v[178:181], v142 offset:3072
	s_add_u32 s8, s8, 0x80000
	s_addc_u32 s9, s9, 0
	s_mov_b32 m0, s17
	v_lshl_add_u64 v[232:233], s[8:9], 0, v[138:139]
	ds_read_b128 v[182:185], v198 offset:32768
	ds_read_b128 v[186:189], v198 offset:33792
	ds_read_b128 v[200:203], v198 offset:34816
	ds_read_b128 v[204:207], v198 offset:35840
	ds_read_b128 v[208:211], v198 offset:36864
	ds_read_b128 v[212:215], v198 offset:37888
	ds_read_b128 v[216:219], v198 offset:38912
	ds_read_b128 v[220:223], v198 offset:39936
	global_load_lds_dwordx4 v[232:233], off
	v_lshl_add_u64 v[232:233], s[8:9], 0, v[140:141]
	s_mov_b32 m0, s33
	s_nop 0
	global_load_lds_dwordx4 v[232:233], off
	s_waitcnt vmcnt(8)
	s_waitcnt lgkmcnt(0)
	s_barrier
; #define PG8_STAGE(bufoff, gbase, voff) do { _Pragma("unroll") for (int _i = 0; _i < 2; ++_i) \
;         __builtin_amdgcn_global_load_lds((const unsigned*)((const char*)(gbase) + (voff)[_i]), (PG8_LAS unsigned*)(lds + (bufoff) + ldsw + _i * 8192), 16, 0, 0); } while (0)
; #define PG8_LDA(dst, b, h) do { _Pragma("unroll") for (int m = 0; m < 4; ++m) _Pragma("unroll") for (int k = 0; k < 2; ++k) dst[m][k] = *(const PG8_LAS bf16x8*)(lds + PG8_SA(b, h) + aoff + m * 2048 + k * 1024); } while (0)
; #define PG8_MMA(ai, bj, At, Bt) do { __builtin_amdgcn_s_setprio(1); _Pragma("unroll") for (int m = 0; m < 4; ++m) _Pragma("unroll") for (int n = 0; n < 2; ++n) _Pragma("unroll") for (int k = 0; k < 2; ++k) \
;         acc[ai][bj][m][n] = __builtin_amdgcn_mfma_f32_16x16x32_bf16(Bt[n][k], At[m][k], acc[ai][bj][m][n], 0, 0, 0); __builtin_amdgcn_s_setprio(0); } while (0)
; #define PG8_WAIT_V(n) asm volatile("s_waitcnt vmcnt(" #n ")" ::: "memory")
; #define PG8_WAIT_L(n) asm volatile("s_waitcnt lgkmcnt(" #n ")" ::: "memory")
; #define PG8_BAR __builtin_amdgcn_s_barrier()
; #define PG8_SCHED __builtin_amdgcn_sched_barrier(0)
; template <class Epi, class Sched, bool ALIGN_EPI = false, bool SP2 = false>
; __device__ __forceinline__ void gemm_phase(PG8_LAS unsigned char* lds, const Gemm g, const Sched& S, const Epi& E) {
;     ...
;             PG8_WAIT_V(8); PG8_WAIT_L(0); PG8_BAR; PG8_MMA(0, 0, At, B0); PG8_MMA(0, 1, At, B1); PG8_BAR; PG8_SCHED;
;             PG8_LDA(At, 1, 1); PG8_STAGE(PG8_SB(1, 0), b3, voffB); PG8_STAGE(PG8_SB(1, 1), b3 + hstep, voffB); PG8_STAGE(PG8_SA(1, 0), a3, voffA);
;             PG8_WAIT_V(8); PG8_WAIT_L(0); PG8_BAR; PG8_MMA(1, 0, At, B0); PG8_MMA(1, 1, At, B1); PG8_BAR; PG8_SCHED;
;     ...
;         if constexpr (ALIGN_EPI) { if (wr == 0) PG8_BAR; }
	s_setprio 1
	s_waitcnt lgkmcnt(0)
	v_mfma_f32_16x16x32_bf16 v[126:129], v[130:133], v[182:185], v[126:129]
	v_mfma_f32_16x16x32_bf16 v[122:125], v[158:161], v[182:185], v[122:125]
	v_mfma_f32_16x16x32_bf16 v[118:121], v[130:133], v[200:203], v[118:121]
	v_mfma_f32_16x16x32_bf16 v[110:113], v[158:161], v[200:203], v[110:113]
	v_mfma_f32_16x16x32_bf16 v[102:105], v[130:133], v[208:211], v[102:105]
	v_mfma_f32_16x16x32_bf16 v[94:97], v[158:161], v[208:211], v[94:97]
	v_mfma_f32_16x16x32_bf16 v[86:89], v[130:133], v[216:219], v[86:89]
	v_mfma_f32_16x16x32_bf16 v[78:81], v[158:161], v[216:219], v[78:81]
	v_mfma_f32_16x16x32_bf16 v[126:129], v[134:137], v[186:189], v[126:129]
	v_mfma_f32_16x16x32_bf16 v[122:125], v[162:165], v[186:189], v[122:125]
	v_mfma_f32_16x16x32_bf16 v[118:121], v[134:137], v[204:207], v[118:121]
	v_mfma_f32_16x16x32_bf16 v[110:113], v[162:165], v[204:207], v[110:113]
	v_mfma_f32_16x16x32_bf16 v[102:105], v[134:137], v[212:215], v[102:105]
	v_mfma_f32_16x16x32_bf16 v[94:97], v[162:165], v[212:215], v[94:97]
	v_mfma_f32_16x16x32_bf16 v[86:89], v[134:137], v[220:223], v[86:89]
	v_mfma_f32_16x16x32_bf16 v[78:81], v[162:165], v[220:223], v[78:81]
	s_setprio 0
	s_setprio 1
	v_mfma_f32_16x16x32_bf16 v[114:117], v[166:169], v[182:185], v[114:117]
	v_mfma_f32_16x16x32_bf16 v[106:109], v[174:177], v[182:185], v[106:109]
	v_mfma_f32_16x16x32_bf16 v[98:101], v[166:169], v[200:203], v[98:101]
	v_mfma_f32_16x16x32_bf16 v[90:93], v[174:177], v[200:203], v[90:93]
	v_mfma_f32_16x16x32_bf16 v[82:85], v[166:169], v[208:211], v[82:85]
	v_mfma_f32_16x16x32_bf16 v[74:77], v[174:177], v[208:211], v[74:77]
	v_mfma_f32_16x16x32_bf16 v[70:73], v[166:169], v[216:219], v[70:73]
	v_mfma_f32_16x16x32_bf16 v[66:69], v[174:177], v[216:219], v[66:69]
	v_mfma_f32_16x16x32_bf16 v[114:117], v[170:173], v[186:189], v[114:117]
	v_mfma_f32_16x16x32_bf16 v[106:109], v[178:181], v[186:189], v[106:109]
	v_mfma_f32_16x16x32_bf16 v[98:101], v[170:173], v[204:207], v[98:101]
	v_mfma_f32_16x16x32_bf16 v[90:93], v[178:181], v[204:207], v[90:93]
	v_mfma_f32_16x16x32_bf16 v[82:85], v[170:173], v[212:215], v[82:85]
	v_mfma_f32_16x16x32_bf16 v[74:77], v[178:181], v[212:215], v[74:77]
	v_mfma_f32_16x16x32_bf16 v[70:73], v[170:173], v[220:223], v[70:73]
	v_mfma_f32_16x16x32_bf16 v[66:69], v[178:181], v[220:223], v[66:69]
	s_setprio 0
	s_barrier
	s_add_i32 s8, s70, s59
	v_lshl_add_u64 v[224:225], v[224:225], 0, s[24:25]
	s_mov_b32 m0, s8
	ds_read_b128 v[182:185], v198 offset:49152
	ds_read_b128 v[186:189], v198 offset:50176
	ds_read_b128 v[200:203], v198 offset:51200
	ds_read_b128 v[204:207], v198 offset:52224
	ds_read_b128 v[208:211], v198 offset:53248
	ds_read_b128 v[212:215], v198 offset:54272
	ds_read_b128 v[216:219], v198 offset:55296
	ds_read_b128 v[220:223], v198 offset:56320
	global_load_lds_dwordx4 v[224:225], off
	s_add_i32 m0, s8, 0x2000
	s_add_u32 s6, s6, 0x80080
	v_lshl_add_u64 v[224:225], v[226:227], 0, s[24:25]
	s_addc_u32 s7, s7, 0
	s_add_i32 s8, s71, s59
	global_load_lds_dwordx4 v[224:225], off
	v_lshl_add_u64 v[224:225], s[6:7], 0, v[138:139]
	s_mov_b32 m0, s8
	s_nop 0
	global_load_lds_dwordx4 v[224:225], off
	v_lshl_add_u64 v[224:225], s[6:7], 0, v[140:141]
	s_add_i32 m0, s8, 0x2000
	s_nop 0
	global_load_lds_dwordx4 v[224:225], off
	v_lshl_add_u64 v[224:225], v[228:229], 0, s[24:25]
	s_mov_b32 m0, s29
	s_nop 0
	global_load_lds_dwordx4 v[224:225], off
	v_lshl_add_u64 v[224:225], v[230:231], 0, s[24:25]
	s_mov_b32 m0, s20
	s_nop 0
	global_load_lds_dwordx4 v[224:225], off
	s_waitcnt vmcnt(8)
	s_waitcnt lgkmcnt(0)
	s_barrier
	s_setprio 1
	s_waitcnt lgkmcnt(0)
	v_mfma_f32_16x16x32_bf16 v[62:65], v[130:133], v[182:185], v[62:65]
	v_mfma_f32_16x16x32_bf16 v[58:61], v[158:161], v[182:185], v[58:61]
	v_mfma_f32_16x16x32_bf16 v[54:57], v[130:133], v[200:203], v[54:57]
	v_mfma_f32_16x16x32_bf16 v[46:49], v[158:161], v[200:203], v[46:49]
	v_mfma_f32_16x16x32_bf16 v[38:41], v[130:133], v[208:211], v[38:41]
	v_mfma_f32_16x16x32_bf16 v[30:33], v[158:161], v[208:211], v[30:33]
	v_mfma_f32_16x16x32_bf16 v[22:25], v[130:133], v[216:219], v[22:25]
	v_mfma_f32_16x16x32_bf16 v[14:17], v[158:161], v[216:219], v[14:17]
	v_mfma_f32_16x16x32_bf16 v[62:65], v[134:137], v[186:189], v[62:65]
	v_mfma_f32_16x16x32_bf16 v[58:61], v[162:165], v[186:189], v[58:61]
	v_mfma_f32_16x16x32_bf16 v[54:57], v[134:137], v[204:207], v[54:57]
	v_mfma_f32_16x16x32_bf16 v[46:49], v[162:165], v[204:207], v[46:49]
	v_mfma_f32_16x16x32_bf16 v[38:41], v[134:137], v[212:215], v[38:41]
	v_mfma_f32_16x16x32_bf16 v[30:33], v[162:165], v[212:215], v[30:33]
	v_mfma_f32_16x16x32_bf16 v[22:25], v[134:137], v[220:223], v[22:25]
	v_mfma_f32_16x16x32_bf16 v[14:17], v[162:165], v[220:223], v[14:17]
	s_setprio 0
	s_setprio 1
	v_mfma_f32_16x16x32_bf16 v[50:53], v[166:169], v[182:185], v[50:53]
	v_mfma_f32_16x16x32_bf16 v[42:45], v[174:177], v[182:185], v[42:45]
	v_mfma_f32_16x16x32_bf16 v[34:37], v[166:169], v[200:203], v[34:37]
	v_mfma_f32_16x16x32_bf16 v[26:29], v[174:177], v[200:203], v[26:29]
	v_mfma_f32_16x16x32_bf16 v[18:21], v[166:169], v[208:211], v[18:21]
	v_mfma_f32_16x16x32_bf16 v[10:13], v[174:177], v[208:211], v[10:13]
	v_mfma_f32_16x16x32_bf16 v[6:9], v[166:169], v[216:219], v[6:9]
	v_mfma_f32_16x16x32_bf16 v[2:5], v[174:177], v[216:219], v[2:5]
	v_mfma_f32_16x16x32_bf16 v[50:53], v[170:173], v[186:189], v[50:53]
	v_mfma_f32_16x16x32_bf16 v[42:45], v[178:181], v[186:189], v[42:45]
	v_mfma_f32_16x16x32_bf16 v[34:37], v[170:173], v[204:207], v[34:37]
	v_mfma_f32_16x16x32_bf16 v[26:29], v[178:181], v[204:207], v[26:29]
	v_mfma_f32_16x16x32_bf16 v[18:21], v[170:173], v[212:215], v[18:21]
	v_mfma_f32_16x16x32_bf16 v[10:13], v[178:181], v[212:215], v[10:13]
	v_mfma_f32_16x16x32_bf16 v[6:9], v[170:173], v[220:223], v[6:9]
	v_mfma_f32_16x16x32_bf16 v[2:5], v[178:181], v[220:223], v[2:5]
	s_setprio 0
	s_barrier
	s_add_i32 s65, s65, 2
	s_add_u32 s4, s4, 0x100
	s_addc_u32 s5, s5, 0
	s_add_u32 s18, s18, 0x100
	s_addc_u32 s63, s63, 0
	s_cmp_gt_u32 s65, 29
	s_branch .LBB0_492
.Lpeel_after_1:
	v_readlane_b32 s4, v254, 19
	v_readlane_b32 s5, v254, 20
	s_and_b64 vcc, exec, s[4:5]
	s_cbranch_vccz .LBB0_495
	s_barrier

; #define PG8_STAGE(bufoff, gbase, voff) do { _Pragma("unroll") for (int _i = 0; _i < 2; ++_i) \
;         __builtin_amdgcn_global_load_lds((const unsigned*)((const char*)(gbase) + (voff)[_i]), (PG8_LAS unsigned*)(lds + (bufoff) + ldsw + _i * 8192), 16, 0, 0); } while (0)
; #define PG8_WAIT_V(n) asm volatile("s_waitcnt vmcnt(" #n ")" ::: "memory")
; #define PG8_BAR __builtin_amdgcn_s_barrier()
; template <class Epi, class Sched, bool ALIGN_EPI = false, bool SP2 = false>
; __device__ __forceinline__ void gemm_phase(PG8_LAS unsigned char* lds, const Gemm g, const Sched& S, const Epi& E) {
;     ...
;     for (int i = 0; i < 2; ++i) { int R, C; stage_rc(tid * 16 + i * 8192, R, C); const int Rb = Epi::PERM ? ((R & ~31) + perm32(R & 31)) : R;
;         voffA[i] = (unsigned)(R * LD + C) * 2u; voffB[i] = (unsigned)(Rb * LD + C) * 2u; }
;     const size_t kstep = (size_t)(BK * 2);
;     const size_t hstep = (size_t)HALF * LD * 2;
;     const size_t tstep = 2 * hstep;
;     const unsigned ldsw = (unsigned)wid * 1024u;
;     const int aoff = lds_byte(wr * 64 + fr, fq * 8), boff = lds_byte(wc * 32 + fr, fq * 8);
;     ...
;     if constexpr (SP2) {
;         PG8_STAGE(PG8_SB(0, 0), cB, voffB); PG8_STAGE(PG8_SB(0, 1), cB + hstep, voffB); PG8_STAGE(PG8_SA(0, 0), cA, voffA); PG8_STAGE(PG8_SA(0, 1), cA + hstep, voffA);
;         if (wr == 1) PG8_BAR;
;         PG8_WAIT_V(2); PG8_BAR;
;         PG8_STAGE(PG8_SB(1, 0), cB + kstep, voffB); PG8_STAGE(PG8_SA(1, 0), cA + kstep, voffA); PG8_STAGE(PG8_SB(1, 1), cB + hstep + kstep, voffB);
;         PG8_WAIT_V(6); PG8_BAR;
.LBB0_1965:
	s_lshl_b32 s4, s4, 5
	s_and_b32 s10, s4, 0x60
	s_mov_b64 s[4:5], 0x80
	s_add_i32 m0, s21, 0x18000
	v_lshl_add_u64 v[8:9], v[8:9], 0, s[4:5]
	s_lshl_b32 s7, s6, 13
	s_lshl_b32 s11, s10, 7
	s_waitcnt vmcnt(2)
	s_barrier
	global_load_lds_dwordx4 v[8:9], off
	v_lshl_add_u64 v[6:7], v[6:7], 0, s[4:5]
	s_add_i32 m0, s21, 0x1a000
	s_add_i32 s37, s21, 0x8000
	s_add_i32 s38, s21, 0xa000
	global_load_lds_dwordx4 v[6:7], off
	v_lshl_add_u64 v[2:3], v[2:3], 0, s[4:5]
	s_mov_b32 m0, s37
	s_add_u32 s8, s24, 0x80080
	global_load_lds_dwordx4 v[2:3], off
	v_lshl_add_u64 v[2:3], v[4:5], 0, s[4:5]
	s_mov_b32 m0, s38
	s_addc_u32 s9, s25, 0
	global_load_lds_dwordx4 v[2:3], off
	s_add_i32 m0, s21, 0x1c000
	v_lshl_add_u64 v[2:3], s[8:9], 0, v[136:137]
	global_load_lds_dwordx4 v[2:3], off
	v_lshl_add_u64 v[2:3], s[8:9], 0, v[132:133]
	s_add_i32 m0, s21, 0x1e000
	s_cmpk_lt_u32 s1, 0x100
	global_load_lds_dwordx4 v[2:3], off
	v_lshrrev_b32_e32 v3, 1, v12
	v_and_b32_e32 v3, 24, v3
	v_and_b32_e32 v2, 15, v12
	v_lshlrev_b32_e32 v4, 1, v3
	v_lshl_or_b32 v1, s6, 6, v2
	v_lshl_or_b32 v2, v2, 6, v4
	v_lshlrev_b32_e32 v4, 2, v12
	v_and_b32_e32 v4, 32, v4
	v_bitop3_b32 v5, v2, s7, v4 bitop3:0xde
	v_bitop3_b32 v131, v2, s11, v4 bitop3:0xde
	v_lshlrev_b32_e32 v2, 15, v15
	v_and_b32_e32 v2, 0xffff0000, v2
	v_or_b32_e32 v148, s10, v3
	v_lshl_add_u32 v2, v14, 12, v2
	v_and_b32_e32 v3, 1, v15
	v_lshl_or_b32 v2, v3, 6, v2
	v_lshl_add_u32 v140, v16, 1, v2
	v_lshlrev_b32_e32 v2, 15, v10
	v_and_b32_e32 v2, 0xffff0000, v2
	s_waitcnt vmcnt(6)
	v_lshl_add_u32 v2, v11, 12, v2
	v_and_b32_e32 v3, 1, v10
	s_cselect_b64 s[6:7], -1, 0
	v_lshl_or_b32 v2, v3, 6, v2
	s_add_i32 s40, 0, 0x10000
	s_add_i32 s41, 0, 0x14000
	s_sext_i32_i16 s43, s0
	s_ashr_i32 s39, s78, 31
	v_mov_b32_e32 v141, v137
	v_lshl_add_u32 v142, v13, 1, v2
	v_mov_b32_e32 v143, v137
	v_mov_b64_e32 v[144:145], 0xbb0
	v_mov_b64_e32 v[146:147], 0xbaf
	v_add_u32_e32 v149, s40, v131
	v_add_u32_e32 v150, s41, v131
	v_add_u32_e32 v151, 0, v5
	s_movk_i32 s42, 0x2c00
	s_barrier
	s_mov_b32 s98, 0
	s_branch .LBB0_1968

; #define PG8_STAGE(bufoff, gbase, voff) do { _Pragma("unroll") for (int _i = 0; _i < 2; ++_i) \
;         __builtin_amdgcn_global_load_lds((const unsigned*)((const char*)(gbase) + (voff)[_i]), (PG8_LAS unsigned*)(lds + (bufoff) + ldsw + _i * 8192), 16, 0, 0); } while (0)
; #define PG8_LDA(dst, b, h) do { _Pragma("unroll") for (int m = 0; m < 4; ++m) _Pragma("unroll") for (int k = 0; k < 2; ++k) dst[m][k] = *(const PG8_LAS bf16x8*)(lds + PG8_SA(b, h) + aoff + m * 2048 + k * 1024); } while (0)
; #define PG8_LDB(dst, b, h) do { _Pragma("unroll") for (int n = 0; n < 2; ++n) _Pragma("unroll") for (int k = 0; k < 2; ++k) dst[n][k] = *(const PG8_LAS bf16x8*)(lds + PG8_SB(b, h) + boff + n * 2048 + k * 1024); } while (0)
; #define PG8_WAIT_V(n) asm volatile("s_waitcnt vmcnt(" #n ")" ::: "memory")
; #define PG8_WAIT_L(n) asm volatile("s_waitcnt lgkmcnt(" #n ")" ::: "memory")
; #define PG8_BAR __builtin_amdgcn_s_barrier()
; #define PG8_SCHED __builtin_amdgcn_sched_barrier(0)
; template <class Epi, class Sched, bool ALIGN_EPI = false, bool SP2 = false>
; __device__ __forceinline__ void gemm_phase(PG8_LAS unsigned char* lds, const Gemm g, const Sched& S, const Epi& E) {
;     ...
;         const char* nA = has_next ? (const char*)g.A + (size_t)nxt.pm * tstep + nxt.kb : cA; const char* nB = has_next ? (const char*)g.Bt + (size_t)nxt.pn * tstep + nxt.kb : cB;
;         for (int t = 0; t < nt; t += 2) {
;             const bool last = (t == nt - 2);
;             const char* a1 = cA + (size_t)(t + 1) * kstep;
;             const char* a2 = last ? nA : cA + (size_t)(t + 2) * kstep; const char* b2 = last ? nB : cB + (size_t)(t + 2) * kstep;
;             const char* a3 = a2 + kstep; const char* b3 = b2 + kstep;
;             if (last && has_next) S.a_ready(nxt);
;             if constexpr (SP2) {
;             PG8_LDB(B0, 0, 0); PG8_LDB(B1, 0, 1); PG8_SCHED; PG8_LDA(At, 0, 0); PG8_STAGE(PG8_SA(1, 1), a1 + hstep, voffA);
;             PG8_WAIT_V(8); PG8_WAIT_L(0); PG8_BAR; PG8_MMA(0, 0, At, B0); PG8_MMA(0, 1, At, B1); PG8_BAR; PG8_SCHED;
;     ...
; #pragma unroll
;         for (int a = 0; a < 2; ++a)
; #pragma unroll
;             for (int b = 0; b < 2; ++b)
; #pragma unroll
;                 for (int m = 0; m < 4; ++m)
; #pragma unroll
;                     for (int n = 0; n < 2; ++n) acc[a][b][m][n] = (f32x4){0.f, 0.f, 0.f, 0.f};
.LBB0_1970:
	s_ashr_i32 s11, s10, 31
	s_lshl_b64 s[12:13], s[10:11], 20
	v_readlane_b32 s18, v253, 41
	v_readlane_b32 s19, v253, 42
	s_add_u32 s12, s18, s12
	s_addc_u32 s13, s19, s13
	s_and_b64 s[18:19], s[0:1], exec
	s_cselect_b32 s11, s13, s23
	s_cselect_b32 s46, s12, s22
	s_ashr_i32 s9, s8, 31
	s_lshl_b64 s[18:19], s[8:9], 20
	v_readlane_b32 s26, v253, 59
	v_readlane_b32 s27, v253, 60
	s_add_u32 s18, s26, s18
	s_addc_u32 s19, s27, s19
	s_and_b64 s[26:27], s[0:1], exec
	s_cselect_b32 s9, s19, s25
	s_cselect_b32 s47, s18, s24
	s_add_u32 s22, s22, 0x80080
	s_addc_u32 s23, s23, 0
	s_add_u32 s48, s24, 0x100
	v_mov_b32_e32 v2, 0
	s_addc_u32 s49, s25, 0
	s_mov_b32 s50, -2
	s_cmp_lg_u32 s98, 0
	s_cbranch_scc1 .Lpeel_2
	v_mov_b32_e32 v3, v2
	v_mov_b32_e32 v4, v2
	v_mov_b32_e32 v5, v2
	v_mov_b32_e32 v10, v2
	v_mov_b32_e32 v11, v2
	v_mov_b32_e32 v12, v2
	v_mov_b32_e32 v13, v2
	v_mov_b32_e32 v18, v2
	v_mov_b32_e32 v19, v2
	v_mov_b32_e32 v20, v2
	v_mov_b32_e32 v21, v2
	v_mov_b32_e32 v26, v2
	v_mov_b32_e32 v27, v2
	v_mov_b32_e32 v28, v2
	v_mov_b32_e32 v29, v2
	v_mov_b32_e32 v34, v2
	v_mov_b32_e32 v35, v2
	v_mov_b32_e32 v36, v2
	v_mov_b32_e32 v37, v2
	v_mov_b32_e32 v42, v2
	v_mov_b32_e32 v43, v2
	v_mov_b32_e32 v44, v2
	v_mov_b32_e32 v45, v2
	v_mov_b32_e32 v50, v2
	v_mov_b32_e32 v51, v2
	v_mov_b32_e32 v52, v2
	v_mov_b32_e32 v53, v2
	v_mov_b32_e32 v58, v2
	v_mov_b32_e32 v59, v2
	v_mov_b32_e32 v60, v2
	v_mov_b32_e32 v61, v2
	v_mov_b32_e32 v6, v2
	v_mov_b32_e32 v7, v2
	v_mov_b32_e32 v8, v2
	v_mov_b32_e32 v9, v2
	v_mov_b32_e32 v14, v2
	v_mov_b32_e32 v15, v2
	v_mov_b32_e32 v16, v2
	v_mov_b32_e32 v17, v2
	v_mov_b32_e32 v22, v2
	v_mov_b32_e32 v23, v2
	v_mov_b32_e32 v24, v2
	v_mov_b32_e32 v25, v2
	v_mov_b32_e32 v30, v2
	v_mov_b32_e32 v31, v2
	v_mov_b32_e32 v32, v2
	v_mov_b32_e32 v33, v2
	v_mov_b32_e32 v38, v2
	v_mov_b32_e32 v39, v2
	v_mov_b32_e32 v40, v2
	v_mov_b32_e32 v41, v2
	v_mov_b32_e32 v46, v2
	v_mov_b32_e32 v47, v2
	v_mov_b32_e32 v48, v2
	v_mov_b32_e32 v49, v2
	v_mov_b32_e32 v54, v2
	v_mov_b32_e32 v55, v2
	v_mov_b32_e32 v56, v2
	v_mov_b32_e32 v57, v2
	v_mov_b32_e32 v62, v2
	v_mov_b32_e32 v63, v2
	v_mov_b32_e32 v64, v2
	v_mov_b32_e32 v65, v2
	v_mov_b32_e32 v66, v2
	v_mov_b32_e32 v67, v2
	v_mov_b32_e32 v68, v2
	v_mov_b32_e32 v69, v2
	v_mov_b32_e32 v74, v2
	v_mov_b32_e32 v75, v2
	v_mov_b32_e32 v76, v2
	v_mov_b32_e32 v77, v2
	v_mov_b32_e32 v82, v2
	v_mov_b32_e32 v83, v2
	v_mov_b32_e32 v84, v2
	v_mov_b32_e32 v85, v2
	v_mov_b32_e32 v90, v2
	v_mov_b32_e32 v91, v2
	v_mov_b32_e32 v92, v2
	v_mov_b32_e32 v93, v2
	v_mov_b32_e32 v98, v2
	v_mov_b32_e32 v99, v2
	v_mov_b32_e32 v100, v2
	v_mov_b32_e32 v101, v2
	v_mov_b32_e32 v106, v2
	v_mov_b32_e32 v107, v2
	v_mov_b32_e32 v108, v2
	v_mov_b32_e32 v109, v2
	v_mov_b32_e32 v114, v2
	v_mov_b32_e32 v115, v2
	v_mov_b32_e32 v116, v2
	v_mov_b32_e32 v117, v2
	v_mov_b32_e32 v122, v2
	v_mov_b32_e32 v123, v2
	v_mov_b32_e32 v124, v2
	v_mov_b32_e32 v125, v2
	v_mov_b32_e32 v70, v2
	v_mov_b32_e32 v71, v2
	v_mov_b32_e32 v72, v2
	v_mov_b32_e32 v73, v2
	v_mov_b32_e32 v78, v2
	v_mov_b32_e32 v79, v2
	v_mov_b32_e32 v80, v2
	v_mov_b32_e32 v81, v2
	v_mov_b32_e32 v86, v2
	v_mov_b32_e32 v87, v2
	v_mov_b32_e32 v88, v2
	v_mov_b32_e32 v89, v2
	v_mov_b32_e32 v94, v2
	v_mov_b32_e32 v95, v2
	v_mov_b32_e32 v96, v2
	v_mov_b32_e32 v97, v2
	v_mov_b32_e32 v102, v2
	v_mov_b32_e32 v103, v2
	v_mov_b32_e32 v104, v2
	v_mov_b32_e32 v105, v2
	v_mov_b32_e32 v110, v2
	v_mov_b32_e32 v111, v2
	v_mov_b32_e32 v112, v2
	v_mov_b32_e32 v113, v2
	v_mov_b32_e32 v118, v2
	v_mov_b32_e32 v119, v2
	v_mov_b32_e32 v120, v2
	v_mov_b32_e32 v121, v2
	v_mov_b32_e32 v126, v2
	v_mov_b32_e32 v127, v2
	v_mov_b32_e32 v128, v2
	v_mov_b32_e32 v129, v2
.LBB0_1971:
	ds_read_b128 v[152:155], v149
	ds_read_b128 v[156:159], v149 offset:1024
	ds_read_b128 v[160:163], v149 offset:2048
	ds_read_b128 v[164:167], v149 offset:3072
	ds_read_b128 v[168:171], v150
	ds_read_b128 v[172:175], v150 offset:1024
	ds_read_b128 v[176:179], v150 offset:2048
	ds_read_b128 v[180:183], v150 offset:3072
	s_add_u32 s24, s22, 0xfff80080
	s_addc_u32 s25, s23, -1
	s_cmp_eq_u32 s50, 28
	s_cselect_b32 s27, s11, s25
	s_cselect_b32 s26, s46, s24
	s_cselect_b32 s25, s9, s49
	s_cselect_b32 s24, s47, s48
	v_lshl_add_u64 v[216:217], s[22:23], 0, v[140:141]
	s_add_i32 m0, s21, 0xc000
	ds_read_b128 v[184:187], v151
	ds_read_b128 v[188:191], v151 offset:1024
	ds_read_b128 v[192:195], v151 offset:2048
	ds_read_b128 v[196:199], v151 offset:3072
	ds_read_b128 v[200:203], v151 offset:4096
	ds_read_b128 v[204:207], v151 offset:5120
	ds_read_b128 v[208:211], v151 offset:6144
	ds_read_b128 v[212:215], v151 offset:7168
	global_load_lds_dwordx4 v[216:217], off
	v_lshl_add_u64 v[216:217], s[22:23], 0, v[142:143]
	s_add_i32 m0, s21, 0xe000
	s_nop 0
	global_load_lds_dwordx4 v[216:217], off
	s_waitcnt vmcnt(8)
	s_waitcnt lgkmcnt(0)
	s_barrier
; #define PG8_STAGE(bufoff, gbase, voff) do { _Pragma("unroll") for (int _i = 0; _i < 2; ++_i) \
;         __builtin_amdgcn_global_load_lds((const unsigned*)((const char*)(gbase) + (voff)[_i]), (PG8_LAS unsigned*)(lds + (bufoff) + ldsw + _i * 8192), 16, 0, 0); } while (0)
; #define PG8_LDA(dst, b, h) do { _Pragma("unroll") for (int m = 0; m < 4; ++m) _Pragma("unroll") for (int k = 0; k < 2; ++k) dst[m][k] = *(const PG8_LAS bf16x8*)(lds + PG8_SA(b, h) + aoff + m * 2048 + k * 1024); } while (0)
; #define PG8_MMA(ai, bj, At, Bt) do { __builtin_amdgcn_s_setprio(1); _Pragma("unroll") for (int m = 0; m < 4; ++m) _Pragma("unroll") for (int n = 0; n < 2; ++n) _Pragma("unroll") for (int k = 0; k < 2; ++k) \
;         acc[ai][bj][m][n] = __builtin_amdgcn_mfma_f32_16x16x32_bf16(Bt[n][k], At[m][k], acc[ai][bj][m][n], 0, 0, 0); __builtin_amdgcn_s_setprio(0); } while (0)
; #define PG8_WAIT_V(n) asm volatile("s_waitcnt vmcnt(" #n ")" ::: "memory")
; #define PG8_WAIT_L(n) asm volatile("s_waitcnt lgkmcnt(" #n ")" ::: "memory")
; #define PG8_BAR __builtin_amdgcn_s_barrier()
; #define PG8_SCHED __builtin_amdgcn_sched_barrier(0)
; template <class Epi, class Sched, bool ALIGN_EPI = false, bool SP2 = false>
; __device__ __forceinline__ void gemm_phase(PG8_LAS unsigned char* lds, const Gemm g, const Sched& S, const Epi& E) {
;     ...
;             PG8_WAIT_V(8); PG8_WAIT_L(0); PG8_BAR; PG8_MMA(0, 0, At, B0); PG8_MMA(0, 1, At, B1); PG8_BAR; PG8_SCHED;
;             PG8_LDA(At, 0, 1); PG8_STAGE(PG8_SB(0, 0), b2, voffB); PG8_STAGE(PG8_SB(0, 1), b2 + hstep, voffB); PG8_STAGE(PG8_SA(0, 0), a2, voffA);
;             PG8_WAIT_V(8); PG8_WAIT_L(0); PG8_BAR; PG8_MMA(1, 0, At, B0); PG8_MMA(1, 1, At, B1); PG8_BAR; PG8_SCHED;
	s_setprio 1
	s_waitcnt lgkmcnt(0)
	v_mfma_f32_16x16x32_bf16 v[126:129], v[152:155], v[184:187], v[126:129]
	v_mfma_f32_16x16x32_bf16 v[118:121], v[160:163], v[184:187], v[118:121]
	v_mfma_f32_16x16x32_bf16 v[110:113], v[152:155], v[192:195], v[110:113]
	v_mfma_f32_16x16x32_bf16 v[102:105], v[160:163], v[192:195], v[102:105]
	v_mfma_f32_16x16x32_bf16 v[94:97], v[152:155], v[200:203], v[94:97]
	v_mfma_f32_16x16x32_bf16 v[86:89], v[160:163], v[200:203], v[86:89]
	v_mfma_f32_16x16x32_bf16 v[78:81], v[152:155], v[208:211], v[78:81]
	v_mfma_f32_16x16x32_bf16 v[70:73], v[160:163], v[208:211], v[70:73]
	v_mfma_f32_16x16x32_bf16 v[126:129], v[156:159], v[188:191], v[126:129]
	v_mfma_f32_16x16x32_bf16 v[118:121], v[164:167], v[188:191], v[118:121]
	v_mfma_f32_16x16x32_bf16 v[110:113], v[156:159], v[196:199], v[110:113]
	v_mfma_f32_16x16x32_bf16 v[102:105], v[164:167], v[196:199], v[102:105]
	v_mfma_f32_16x16x32_bf16 v[94:97], v[156:159], v[204:207], v[94:97]
	v_mfma_f32_16x16x32_bf16 v[86:89], v[164:167], v[204:207], v[86:89]
	v_mfma_f32_16x16x32_bf16 v[78:81], v[156:159], v[212:215], v[78:81]
	v_mfma_f32_16x16x32_bf16 v[70:73], v[164:167], v[212:215], v[70:73]
	s_setprio 0
	s_setprio 1
	v_mfma_f32_16x16x32_bf16 v[122:125], v[168:171], v[184:187], v[122:125]
	v_mfma_f32_16x16x32_bf16 v[114:117], v[176:179], v[184:187], v[114:117]
	v_mfma_f32_16x16x32_bf16 v[106:109], v[168:171], v[192:195], v[106:109]
	v_mfma_f32_16x16x32_bf16 v[98:101], v[176:179], v[192:195], v[98:101]
	v_mfma_f32_16x16x32_bf16 v[90:93], v[168:171], v[200:203], v[90:93]
	v_mfma_f32_16x16x32_bf16 v[82:85], v[176:179], v[200:203], v[82:85]
	v_mfma_f32_16x16x32_bf16 v[74:77], v[168:171], v[208:211], v[74:77]
	v_mfma_f32_16x16x32_bf16 v[66:69], v[176:179], v[208:211], v[66:69]
	v_mfma_f32_16x16x32_bf16 v[122:125], v[172:175], v[188:191], v[122:125]
	v_mfma_f32_16x16x32_bf16 v[114:117], v[180:183], v[188:191], v[114:117]
	v_mfma_f32_16x16x32_bf16 v[106:109], v[172:175], v[196:199], v[106:109]
	v_mfma_f32_16x16x32_bf16 v[98:101], v[180:183], v[196:199], v[98:101]
	v_mfma_f32_16x16x32_bf16 v[90:93], v[172:175], v[204:207], v[90:93]
	v_mfma_f32_16x16x32_bf16 v[82:85], v[180:183], v[204:207], v[82:85]
	v_mfma_f32_16x16x32_bf16 v[74:77], v[172:175], v[212:215], v[74:77]
	v_mfma_f32_16x16x32_bf16 v[66:69], v[180:183], v[212:215], v[66:69]
	s_setprio 0
	s_barrier
	s_add_i32 s51, s40, s29
	v_lshl_add_u64 v[216:217], s[24:25], 0, v[136:137]
	s_mov_b32 m0, s51
	ds_read_b128 v[184:187], v151 offset:16384
	ds_read_b128 v[188:191], v151 offset:17408
	ds_read_b128 v[192:195], v151 offset:18432
	ds_read_b128 v[196:199], v151 offset:19456
	ds_read_b128 v[200:203], v151 offset:20480
	ds_read_b128 v[204:207], v151 offset:21504
	ds_read_b128 v[208:211], v151 offset:22528
	ds_read_b128 v[212:215], v151 offset:23552
	global_load_lds_dwordx4 v[216:217], off
	s_add_i32 m0, s51, 0x2000
	s_add_u32 s52, s24, 0x80000
	v_lshl_add_u64 v[220:221], s[24:25], 0, v[132:133]
	s_addc_u32 s53, s25, 0
	s_add_i32 s51, s41, s29
	global_load_lds_dwordx4 v[220:221], off
	v_lshl_add_u64 v[222:223], s[52:53], 0, v[136:137]
	s_mov_b32 m0, s51
	v_lshl_add_u64 v[224:225], s[26:27], 0, v[134:135]
	global_load_lds_dwordx4 v[222:223], off
	v_lshl_add_u64 v[222:223], s[52:53], 0, v[132:133]
	s_add_i32 m0, s51, 0x2000
	s_nop 0
	global_load_lds_dwordx4 v[222:223], off
	v_lshl_add_u64 v[222:223], s[26:27], 0, v[138:139]
	s_mov_b32 m0, s21
	s_nop 0
	global_load_lds_dwordx4 v[222:223], off
	s_mov_b32 m0, s33
	s_nop 0
	global_load_lds_dwordx4 v[224:225], off
	s_waitcnt vmcnt(8)
	s_waitcnt lgkmcnt(0)
	s_barrier
	s_setprio 1
	s_waitcnt lgkmcnt(0)
	v_mfma_f32_16x16x32_bf16 v[62:65], v[152:155], v[184:187], v[62:65]
	v_mfma_f32_16x16x32_bf16 v[54:57], v[160:163], v[184:187], v[54:57]
	v_mfma_f32_16x16x32_bf16 v[46:49], v[152:155], v[192:195], v[46:49]
	v_mfma_f32_16x16x32_bf16 v[38:41], v[160:163], v[192:195], v[38:41]
	v_mfma_f32_16x16x32_bf16 v[30:33], v[152:155], v[200:203], v[30:33]
	v_mfma_f32_16x16x32_bf16 v[22:25], v[160:163], v[200:203], v[22:25]
	v_mfma_f32_16x16x32_bf16 v[14:17], v[152:155], v[208:211], v[14:17]
	v_mfma_f32_16x16x32_bf16 v[6:9], v[160:163], v[208:211], v[6:9]
	v_mfma_f32_16x16x32_bf16 v[62:65], v[156:159], v[188:191], v[62:65]
	v_mfma_f32_16x16x32_bf16 v[54:57], v[164:167], v[188:191], v[54:57]
	v_mfma_f32_16x16x32_bf16 v[46:49], v[156:159], v[196:199], v[46:49]
	v_mfma_f32_16x16x32_bf16 v[38:41], v[164:167], v[196:199], v[38:41]
	v_mfma_f32_16x16x32_bf16 v[30:33], v[156:159], v[204:207], v[30:33]
	v_mfma_f32_16x16x32_bf16 v[22:25], v[164:167], v[204:207], v[22:25]
	v_mfma_f32_16x16x32_bf16 v[14:17], v[156:159], v[212:215], v[14:17]
	v_mfma_f32_16x16x32_bf16 v[6:9], v[164:167], v[212:215], v[6:9]
	s_setprio 0
	s_setprio 1
	v_mfma_f32_16x16x32_bf16 v[58:61], v[168:171], v[184:187], v[58:61]
	v_mfma_f32_16x16x32_bf16 v[50:53], v[176:179], v[184:187], v[50:53]
	v_mfma_f32_16x16x32_bf16 v[42:45], v[168:171], v[192:195], v[42:45]
	v_mfma_f32_16x16x32_bf16 v[34:37], v[176:179], v[192:195], v[34:37]
	v_mfma_f32_16x16x32_bf16 v[26:29], v[168:171], v[200:203], v[26:29]
	v_mfma_f32_16x16x32_bf16 v[18:21], v[176:179], v[200:203], v[18:21]
	v_mfma_f32_16x16x32_bf16 v[10:13], v[168:171], v[208:211], v[10:13]
	v_mfma_f32_16x16x32_bf16 v[2:5], v[176:179], v[208:211], v[2:5]
	v_mfma_f32_16x16x32_bf16 v[58:61], v[172:175], v[188:191], v[58:61]
	v_mfma_f32_16x16x32_bf16 v[50:53], v[180:183], v[188:191], v[50:53]
	v_mfma_f32_16x16x32_bf16 v[42:45], v[172:175], v[196:199], v[42:45]
	v_mfma_f32_16x16x32_bf16 v[34:37], v[180:183], v[196:199], v[34:37]
	v_mfma_f32_16x16x32_bf16 v[26:29], v[172:175], v[204:207], v[26:29]
	v_mfma_f32_16x16x32_bf16 v[18:21], v[180:183], v[204:207], v[18:21]
	v_mfma_f32_16x16x32_bf16 v[10:13], v[172:175], v[212:215], v[10:13]
	v_mfma_f32_16x16x32_bf16 v[2:5], v[180:183], v[212:215], v[2:5]
	s_setprio 0
	s_barrier
; #define PG8_STAGE(bufoff, gbase, voff) do { _Pragma("unroll") for (int _i = 0; _i < 2; ++_i) \
;         __builtin_amdgcn_global_load_lds((const unsigned*)((const char*)(gbase) + (voff)[_i]), (PG8_LAS unsigned*)(lds + (bufoff) + ldsw + _i * 8192), 16, 0, 0); } while (0)
; #define PG8_LDA(dst, b, h) do { _Pragma("unroll") for (int m = 0; m < 4; ++m) _Pragma("unroll") for (int k = 0; k < 2; ++k) dst[m][k] = *(const PG8_LAS bf16x8*)(lds + PG8_SA(b, h) + aoff + m * 2048 + k * 1024); } while (0)
; #define PG8_LDB(dst, b, h) do { _Pragma("unroll") for (int n = 0; n < 2; ++n) _Pragma("unroll") for (int k = 0; k < 2; ++k) dst[n][k] = *(const PG8_LAS bf16x8*)(lds + PG8_SB(b, h) + boff + n * 2048 + k * 1024); } while (0)
; #define PG8_MMA(ai, bj, At, Bt) do { __builtin_amdgcn_s_setprio(1); _Pragma("unroll") for (int m = 0; m < 4; ++m) _Pragma("unroll") for (int n = 0; n < 2; ++n) _Pragma("unroll") for (int k = 0; k < 2; ++k) \
;         acc[ai][bj][m][n] = __builtin_amdgcn_mfma_f32_16x16x32_bf16(Bt[n][k], At[m][k], acc[ai][bj][m][n], 0, 0, 0); __builtin_amdgcn_s_setprio(0); } while (0)
; #define PG8_WAIT_V(n) asm volatile("s_waitcnt vmcnt(" #n ")" ::: "memory")
; #define PG8_WAIT_L(n) asm volatile("s_waitcnt lgkmcnt(" #n ")" ::: "memory")
; #define PG8_BAR __builtin_amdgcn_s_barrier()
; #define PG8_SCHED __builtin_amdgcn_sched_barrier(0)
; template <class Epi, class Sched, bool ALIGN_EPI = false, bool SP2 = false>
; __device__ __forceinline__ void gemm_phase(PG8_LAS unsigned char* lds, const Gemm g, const Sched& S, const Epi& E) {
;     ...
;             PG8_LDB(B0, 1, 0); PG8_LDB(B1, 1, 1); PG8_SCHED; PG8_LDA(At, 1, 0); PG8_STAGE(PG8_SA(0, 1), a2 + hstep, voffA);
;             PG8_WAIT_V(8); PG8_WAIT_L(0); PG8_BAR; PG8_MMA(0, 0, At, B0); PG8_MMA(0, 1, At, B1); PG8_BAR; PG8_SCHED;
;             PG8_LDA(At, 1, 1); PG8_STAGE(PG8_SB(1, 0), b3, voffB); PG8_STAGE(PG8_SB(1, 1), b3 + hstep, voffB); PG8_STAGE(PG8_SA(1, 0), a3, voffA);
;             PG8_WAIT_V(8); PG8_WAIT_L(0); PG8_BAR; PG8_MMA(1, 0, At, B0); PG8_MMA(1, 1, At, B1); PG8_BAR; PG8_SCHED;
	s_add_i32 s51, 0, 0x18000
	s_add_i32 s52, 0, 0x1c000
	v_add_u32_e32 v164, s51, v131
	v_add_u32_e32 v180, s52, v131
	ds_read_b128 v[152:155], v164
	ds_read_b128 v[156:159], v164 offset:1024
	ds_read_b128 v[160:163], v164 offset:2048
	ds_read_b128 v[164:167], v164 offset:3072
	ds_read_b128 v[168:171], v180
	ds_read_b128 v[172:175], v180 offset:1024
	ds_read_b128 v[176:179], v180 offset:2048
	ds_read_b128 v[180:183], v180 offset:3072
	s_add_u32 s26, s26, 0x80000
	s_addc_u32 s27, s27, 0
	s_mov_b32 m0, s34
	v_lshl_add_u64 v[226:227], s[26:27], 0, v[138:139]
	ds_read_b128 v[184:187], v151 offset:32768
	ds_read_b128 v[188:191], v151 offset:33792
	ds_read_b128 v[192:195], v151 offset:34816
	ds_read_b128 v[196:199], v151 offset:35840
	ds_read_b128 v[200:203], v151 offset:36864
	ds_read_b128 v[204:207], v151 offset:37888
	ds_read_b128 v[208:211], v151 offset:38912
	ds_read_b128 v[212:215], v151 offset:39936
	global_load_lds_dwordx4 v[226:227], off
	v_lshl_add_u64 v[226:227], s[26:27], 0, v[134:135]
	s_mov_b32 m0, s35
	s_nop 0
	global_load_lds_dwordx4 v[226:227], off
	s_waitcnt vmcnt(8)
	s_waitcnt lgkmcnt(0)
	s_barrier
	s_setprio 1
	s_waitcnt lgkmcnt(0)
	v_mfma_f32_16x16x32_bf16 v[126:129], v[152:155], v[184:187], v[126:129]
	v_mfma_f32_16x16x32_bf16 v[118:121], v[160:163], v[184:187], v[118:121]
	v_mfma_f32_16x16x32_bf16 v[110:113], v[152:155], v[192:195], v[110:113]
	v_mfma_f32_16x16x32_bf16 v[102:105], v[160:163], v[192:195], v[102:105]
	v_mfma_f32_16x16x32_bf16 v[94:97], v[152:155], v[200:203], v[94:97]
	v_mfma_f32_16x16x32_bf16 v[86:89], v[160:163], v[200:203], v[86:89]
	v_mfma_f32_16x16x32_bf16 v[78:81], v[152:155], v[208:211], v[78:81]
	v_mfma_f32_16x16x32_bf16 v[70:73], v[160:163], v[208:211], v[70:73]
	v_mfma_f32_16x16x32_bf16 v[126:129], v[156:159], v[188:191], v[126:129]
	v_mfma_f32_16x16x32_bf16 v[118:121], v[164:167], v[188:191], v[118:121]
	v_mfma_f32_16x16x32_bf16 v[110:113], v[156:159], v[196:199], v[110:113]
	v_mfma_f32_16x16x32_bf16 v[102:105], v[164:167], v[196:199], v[102:105]
	v_mfma_f32_16x16x32_bf16 v[94:97], v[156:159], v[204:207], v[94:97]
	v_mfma_f32_16x16x32_bf16 v[86:89], v[164:167], v[204:207], v[86:89]
	v_mfma_f32_16x16x32_bf16 v[78:81], v[156:159], v[212:215], v[78:81]
	v_mfma_f32_16x16x32_bf16 v[70:73], v[164:167], v[212:215], v[70:73]
	s_setprio 0
	s_setprio 1
	v_mfma_f32_16x16x32_bf16 v[122:125], v[168:171], v[184:187], v[122:125]
	v_mfma_f32_16x16x32_bf16 v[114:117], v[176:179], v[184:187], v[114:117]
	v_mfma_f32_16x16x32_bf16 v[106:109], v[168:171], v[192:195], v[106:109]
	v_mfma_f32_16x16x32_bf16 v[98:101], v[176:179], v[192:195], v[98:101]
	v_mfma_f32_16x16x32_bf16 v[90:93], v[168:171], v[200:203], v[90:93]
	v_mfma_f32_16x16x32_bf16 v[82:85], v[176:179], v[200:203], v[82:85]
	v_mfma_f32_16x16x32_bf16 v[74:77], v[168:171], v[208:211], v[74:77]
	v_mfma_f32_16x16x32_bf16 v[66:69], v[176:179], v[208:211], v[66:69]
	v_mfma_f32_16x16x32_bf16 v[122:125], v[172:175], v[188:191], v[122:125]
	v_mfma_f32_16x16x32_bf16 v[114:117], v[180:183], v[188:191], v[114:117]
	v_mfma_f32_16x16x32_bf16 v[106:109], v[172:175], v[196:199], v[106:109]
	v_mfma_f32_16x16x32_bf16 v[98:101], v[180:183], v[196:199], v[98:101]
	v_mfma_f32_16x16x32_bf16 v[90:93], v[172:175], v[204:207], v[90:93]
	v_mfma_f32_16x16x32_bf16 v[82:85], v[180:183], v[204:207], v[82:85]
	v_mfma_f32_16x16x32_bf16 v[74:77], v[172:175], v[212:215], v[74:77]
	v_mfma_f32_16x16x32_bf16 v[66:69], v[180:183], v[212:215], v[66:69]
	s_setprio 0
	s_barrier
	s_add_i32 s26, s51, s29
	v_lshl_add_u64 v[216:217], v[216:217], 0, s[4:5]
	s_mov_b32 m0, s26
	ds_read_b128 v[184:187], v151 offset:49152
	ds_read_b128 v[188:191], v151 offset:50176
	ds_read_b128 v[192:195], v151 offset:51200
	ds_read_b128 v[196:199], v151 offset:52224
	ds_read_b128 v[200:203], v151 offset:53248
	ds_read_b128 v[204:207], v151 offset:54272
	ds_read_b128 v[208:211], v151 offset:55296
	ds_read_b128 v[212:215], v151 offset:56320
	global_load_lds_dwordx4 v[216:217], off
	s_add_i32 m0, s26, 0x2000
	s_add_u32 s24, s24, 0x80080
	v_lshl_add_u64 v[216:217], v[220:221], 0, s[4:5]
	s_addc_u32 s25, s25, 0
	s_add_i32 s26, s52, s29
	global_load_lds_dwordx4 v[216:217], off
	v_lshl_add_u64 v[216:217], s[24:25], 0, v[136:137]
	s_mov_b32 m0, s26
	s_nop 0
	global_load_lds_dwordx4 v[216:217], off
	v_lshl_add_u64 v[216:217], s[24:25], 0, v[132:133]
	s_add_i32 m0, s26, 0x2000
	s_nop 0
	global_load_lds_dwordx4 v[216:217], off
	v_lshl_add_u64 v[216:217], v[222:223], 0, s[4:5]
	s_mov_b32 m0, s37
	s_nop 0
	global_load_lds_dwordx4 v[216:217], off
	v_lshl_add_u64 v[216:217], v[224:225], 0, s[4:5]
	s_mov_b32 m0, s38
	s_nop 0
	global_load_lds_dwordx4 v[216:217], off
	s_waitcnt vmcnt(8)
	s_waitcnt lgkmcnt(0)
	s_barrier
; #define PG8_STAGE(bufoff, gbase, voff) do { _Pragma("unroll") for (int _i = 0; _i < 2; ++_i) \
;         __builtin_amdgcn_global_load_lds((const unsigned*)((const char*)(gbase) + (voff)[_i]), (PG8_LAS unsigned*)(lds + (bufoff) + ldsw + _i * 8192), 16, 0, 0); } while (0)
; #define PG8_LDA(dst, b, h) do { _Pragma("unroll") for (int m = 0; m < 4; ++m) _Pragma("unroll") for (int k = 0; k < 2; ++k) dst[m][k] = *(const PG8_LAS bf16x8*)(lds + PG8_SA(b, h) + aoff + m * 2048 + k * 1024); } while (0)
; #define PG8_LDB(dst, b, h) do { _Pragma("unroll") for (int n = 0; n < 2; ++n) _Pragma("unroll") for (int k = 0; k < 2; ++k) dst[n][k] = *(const PG8_LAS bf16x8*)(lds + PG8_SB(b, h) + boff + n * 2048 + k * 1024); } while (0)
; #define PG8_MMA(ai, bj, At, Bt) do { __builtin_amdgcn_s_setprio(1); _Pragma("unroll") for (int m = 0; m < 4; ++m) _Pragma("unroll") for (int n = 0; n < 2; ++n) _Pragma("unroll") for (int k = 0; k < 2; ++k) \
;         acc[ai][bj][m][n] = __builtin_amdgcn_mfma_f32_16x16x32_bf16(Bt[n][k], At[m][k], acc[ai][bj][m][n], 0, 0, 0); __builtin_amdgcn_s_setprio(0); } while (0)
; #define PG8_WAIT_V(n) asm volatile("s_waitcnt vmcnt(" #n ")" ::: "memory")
; template <class Epi, class Sched, bool ALIGN_EPI = false, bool SP2 = false>
; __device__ __forceinline__ void gemm_phase(PG8_LAS unsigned char* lds, const Gemm g, const Sched& S, const Epi& E) {
;     ...
;             PG8_LDB(B0, 0, 0); PG8_LDB(B1, 0, 1); PG8_SCHED; PG8_LDA(At, 0, 0); PG8_STAGE(PG8_SA(1, 1), a1 + hstep, voffA);
;             PG8_WAIT_V(8); PG8_WAIT_L(0); PG8_BAR; PG8_MMA(0, 0, At, B0); PG8_MMA(0, 1, At, B1); PG8_BAR; PG8_SCHED;
;             PG8_LDA(At, 0, 1); PG8_STAGE(PG8_SB(0, 0), b2, voffB); PG8_STAGE(PG8_SB(0, 1), b2 + hstep, voffB); PG8_STAGE(PG8_SA(0, 0), a2, voffA);
;             PG8_WAIT_V(8); PG8_WAIT_L(0); PG8_BAR; PG8_MMA(1, 0, At, B0); PG8_MMA(1, 1, At, B1); PG8_BAR; PG8_SCHED;
;             PG8_LDB(B0, 1, 0); PG8_LDB(B1, 1, 1); PG8_SCHED; PG8_LDA(At, 1, 0); PG8_STAGE(PG8_SA(0, 1), a2 + hstep, voffA);
;             PG8_WAIT_V(8); PG8_WAIT_L(0); PG8_BAR; PG8_MMA(0, 0, At, B0); PG8_MMA(0, 1, At, B1); PG8_BAR; PG8_SCHED;
;             PG8_LDA(At, 1, 1); PG8_STAGE(PG8_SB(1, 0), b3, voffB); PG8_STAGE(PG8_SB(1, 1), b3 + hstep, voffB); PG8_STAGE(PG8_SA(1, 0), a3, voffA);
;             PG8_WAIT_V(8); PG8_WAIT_L(0); PG8_BAR; PG8_MMA(1, 0, At, B0); PG8_MMA(1, 1, At, B1); PG8_BAR; PG8_SCHED;
	s_setprio 1
	s_waitcnt lgkmcnt(0)
	v_mfma_f32_16x16x32_bf16 v[62:65], v[152:155], v[184:187], v[62:65]
	v_mfma_f32_16x16x32_bf16 v[54:57], v[160:163], v[184:187], v[54:57]
	v_mfma_f32_16x16x32_bf16 v[46:49], v[152:155], v[192:195], v[46:49]
	v_mfma_f32_16x16x32_bf16 v[38:41], v[160:163], v[192:195], v[38:41]
	v_mfma_f32_16x16x32_bf16 v[30:33], v[152:155], v[200:203], v[30:33]
	v_mfma_f32_16x16x32_bf16 v[22:25], v[160:163], v[200:203], v[22:25]
	v_mfma_f32_16x16x32_bf16 v[14:17], v[152:155], v[208:211], v[14:17]
	v_mfma_f32_16x16x32_bf16 v[6:9], v[160:163], v[208:211], v[6:9]
	v_mfma_f32_16x16x32_bf16 v[62:65], v[156:159], v[188:191], v[62:65]
	v_mfma_f32_16x16x32_bf16 v[54:57], v[164:167], v[188:191], v[54:57]
	v_mfma_f32_16x16x32_bf16 v[46:49], v[156:159], v[196:199], v[46:49]
	v_mfma_f32_16x16x32_bf16 v[38:41], v[164:167], v[196:199], v[38:41]
	v_mfma_f32_16x16x32_bf16 v[30:33], v[156:159], v[204:207], v[30:33]
	v_mfma_f32_16x16x32_bf16 v[22:25], v[164:167], v[204:207], v[22:25]
	v_mfma_f32_16x16x32_bf16 v[14:17], v[156:159], v[212:215], v[14:17]
	v_mfma_f32_16x16x32_bf16 v[6:9], v[164:167], v[212:215], v[6:9]
	s_setprio 0
	s_setprio 1
	v_mfma_f32_16x16x32_bf16 v[58:61], v[168:171], v[184:187], v[58:61]
	v_mfma_f32_16x16x32_bf16 v[50:53], v[176:179], v[184:187], v[50:53]
	v_mfma_f32_16x16x32_bf16 v[42:45], v[168:171], v[192:195], v[42:45]
	v_mfma_f32_16x16x32_bf16 v[34:37], v[176:179], v[192:195], v[34:37]
	v_mfma_f32_16x16x32_bf16 v[26:29], v[168:171], v[200:203], v[26:29]
	v_mfma_f32_16x16x32_bf16 v[18:21], v[176:179], v[200:203], v[18:21]
	v_mfma_f32_16x16x32_bf16 v[10:13], v[168:171], v[208:211], v[10:13]
	v_mfma_f32_16x16x32_bf16 v[2:5], v[176:179], v[208:211], v[2:5]
	v_mfma_f32_16x16x32_bf16 v[58:61], v[172:175], v[188:191], v[58:61]
	v_mfma_f32_16x16x32_bf16 v[50:53], v[180:183], v[188:191], v[50:53]
	v_mfma_f32_16x16x32_bf16 v[42:45], v[172:175], v[196:199], v[42:45]
	v_mfma_f32_16x16x32_bf16 v[34:37], v[180:183], v[196:199], v[34:37]
	v_mfma_f32_16x16x32_bf16 v[26:29], v[172:175], v[204:207], v[26:29]
	v_mfma_f32_16x16x32_bf16 v[18:21], v[180:183], v[204:207], v[18:21]
	v_mfma_f32_16x16x32_bf16 v[10:13], v[172:175], v[212:215], v[10:13]
	v_mfma_f32_16x16x32_bf16 v[2:5], v[180:183], v[212:215], v[2:5]
	s_setprio 0
	s_barrier
	s_add_i32 s50, s50, 2
	s_add_u32 s22, s22, 0x100
	s_addc_u32 s23, s23, 0
	s_add_u32 s48, s48, 0x100
	s_addc_u32 s49, s49, 0
	s_cmp_gt_u32 s50, 29
	s_cbranch_scc0 .LBB0_1971
	s_branch .Lpeel_after_2
.Lpeel_2:
	ds_read_b128 v[152:155], v149
	ds_read_b128 v[156:159], v149 offset:1024
	ds_read_b128 v[160:163], v149 offset:2048
	ds_read_b128 v[164:167], v149 offset:3072
	ds_read_b128 v[168:171], v150
	ds_read_b128 v[172:175], v150 offset:1024
	ds_read_b128 v[176:179], v150 offset:2048
	ds_read_b128 v[180:183], v150 offset:3072
	s_add_u32 s24, s22, 0xfff80080
	s_addc_u32 s25, s23, -1
	s_cmp_eq_u32 s50, 28
	s_cselect_b32 s27, s11, s25
	s_cselect_b32 s26, s46, s24
	s_cselect_b32 s25, s9, s49
	s_cselect_b32 s24, s47, s48
	v_lshl_add_u64 v[216:217], s[22:23], 0, v[140:141]
	s_add_i32 m0, s21, 0xc000
	ds_read_b128 v[184:187], v151
	ds_read_b128 v[188:191], v151 offset:1024
	ds_read_b128 v[192:195], v151 offset:2048
	ds_read_b128 v[196:199], v151 offset:3072
	ds_read_b128 v[200:203], v151 offset:4096
	ds_read_b128 v[204:207], v151 offset:5120
	ds_read_b128 v[208:211], v151 offset:6144
	ds_read_b128 v[212:215], v151 offset:7168
	global_load_lds_dwordx4 v[216:217], off
	v_lshl_add_u64 v[216:217], s[22:23], 0, v[142:143]
	s_add_i32 m0, s21, 0xe000
	s_nop 0
	global_load_lds_dwordx4 v[216:217], off
	s_waitcnt vmcnt(16)
	s_waitcnt lgkmcnt(0)
	s_barrier
	s_setprio 1
	s_waitcnt lgkmcnt(0)
	v_mfma_f32_16x16x32_bf16 v[126:129], v[152:155], v[184:187], 0
	v_mfma_f32_16x16x32_bf16 v[118:121], v[160:163], v[184:187], 0
	v_mfma_f32_16x16x32_bf16 v[110:113], v[152:155], v[192:195], 0
	v_mfma_f32_16x16x32_bf16 v[102:105], v[160:163], v[192:195], 0
	v_mfma_f32_16x16x32_bf16 v[94:97], v[152:155], v[200:203], 0
	v_mfma_f32_16x16x32_bf16 v[86:89], v[160:163], v[200:203], 0
	v_mfma_f32_16x16x32_bf16 v[78:81], v[152:155], v[208:211], 0
	v_mfma_f32_16x16x32_bf16 v[70:73], v[160:163], v[208:211], 0
	v_mfma_f32_16x16x32_bf16 v[126:129], v[156:159], v[188:191], v[126:129]
	v_mfma_f32_16x16x32_bf16 v[118:121], v[164:167], v[188:191], v[118:121]
	v_mfma_f32_16x16x32_bf16 v[110:113], v[156:159], v[196:199], v[110:113]
	v_mfma_f32_16x16x32_bf16 v[102:105], v[164:167], v[196:199], v[102:105]
	v_mfma_f32_16x16x32_bf16 v[94:97], v[156:159], v[204:207], v[94:97]
	v_mfma_f32_16x16x32_bf16 v[86:89], v[164:167], v[204:207], v[86:89]
	v_mfma_f32_16x16x32_bf16 v[78:81], v[156:159], v[212:215], v[78:81]
	v_mfma_f32_16x16x32_bf16 v[70:73], v[164:167], v[212:215], v[70:73]
	s_setprio 0
	s_setprio 1
	v_mfma_f32_16x16x32_bf16 v[122:125], v[168:171], v[184:187], 0
	v_mfma_f32_16x16x32_bf16 v[114:117], v[176:179], v[184:187], 0
	v_mfma_f32_16x16x32_bf16 v[106:109], v[168:171], v[192:195], 0
	v_mfma_f32_16x16x32_bf16 v[98:101], v[176:179], v[192:195], 0
	v_mfma_f32_16x16x32_bf16 v[90:93], v[168:171], v[200:203], 0
	v_mfma_f32_16x16x32_bf16 v[82:85], v[176:179], v[200:203], 0
	v_mfma_f32_16x16x32_bf16 v[74:77], v[168:171], v[208:211], 0
	v_mfma_f32_16x16x32_bf16 v[66:69], v[176:179], v[208:211], 0
	v_mfma_f32_16x16x32_bf16 v[122:125], v[172:175], v[188:191], v[122:125]
	v_mfma_f32_16x16x32_bf16 v[114:117], v[180:183], v[188:191], v[114:117]
	v_mfma_f32_16x16x32_bf16 v[106:109], v[172:175], v[196:199], v[106:109]
	v_mfma_f32_16x16x32_bf16 v[98:101], v[180:183], v[196:199], v[98:101]
	v_mfma_f32_16x16x32_bf16 v[90:93], v[172:175], v[204:207], v[90:93]
	v_mfma_f32_16x16x32_bf16 v[82:85], v[180:183], v[204:207], v[82:85]
	v_mfma_f32_16x16x32_bf16 v[74:77], v[172:175], v[212:215], v[74:77]
	v_mfma_f32_16x16x32_bf16 v[66:69], v[180:183], v[212:215], v[66:69]
	s_setprio 0
	s_barrier
; #define PG8_STAGE(bufoff, gbase, voff) do { _Pragma("unroll") for (int _i = 0; _i < 2; ++_i) \
;         __builtin_amdgcn_global_load_lds((const unsigned*)((const char*)(gbase) + (voff)[_i]), (PG8_LAS unsigned*)(lds + (bufoff) + ldsw + _i * 8192), 16, 0, 0); } while (0)
; #define PG8_LDA(dst, b, h) do { _Pragma("unroll") for (int m = 0; m < 4; ++m) _Pragma("unroll") for (int k = 0; k < 2; ++k) dst[m][k] = *(const PG8_LAS bf16x8*)(lds + PG8_SA(b, h) + aoff + m * 2048 + k * 1024); } while (0)
; #define PG8_LDB(dst, b, h) do { _Pragma("unroll") for (int n = 0; n < 2; ++n) _Pragma("unroll") for (int k = 0; k < 2; ++k) dst[n][k] = *(const PG8_LAS bf16x8*)(lds + PG8_SB(b, h) + boff + n * 2048 + k * 1024); } while (0)
; #define PG8_MMA(ai, bj, At, Bt) do { __builtin_amdgcn_s_setprio(1); _Pragma("unroll") for (int m = 0; m < 4; ++m) _Pragma("unroll") for (int n = 0; n < 2; ++n) _Pragma("unroll") for (int k = 0; k < 2; ++k) \
;         acc[ai][bj][m][n] = __builtin_amdgcn_mfma_f32_16x16x32_bf16(Bt[n][k], At[m][k], acc[ai][bj][m][n], 0, 0, 0); __builtin_amdgcn_s_setprio(0); } while (0)
; #define PG8_WAIT_V(n) asm volatile("s_waitcnt vmcnt(" #n ")" ::: "memory")
; #define PG8_WAIT_L(n) asm volatile("s_waitcnt lgkmcnt(" #n ")" ::: "memory")
; #define PG8_BAR __builtin_amdgcn_s_barrier()
; #define PG8_SCHED __builtin_amdgcn_sched_barrier(0)
; template <class Epi, class Sched, bool ALIGN_EPI = false, bool SP2 = false>
; __device__ __forceinline__ void gemm_phase(PG8_LAS unsigned char* lds, const Gemm g, const Sched& S, const Epi& E) {
;     ...
;             PG8_LDA(At, 0, 1); PG8_STAGE(PG8_SB(0, 0), b2, voffB); PG8_STAGE(PG8_SB(0, 1), b2 + hstep, voffB); PG8_STAGE(PG8_SA(0, 0), a2, voffA);
;             PG8_WAIT_V(8); PG8_WAIT_L(0); PG8_BAR; PG8_MMA(1, 0, At, B0); PG8_MMA(1, 1, At, B1); PG8_BAR; PG8_SCHED;
;             PG8_LDB(B0, 1, 0); PG8_LDB(B1, 1, 1); PG8_SCHED; PG8_LDA(At, 1, 0); PG8_STAGE(PG8_SA(0, 1), a2 + hstep, voffA);
;             PG8_WAIT_V(8); PG8_WAIT_L(0); PG8_BAR; PG8_MMA(0, 0, At, B0); PG8_MMA(0, 1, At, B1); PG8_BAR; PG8_SCHED;
	s_add_i32 s51, s40, s29
	v_lshl_add_u64 v[216:217], s[24:25], 0, v[136:137]
	s_mov_b32 m0, s51
	ds_read_b128 v[184:187], v151 offset:16384
	ds_read_b128 v[188:191], v151 offset:17408
	ds_read_b128 v[192:195], v151 offset:18432
	ds_read_b128 v[196:199], v151 offset:19456
	ds_read_b128 v[200:203], v151 offset:20480
	ds_read_b128 v[204:207], v151 offset:21504
	ds_read_b128 v[208:211], v151 offset:22528
	ds_read_b128 v[212:215], v151 offset:23552
	global_load_lds_dwordx4 v[216:217], off
	s_add_i32 m0, s51, 0x2000
	s_add_u32 s52, s24, 0x80000
	v_lshl_add_u64 v[220:221], s[24:25], 0, v[132:133]
	s_addc_u32 s53, s25, 0
	s_add_i32 s51, s41, s29
	global_load_lds_dwordx4 v[220:221], off
	v_lshl_add_u64 v[222:223], s[52:53], 0, v[136:137]
	s_mov_b32 m0, s51
	v_lshl_add_u64 v[224:225], s[26:27], 0, v[134:135]
	global_load_lds_dwordx4 v[222:223], off
	v_lshl_add_u64 v[222:223], s[52:53], 0, v[132:133]
	s_add_i32 m0, s51, 0x2000
	s_nop 0
	global_load_lds_dwordx4 v[222:223], off
	v_lshl_add_u64 v[222:223], s[26:27], 0, v[138:139]
	s_mov_b32 m0, s21
	s_nop 0
	global_load_lds_dwordx4 v[222:223], off
	s_mov_b32 m0, s33
	s_nop 0
	global_load_lds_dwordx4 v[224:225], off
	s_waitcnt vmcnt(16)
	s_waitcnt lgkmcnt(0)
	s_barrier
	s_setprio 1
	s_waitcnt lgkmcnt(0)
	v_mfma_f32_16x16x32_bf16 v[62:65], v[152:155], v[184:187], 0
	v_mfma_f32_16x16x32_bf16 v[54:57], v[160:163], v[184:187], 0
	v_mfma_f32_16x16x32_bf16 v[46:49], v[152:155], v[192:195], 0
	v_mfma_f32_16x16x32_bf16 v[38:41], v[160:163], v[192:195], 0
	v_mfma_f32_16x16x32_bf16 v[30:33], v[152:155], v[200:203], 0
	v_mfma_f32_16x16x32_bf16 v[22:25], v[160:163], v[200:203], 0
	v_mfma_f32_16x16x32_bf16 v[14:17], v[152:155], v[208:211], 0
	v_mfma_f32_16x16x32_bf16 v[6:9], v[160:163], v[208:211], 0
	v_mfma_f32_16x16x32_bf16 v[62:65], v[156:159], v[188:191], v[62:65]
	v_mfma_f32_16x16x32_bf16 v[54:57], v[164:167], v[188:191], v[54:57]
	v_mfma_f32_16x16x32_bf16 v[46:49], v[156:159], v[196:199], v[46:49]
	v_mfma_f32_16x16x32_bf16 v[38:41], v[164:167], v[196:199], v[38:41]
	v_mfma_f32_16x16x32_bf16 v[30:33], v[156:159], v[204:207], v[30:33]
	v_mfma_f32_16x16x32_bf16 v[22:25], v[164:167], v[204:207], v[22:25]
	v_mfma_f32_16x16x32_bf16 v[14:17], v[156:159], v[212:215], v[14:17]
	v_mfma_f32_16x16x32_bf16 v[6:9], v[164:167], v[212:215], v[6:9]
	s_setprio 0
	s_setprio 1
	v_mfma_f32_16x16x32_bf16 v[58:61], v[168:171], v[184:187], 0
	v_mfma_f32_16x16x32_bf16 v[50:53], v[176:179], v[184:187], 0
	v_mfma_f32_16x16x32_bf16 v[42:45], v[168:171], v[192:195], 0
	v_mfma_f32_16x16x32_bf16 v[34:37], v[176:179], v[192:195], 0
	v_mfma_f32_16x16x32_bf16 v[26:29], v[168:171], v[200:203], 0
	v_mfma_f32_16x16x32_bf16 v[18:21], v[176:179], v[200:203], 0
	v_mfma_f32_16x16x32_bf16 v[10:13], v[168:171], v[208:211], 0
	v_mfma_f32_16x16x32_bf16 v[2:5], v[176:179], v[208:211], 0
	v_mfma_f32_16x16x32_bf16 v[58:61], v[172:175], v[188:191], v[58:61]
	v_mfma_f32_16x16x32_bf16 v[50:53], v[180:183], v[188:191], v[50:53]
	v_mfma_f32_16x16x32_bf16 v[42:45], v[172:175], v[196:199], v[42:45]
	v_mfma_f32_16x16x32_bf16 v[34:37], v[180:183], v[196:199], v[34:37]
	v_mfma_f32_16x16x32_bf16 v[26:29], v[172:175], v[204:207], v[26:29]
	v_mfma_f32_16x16x32_bf16 v[18:21], v[180:183], v[204:207], v[18:21]
	v_mfma_f32_16x16x32_bf16 v[10:13], v[172:175], v[212:215], v[10:13]
	v_mfma_f32_16x16x32_bf16 v[2:5], v[180:183], v[212:215], v[2:5]
	s_setprio 0
	s_barrier
	s_add_i32 s51, 0, 0x18000
	s_add_i32 s52, 0, 0x1c000
	v_add_u32_e32 v164, s51, v131
	v_add_u32_e32 v180, s52, v131
	ds_read_b128 v[152:155], v164
	ds_read_b128 v[156:159], v164 offset:1024
	ds_read_b128 v[160:163], v164 offset:2048
	ds_read_b128 v[164:167], v164 offset:3072
	ds_read_b128 v[168:171], v180
	ds_read_b128 v[172:175], v180 offset:1024
	ds_read_b128 v[176:179], v180 offset:2048
	ds_read_b128 v[180:183], v180 offset:3072
	s_add_u32 s26, s26, 0x80000
	s_addc_u32 s27, s27, 0
	s_mov_b32 m0, s34
	v_lshl_add_u64 v[226:227], s[26:27], 0, v[138:139]
	ds_read_b128 v[184:187], v151 offset:32768
	ds_read_b128 v[188:191], v151 offset:33792
	ds_read_b128 v[192:195], v151 offset:34816
	ds_read_b128 v[196:199], v151 offset:35840
	ds_read_b128 v[200:203], v151 offset:36864
	ds_read_b128 v[204:207], v151 offset:37888
	ds_read_b128 v[208:211], v151 offset:38912
	ds_read_b128 v[212:215], v151 offset:39936
	global_load_lds_dwordx4 v[226:227], off
	v_lshl_add_u64 v[226:227], s[26:27], 0, v[134:135]
	s_mov_b32 m0, s35
	s_nop 0
	global_load_lds_dwordx4 v[226:227], off
	s_waitcnt vmcnt(8)
	s_waitcnt lgkmcnt(0)
	s_barrier
; #define PG8_STAGE(bufoff, gbase, voff) do { _Pragma("unroll") for (int _i = 0; _i < 2; ++_i) \
;         __builtin_amdgcn_global_load_lds((const unsigned*)((const char*)(gbase) + (voff)[_i]), (PG8_LAS unsigned*)(lds + (bufoff) + ldsw + _i * 8192), 16, 0, 0); } while (0)
; #define PG8_LDA(dst, b, h) do { _Pragma("unroll") for (int m = 0; m < 4; ++m) _Pragma("unroll") for (int k = 0; k < 2; ++k) dst[m][k] = *(const PG8_LAS bf16x8*)(lds + PG8_SA(b, h) + aoff + m * 2048 + k * 1024); } while (0)
; #define PG8_MMA(ai, bj, At, Bt) do { __builtin_amdgcn_s_setprio(1); _Pragma("unroll") for (int m = 0; m < 4; ++m) _Pragma("unroll") for (int n = 0; n < 2; ++n) _Pragma("unroll") for (int k = 0; k < 2; ++k) \
;         acc[ai][bj][m][n] = __builtin_amdgcn_mfma_f32_16x16x32_bf16(Bt[n][k], At[m][k], acc[ai][bj][m][n], 0, 0, 0); __builtin_amdgcn_s_setprio(0); } while (0)
; #define PG8_WAIT_V(n) asm volatile("s_waitcnt vmcnt(" #n ")" ::: "memory")
; #define PG8_WAIT_L(n) asm volatile("s_waitcnt lgkmcnt(" #n ")" ::: "memory")
; #define PG8_BAR __builtin_amdgcn_s_barrier()
; #define PG8_SCHED __builtin_amdgcn_sched_barrier(0)
; template <class Epi, class Sched, bool ALIGN_EPI = false, bool SP2 = false>
; __device__ __forceinline__ void gemm_phase(PG8_LAS unsigned char* lds, const Gemm g, const Sched& S, const Epi& E) {
;     ...
;             PG8_WAIT_V(8); PG8_WAIT_L(0); PG8_BAR; PG8_MMA(0, 0, At, B0); PG8_MMA(0, 1, At, B1); PG8_BAR; PG8_SCHED;
;             PG8_LDA(At, 1, 1); PG8_STAGE(PG8_SB(1, 0), b3, voffB); PG8_STAGE(PG8_SB(1, 1), b3 + hstep, voffB); PG8_STAGE(PG8_SA(1, 0), a3, voffA);
;             PG8_WAIT_V(8); PG8_WAIT_L(0); PG8_BAR; PG8_MMA(1, 0, At, B0); PG8_MMA(1, 1, At, B1); PG8_BAR; PG8_SCHED;
	s_setprio 1
	s_waitcnt lgkmcnt(0)
	v_mfma_f32_16x16x32_bf16 v[126:129], v[152:155], v[184:187], v[126:129]
	v_mfma_f32_16x16x32_bf16 v[118:121], v[160:163], v[184:187], v[118:121]
	v_mfma_f32_16x16x32_bf16 v[110:113], v[152:155], v[192:195], v[110:113]
	v_mfma_f32_16x16x32_bf16 v[102:105], v[160:163], v[192:195], v[102:105]
	v_mfma_f32_16x16x32_bf16 v[94:97], v[152:155], v[200:203], v[94:97]
	v_mfma_f32_16x16x32_bf16 v[86:89], v[160:163], v[200:203], v[86:89]
	v_mfma_f32_16x16x32_bf16 v[78:81], v[152:155], v[208:211], v[78:81]
	v_mfma_f32_16x16x32_bf16 v[70:73], v[160:163], v[208:211], v[70:73]
	v_mfma_f32_16x16x32_bf16 v[126:129], v[156:159], v[188:191], v[126:129]
	v_mfma_f32_16x16x32_bf16 v[118:121], v[164:167], v[188:191], v[118:121]
	v_mfma_f32_16x16x32_bf16 v[110:113], v[156:159], v[196:199], v[110:113]
	v_mfma_f32_16x16x32_bf16 v[102:105], v[164:167], v[196:199], v[102:105]
	v_mfma_f32_16x16x32_bf16 v[94:97], v[156:159], v[204:207], v[94:97]
	v_mfma_f32_16x16x32_bf16 v[86:89], v[164:167], v[204:207], v[86:89]
	v_mfma_f32_16x16x32_bf16 v[78:81], v[156:159], v[212:215], v[78:81]
	v_mfma_f32_16x16x32_bf16 v[70:73], v[164:167], v[212:215], v[70:73]
	s_setprio 0
	s_setprio 1
	v_mfma_f32_16x16x32_bf16 v[122:125], v[168:171], v[184:187], v[122:125]
	v_mfma_f32_16x16x32_bf16 v[114:117], v[176:179], v[184:187], v[114:117]
	v_mfma_f32_16x16x32_bf16 v[106:109], v[168:171], v[192:195], v[106:109]
	v_mfma_f32_16x16x32_bf16 v[98:101], v[176:179], v[192:195], v[98:101]
	v_mfma_f32_16x16x32_bf16 v[90:93], v[168:171], v[200:203], v[90:93]
	v_mfma_f32_16x16x32_bf16 v[82:85], v[176:179], v[200:203], v[82:85]
	v_mfma_f32_16x16x32_bf16 v[74:77], v[168:171], v[208:211], v[74:77]
	v_mfma_f32_16x16x32_bf16 v[66:69], v[176:179], v[208:211], v[66:69]
	v_mfma_f32_16x16x32_bf16 v[122:125], v[172:175], v[188:191], v[122:125]
	v_mfma_f32_16x16x32_bf16 v[114:117], v[180:183], v[188:191], v[114:117]
	v_mfma_f32_16x16x32_bf16 v[106:109], v[172:175], v[196:199], v[106:109]
	v_mfma_f32_16x16x32_bf16 v[98:101], v[180:183], v[196:199], v[98:101]
	v_mfma_f32_16x16x32_bf16 v[90:93], v[172:175], v[204:207], v[90:93]
	v_mfma_f32_16x16x32_bf16 v[82:85], v[180:183], v[204:207], v[82:85]
	v_mfma_f32_16x16x32_bf16 v[74:77], v[172:175], v[212:215], v[74:77]
	v_mfma_f32_16x16x32_bf16 v[66:69], v[180:183], v[212:215], v[66:69]
	s_setprio 0
	s_barrier
	s_add_i32 s26, s51, s29
	v_lshl_add_u64 v[216:217], v[216:217], 0, s[4:5]
	s_mov_b32 m0, s26
	ds_read_b128 v[184:187], v151 offset:49152
	ds_read_b128 v[188:191], v151 offset:50176
	ds_read_b128 v[192:195], v151 offset:51200
	ds_read_b128 v[196:199], v151 offset:52224
	ds_read_b128 v[200:203], v151 offset:53248
	ds_read_b128 v[204:207], v151 offset:54272
	ds_read_b128 v[208:211], v151 offset:55296
	ds_read_b128 v[212:215], v151 offset:56320
	global_load_lds_dwordx4 v[216:217], off
	s_add_i32 m0, s26, 0x2000
	s_add_u32 s24, s24, 0x80080
	v_lshl_add_u64 v[216:217], v[220:221], 0, s[4:5]
	s_addc_u32 s25, s25, 0
	s_add_i32 s26, s52, s29
	global_load_lds_dwordx4 v[216:217], off
	v_lshl_add_u64 v[216:217], s[24:25], 0, v[136:137]
	s_mov_b32 m0, s26
	s_nop 0
	global_load_lds_dwordx4 v[216:217], off
	v_lshl_add_u64 v[216:217], s[24:25], 0, v[132:133]
	s_add_i32 m0, s26, 0x2000
	s_nop 0
	global_load_lds_dwordx4 v[216:217], off
	v_lshl_add_u64 v[216:217], v[222:223], 0, s[4:5]
	s_mov_b32 m0, s37
	s_nop 0
	global_load_lds_dwordx4 v[216:217], off
	v_lshl_add_u64 v[216:217], v[224:225], 0, s[4:5]
	s_mov_b32 m0, s38
	s_nop 0
	global_load_lds_dwordx4 v[216:217], off
	s_waitcnt vmcnt(8)
	s_waitcnt lgkmcnt(0)
	s_barrier
	s_setprio 1
	s_waitcnt lgkmcnt(0)
	v_mfma_f32_16x16x32_bf16 v[62:65], v[152:155], v[184:187], v[62:65]
	v_mfma_f32_16x16x32_bf16 v[54:57], v[160:163], v[184:187], v[54:57]
	v_mfma_f32_16x16x32_bf16 v[46:49], v[152:155], v[192:195], v[46:49]
	v_mfma_f32_16x16x32_bf16 v[38:41], v[160:163], v[192:195], v[38:41]
	v_mfma_f32_16x16x32_bf16 v[30:33], v[152:155], v[200:203], v[30:33]
	v_mfma_f32_16x16x32_bf16 v[22:25], v[160:163], v[200:203], v[22:25]
	v_mfma_f32_16x16x32_bf16 v[14:17], v[152:155], v[208:211], v[14:17]
	v_mfma_f32_16x16x32_bf16 v[6:9], v[160:163], v[208:211], v[6:9]
	v_mfma_f32_16x16x32_bf16 v[62:65], v[156:159], v[188:191], v[62:65]
	v_mfma_f32_16x16x32_bf16 v[54:57], v[164:167], v[188:191], v[54:57]
	v_mfma_f32_16x16x32_bf16 v[46:49], v[156:159], v[196:199], v[46:49]
	v_mfma_f32_16x16x32_bf16 v[38:41], v[164:167], v[196:199], v[38:41]
	v_mfma_f32_16x16x32_bf16 v[30:33], v[156:159], v[204:207], v[30:33]
	v_mfma_f32_16x16x32_bf16 v[22:25], v[164:167], v[204:207], v[22:25]
	v_mfma_f32_16x16x32_bf16 v[14:17], v[156:159], v[212:215], v[14:17]
	v_mfma_f32_16x16x32_bf16 v[6:9], v[164:167], v[212:215], v[6:9]
	s_setprio 0
	s_setprio 1
	v_mfma_f32_16x16x32_bf16 v[58:61], v[168:171], v[184:187], v[58:61]
	v_mfma_f32_16x16x32_bf16 v[50:53], v[176:179], v[184:187], v[50:53]
	v_mfma_f32_16x16x32_bf16 v[42:45], v[168:171], v[192:195], v[42:45]
	v_mfma_f32_16x16x32_bf16 v[34:37], v[176:179], v[192:195], v[34:37]
	v_mfma_f32_16x16x32_bf16 v[26:29], v[168:171], v[200:203], v[26:29]
	v_mfma_f32_16x16x32_bf16 v[18:21], v[176:179], v[200:203], v[18:21]
	v_mfma_f32_16x16x32_bf16 v[10:13], v[168:171], v[208:211], v[10:13]
	v_mfma_f32_16x16x32_bf16 v[2:5], v[176:179], v[208:211], v[2:5]
	v_mfma_f32_16x16x32_bf16 v[58:61], v[172:175], v[188:191], v[58:61]
	v_mfma_f32_16x16x32_bf16 v[50:53], v[180:183], v[188:191], v[50:53]
	v_mfma_f32_16x16x32_bf16 v[42:45], v[172:175], v[196:199], v[42:45]
	v_mfma_f32_16x16x32_bf16 v[34:37], v[180:183], v[196:199], v[34:37]
	v_mfma_f32_16x16x32_bf16 v[26:29], v[172:175], v[204:207], v[26:29]
	v_mfma_f32_16x16x32_bf16 v[18:21], v[180:183], v[204:207], v[18:21]
	v_mfma_f32_16x16x32_bf16 v[10:13], v[172:175], v[212:215], v[10:13]
	v_mfma_f32_16x16x32_bf16 v[2:5], v[180:183], v[212:215], v[2:5]
	s_setprio 0
	s_barrier
	s_add_i32 s50, s50, 2
	s_add_u32 s22, s22, 0x100
	s_addc_u32 s23, s23, 0
	s_add_u32 s48, s48, 0x100
	s_addc_u32 s49, s49, 0
	s_cmp_gt_u32 s50, 29
	s_branch .LBB0_1971
; #define PG8_BAR __builtin_amdgcn_s_barrier()
; DI unsigned pk2(float lo, float hi) { f32x2 v = {lo, hi}; bf16x2_t b = __builtin_convertvector(v, bf16x2_t); return __builtin_bit_cast(unsigned, b); }
; DI float siluf_(float x) { return x * sigmoidf_(x); }
; template <class Epi, class Sched, bool ALIGN_EPI = false, bool SP2 = false>
; __device__ __forceinline__ void gemm_phase(PG8_LAS unsigned char* lds, const Gemm g, const Sched& S, const Epi& E) {
;     ...
;         if constexpr (ALIGN_EPI) { if (wr == 0) PG8_BAR; }
;     DI void operator()(const f32x4 (&acc)[2][2][4][2], const pg8::Unit& u, int wr, int wc, int fr, int fq) const {
;         const int row0 = u.pm * 256 + wr * 64 + fr, col0 = u.pn * 128 + wc * 32 + 8 * fq;
; #pragma unroll
;         for (int ai = 0; ai < 2; ++ai)
; #pragma unroll
;             for (int m = 0; m < 4; ++m) {
;                 const f32x4 g0 = acc[ai][0][m][0], g1 = acc[ai][0][m][1], u0 = acc[ai][1][m][0], u1 = acc[ai][1][m][1];
;                 u32x4 w;
;                 w.x = pk2(siluf_(g0[0]) * u0[0], siluf_(g0[1]) * u0[1]); w.y = pk2(siluf_(g0[2]) * u0[2], siluf_(g0[3]) * u0[3]);
;                 w.z = pk2(siluf_(g1[0]) * u1[0], siluf_(g1[1]) * u1[1]); w.w = pk2(siluf_(g1[2]) * u1[2], siluf_(g1[3]) * u1[3]);
;                 *(u32x4*)(H + (size_t)(row0 + ai * 128 + m * 16) * DFF + col0) = w;
;             }
.Lpeel_after_2:
	s_and_b64 vcc, exec, s[6:7]
	s_cbranch_vccz .LBB0_1974
	s_barrier
.LBB0_1974:
	v_mul_f32_e32 v153, 0xbfb8aa3b, v126
	v_exp_f32_e32 v153, v153
	v_mul_f32_e32 v155, 0xbfb8aa3b, v127
	v_exp_f32_e32 v157, v155
	v_readlane_b32 s22, v253, 45
	v_add_f32_e32 v153, 1.0, v153
	v_rcp_f32_e32 v156, v153
	v_add_f32_e32 v153, 1.0, v157
	v_mul_f32_e32 v157, 0xbfb8aa3b, v128
	v_exp_f32_e32 v158, v157
	v_mul_f32_e32 v157, 0xbfb8aa3b, v129
	v_exp_f32_e32 v159, v157
	v_rcp_f32_e32 v157, v153
	v_add_f32_e32 v153, 1.0, v158
	v_rcp_f32_e32 v158, v153
	v_add_f32_e32 v153, 1.0, v159
	v_rcp_f32_e32 v159, v153
	v_pk_mul_f32 v[126:127], v[126:127], v[156:157]
	v_lshl_or_b32 v154, s43, 7, v148
	v_pk_mul_f32 v[122:123], v[126:127], v[122:123]
	v_pk_mul_f32 v[126:127], v[128:129], v[158:159]
	v_cvt_pk_bf16_f32 v122, v122, v123
	v_mul_f32_e32 v123, 0xbfb8aa3b, v118
	v_pk_mul_f32 v[124:125], v[126:127], v[124:125]
	v_exp_f32_e32 v126, v123
	v_mul_f32_e32 v123, 0xbfb8aa3b, v119
	v_exp_f32_e32 v127, v123
	v_cvt_pk_bf16_f32 v123, v124, v125
	v_add_f32_e32 v124, 1.0, v126
	v_mul_f32_e32 v126, 0xbfb8aa3b, v120
	v_add_f32_e32 v125, 1.0, v127
	v_mul_f32_e32 v127, 0xbfb8aa3b, v121
	v_exp_f32_e32 v126, v126
	v_exp_f32_e32 v127, v127
	v_rcp_f32_e32 v124, v124
	v_rcp_f32_e32 v125, v125
	v_add_f32_e32 v126, 1.0, v126
	v_add_f32_e32 v127, 1.0, v127
	v_rcp_f32_e32 v126, v126
	v_rcp_f32_e32 v127, v127
	v_pk_mul_f32 v[118:119], v[118:119], v[124:125]
	v_readlane_b32 s23, v253, 46
	v_pk_mul_f32 v[114:115], v[118:119], v[114:115]
	v_lshl_add_u32 v152, s20, 8, v1
	v_cvt_pk_bf16_f32 v124, v114, v115
	v_pk_mul_f32 v[114:115], v[120:121], v[126:127]
	v_mul_f32_e32 v120, 0xbfb8aa3b, v110
	v_mul_f32_e32 v121, 0xbfb8aa3b, v111
	v_pk_mul_f32 v[114:115], v[114:115], v[116:117]
	v_exp_f32_e32 v120, v120
	v_exp_f32_e32 v121, v121
	v_ashrrev_i32_e32 v155, 31, v154
	v_cvt_pk_bf16_f32 v125, v114, v115
	v_mov_b64_e32 v[114:115], s[22:23]
	v_mad_i64_i32 v[118:119], s[22:23], v152, s42, v[114:115]
	v_lshlrev_b64 v[116:117], 1, v[154:155]
	v_lshl_add_u64 v[118:119], v[118:119], 0, v[116:117]
	global_store_dwordx4 v[118:119], v[122:125], off
	v_add_f32_e32 v118, 1.0, v120
	v_add_f32_e32 v119, 1.0, v121
	v_mul_f32_e32 v120, 0xbfb8aa3b, v112
	v_mul_f32_e32 v121, 0xbfb8aa3b, v113
	v_exp_f32_e32 v120, v120
	v_exp_f32_e32 v121, v121
	v_rcp_f32_e32 v118, v118
	v_rcp_f32_e32 v119, v119
	v_add_f32_e32 v120, 1.0, v120
	v_add_f32_e32 v121, 1.0, v121
	v_rcp_f32_e32 v120, v120
	v_rcp_f32_e32 v121, v121
	v_pk_mul_f32 v[110:111], v[110:111], v[118:119]
	v_readlane_b32 s46, v253, 17
	v_pk_mul_f32 v[106:107], v[110:111], v[106:107]
	v_pk_mul_f32 v[110:111], v[112:113], v[120:121]
	v_cvt_pk_bf16_f32 v106, v106, v107
	v_mul_f32_e32 v107, 0xbfb8aa3b, v102
	v_pk_mul_f32 v[108:109], v[110:111], v[108:109]
	v_exp_f32_e32 v110, v107
	v_mul_f32_e32 v107, 0xbfb8aa3b, v103
	v_exp_f32_e32 v111, v107
	v_cvt_pk_bf16_f32 v107, v108, v109
	v_add_f32_e32 v108, 1.0, v110
	v_mul_f32_e32 v110, 0xbfb8aa3b, v104
	v_add_f32_e32 v109, 1.0, v111
	v_mul_f32_e32 v111, 0xbfb8aa3b, v105
	v_exp_f32_e32 v110, v110
	v_exp_f32_e32 v111, v111
	v_rcp_f32_e32 v108, v108
	v_rcp_f32_e32 v109, v109
	v_add_f32_e32 v110, 1.0, v110
	v_add_f32_e32 v111, 1.0, v111
	v_rcp_f32_e32 v110, v110
	v_rcp_f32_e32 v111, v111
	v_pk_mul_f32 v[102:103], v[102:103], v[108:109]
	s_andn2_b64 vcc, exec, s[0:1]
	v_pk_mul_f32 v[98:99], v[102:103], v[98:99]
	s_mov_b64 s[0:1], -1
	v_cvt_pk_bf16_f32 v108, v98, v99
	v_pk_mul_f32 v[98:99], v[104:105], v[110:111]
	v_readlane_b32 s47, v253, 18
	v_pk_mul_f32 v[98:99], v[98:99], v[100:101]
	v_mul_f32_e32 v100, 0xbfb8aa3b, v94
	v_mul_f32_e32 v101, 0xbfb8aa3b, v95
	v_exp_f32_e32 v100, v100
	v_exp_f32_e32 v101, v101
	v_cvt_pk_bf16_f32 v109, v98, v99
	v_or_b32_e32 v98, 16, v152
	v_mad_i64_i32 v[98:99], s[22:23], v98, s42, v[114:115]
	v_lshl_add_u64 v[98:99], v[98:99], 0, v[116:117]
	global_store_dwordx4 v[98:99], v[106:109], off
	v_add_f32_e32 v98, 1.0, v100
	v_add_f32_e32 v99, 1.0, v101
	v_mul_f32_e32 v100, 0xbfb8aa3b, v96
	v_mul_f32_e32 v101, 0xbfb8aa3b, v97
	v_exp_f32_e32 v100, v100
	v_exp_f32_e32 v101, v101
	v_rcp_f32_e32 v98, v98
	v_rcp_f32_e32 v99, v99
	v_add_f32_e32 v100, 1.0, v100
	v_add_f32_e32 v101, 1.0, v101
	v_rcp_f32_e32 v100, v100
	v_rcp_f32_e32 v101, v101
	v_pk_mul_f32 v[94:95], v[94:95], v[98:99]
	s_nop 0
	v_pk_mul_f32 v[90:91], v[94:95], v[90:91]
	v_pk_mul_f32 v[94:95], v[96:97], v[100:101]
	v_cvt_pk_bf16_f32 v90, v90, v91
	v_mul_f32_e32 v91, 0xbfb8aa3b, v86
	v_pk_mul_f32 v[92:93], v[94:95], v[92:93]
	v_exp_f32_e32 v94, v91
	v_mul_f32_e32 v91, 0xbfb8aa3b, v87
	v_exp_f32_e32 v95, v91
	v_cvt_pk_bf16_f32 v91, v92, v93
	v_add_f32_e32 v92, 1.0, v94
	v_mul_f32_e32 v94, 0xbfb8aa3b, v88
	v_add_f32_e32 v93, 1.0, v95
	v_mul_f32_e32 v95, 0xbfb8aa3b, v89
	v_exp_f32_e32 v94, v94
	v_exp_f32_e32 v95, v95
	v_rcp_f32_e32 v92, v92
	v_rcp_f32_e32 v93, v93
	v_add_f32_e32 v94, 1.0, v94
	v_add_f32_e32 v95, 1.0, v95
	v_rcp_f32_e32 v94, v94
	v_rcp_f32_e32 v95, v95
	v_pk_mul_f32 v[86:87], v[86:87], v[92:93]
	s_nop 0
	v_pk_mul_f32 v[82:83], v[86:87], v[82:83]
	s_nop 0
	v_cvt_pk_bf16_f32 v92, v82, v83
	v_pk_mul_f32 v[82:83], v[88:89], v[94:95]
	s_nop 0
	v_pk_mul_f32 v[82:83], v[82:83], v[84:85]
	v_mul_f32_e32 v84, 0xbfb8aa3b, v78
	v_mul_f32_e32 v85, 0xbfb8aa3b, v79
	v_exp_f32_e32 v84, v84
	v_exp_f32_e32 v85, v85
	v_cvt_pk_bf16_f32 v93, v82, v83
	v_or_b32_e32 v82, 32, v152
	v_mad_i64_i32 v[82:83], s[22:23], v82, s42, v[114:115]
	v_lshl_add_u64 v[82:83], v[82:83], 0, v[116:117]
	global_store_dwordx4 v[82:83], v[90:93], off
	v_add_f32_e32 v82, 1.0, v84
	v_add_f32_e32 v83, 1.0, v85
	v_mul_f32_e32 v84, 0xbfb8aa3b, v80
	v_mul_f32_e32 v85, 0xbfb8aa3b, v81
; DI unsigned pk2(float lo, float hi) { f32x2 v = {lo, hi}; bf16x2_t b = __builtin_convertvector(v, bf16x2_t); return __builtin_bit_cast(unsigned, b); }
; DI float siluf_(float x) { return x * sigmoidf_(x); }
;     DI void operator()(const f32x4 (&acc)[2][2][4][2], const pg8::Unit& u, int wr, int wc, int fr, int fq) const {
;         const int row0 = u.pm * 256 + wr * 64 + fr, col0 = u.pn * 128 + wc * 32 + 8 * fq;
; #pragma unroll
;         for (int ai = 0; ai < 2; ++ai)
; #pragma unroll
;             for (int m = 0; m < 4; ++m) {
;                 const f32x4 g0 = acc[ai][0][m][0], g1 = acc[ai][0][m][1], u0 = acc[ai][1][m][0], u1 = acc[ai][1][m][1];
;                 u32x4 w;
;                 w.x = pk2(siluf_(g0[0]) * u0[0], siluf_(g0[1]) * u0[1]); w.y = pk2(siluf_(g0[2]) * u0[2], siluf_(g0[3]) * u0[3]);
;                 w.z = pk2(siluf_(g1[0]) * u1[0], siluf_(g1[1]) * u1[1]); w.w = pk2(siluf_(g1[2]) * u1[2], siluf_(g1[3]) * u1[3]);
;                 *(u32x4*)(H + (size_t)(row0 + ai * 128 + m * 16) * DFF + col0) = w;
;             }
	v_exp_f32_e32 v84, v84
	v_exp_f32_e32 v85, v85
	v_rcp_f32_e32 v82, v82
	v_rcp_f32_e32 v83, v83
	v_add_f32_e32 v84, 1.0, v84
	v_add_f32_e32 v85, 1.0, v85
	v_rcp_f32_e32 v84, v84
	v_rcp_f32_e32 v85, v85
	v_pk_mul_f32 v[78:79], v[78:79], v[82:83]
	s_nop 0
	v_pk_mul_f32 v[74:75], v[78:79], v[74:75]
	v_pk_mul_f32 v[78:79], v[80:81], v[84:85]
	v_cvt_pk_bf16_f32 v74, v74, v75
	v_mul_f32_e32 v75, 0xbfb8aa3b, v70
	v_pk_mul_f32 v[76:77], v[78:79], v[76:77]
	v_exp_f32_e32 v78, v75
	v_mul_f32_e32 v75, 0xbfb8aa3b, v71
	v_exp_f32_e32 v79, v75
	v_cvt_pk_bf16_f32 v75, v76, v77
	v_add_f32_e32 v76, 1.0, v78
	v_mul_f32_e32 v78, 0xbfb8aa3b, v72
	v_add_f32_e32 v77, 1.0, v79
	v_mul_f32_e32 v79, 0xbfb8aa3b, v73
	v_exp_f32_e32 v78, v78
	v_exp_f32_e32 v79, v79
	v_rcp_f32_e32 v76, v76
	v_rcp_f32_e32 v77, v77
	v_add_f32_e32 v78, 1.0, v78
	v_add_f32_e32 v79, 1.0, v79
	v_rcp_f32_e32 v78, v78
	v_rcp_f32_e32 v79, v79
	v_pk_mul_f32 v[70:71], v[70:71], v[76:77]
	s_nop 0
	v_pk_mul_f32 v[66:67], v[70:71], v[66:67]
	v_add_u32_e32 v70, 0x80, v152
	v_cvt_pk_bf16_f32 v76, v66, v67
	v_pk_mul_f32 v[66:67], v[72:73], v[78:79]
	s_nop 0
	v_pk_mul_f32 v[66:67], v[66:67], v[68:69]
	v_mul_f32_e32 v68, 0xbfb8aa3b, v64
	v_cvt_pk_bf16_f32 v77, v66, v67
	v_or_b32_e32 v66, 48, v152
	v_mad_i64_i32 v[66:67], s[22:23], v66, s42, v[114:115]
	v_lshl_add_u64 v[66:67], v[66:67], 0, v[116:117]
	global_store_dwordx4 v[66:67], v[74:77], off
	v_mul_f32_e32 v66, 0xbfb8aa3b, v62
	v_mul_f32_e32 v67, 0xbfb8aa3b, v63
	v_exp_f32_e32 v66, v66
	v_exp_f32_e32 v67, v67
	v_mul_f32_e32 v69, 0xbfb8aa3b, v65
	v_exp_f32_e32 v68, v68
	v_exp_f32_e32 v69, v69
	v_add_f32_e32 v66, 1.0, v66
	v_add_f32_e32 v67, 1.0, v67
	v_rcp_f32_e32 v66, v66
	v_rcp_f32_e32 v67, v67
	v_add_f32_e32 v68, 1.0, v68
	v_add_f32_e32 v69, 1.0, v69
	v_rcp_f32_e32 v68, v68
	v_rcp_f32_e32 v69, v69
	v_pk_mul_f32 v[62:63], v[62:63], v[66:67]
	s_nop 0
	v_pk_mul_f32 v[58:59], v[62:63], v[58:59]
	v_pk_mul_f32 v[62:63], v[64:65], v[68:69]
	v_cvt_pk_bf16_f32 v58, v58, v59
	v_mul_f32_e32 v59, 0xbfb8aa3b, v54
	v_pk_mul_f32 v[60:61], v[62:63], v[60:61]
	v_exp_f32_e32 v62, v59
	v_mul_f32_e32 v59, 0xbfb8aa3b, v55
	v_exp_f32_e32 v63, v59
	v_cvt_pk_bf16_f32 v59, v60, v61
	v_add_f32_e32 v60, 1.0, v62
	v_mul_f32_e32 v62, 0xbfb8aa3b, v56
	v_add_f32_e32 v61, 1.0, v63
	v_mul_f32_e32 v63, 0xbfb8aa3b, v57
	v_exp_f32_e32 v62, v62
	v_exp_f32_e32 v63, v63
	v_rcp_f32_e32 v60, v60
	v_rcp_f32_e32 v61, v61
	v_add_f32_e32 v62, 1.0, v62
	v_add_f32_e32 v63, 1.0, v63
	v_rcp_f32_e32 v62, v62
	v_rcp_f32_e32 v63, v63
	v_pk_mul_f32 v[54:55], v[54:55], v[60:61]
	s_nop 0
	v_pk_mul_f32 v[50:51], v[54:55], v[50:51]
	s_nop 0
	v_cvt_pk_bf16_f32 v60, v50, v51
	v_pk_mul_f32 v[50:51], v[56:57], v[62:63]
	s_nop 0
	v_pk_mul_f32 v[50:51], v[50:51], v[52:53]
	v_mul_f32_e32 v52, 0xbfb8aa3b, v46
	v_mul_f32_e32 v53, 0xbfb8aa3b, v47
	v_exp_f32_e32 v52, v52
	v_exp_f32_e32 v53, v53
	v_cvt_pk_bf16_f32 v61, v50, v51
	v_mad_i64_i32 v[50:51], s[22:23], v70, s42, v[114:115]
	v_lshl_add_u64 v[50:51], v[50:51], 0, v[116:117]
	global_store_dwordx4 v[50:51], v[58:61], off
	v_add_f32_e32 v50, 1.0, v52
	v_add_f32_e32 v51, 1.0, v53
	v_mul_f32_e32 v52, 0xbfb8aa3b, v48
	v_mul_f32_e32 v53, 0xbfb8aa3b, v49
	v_exp_f32_e32 v52, v52
	v_exp_f32_e32 v53, v53
	v_rcp_f32_e32 v50, v50
	v_rcp_f32_e32 v51, v51
	v_add_f32_e32 v52, 1.0, v52
	v_add_f32_e32 v53, 1.0, v53
	v_rcp_f32_e32 v52, v52
	v_rcp_f32_e32 v53, v53
	v_pk_mul_f32 v[46:47], v[46:47], v[50:51]
	s_nop 0
	v_pk_mul_f32 v[42:43], v[46:47], v[42:43]
	v_pk_mul_f32 v[46:47], v[48:49], v[52:53]
	v_cvt_pk_bf16_f32 v42, v42, v43
	v_mul_f32_e32 v43, 0xbfb8aa3b, v38
	v_pk_mul_f32 v[44:45], v[46:47], v[44:45]
	v_exp_f32_e32 v46, v43
	v_mul_f32_e32 v43, 0xbfb8aa3b, v39
	v_exp_f32_e32 v47, v43
	v_cvt_pk_bf16_f32 v43, v44, v45
	v_add_f32_e32 v44, 1.0, v46
	v_mul_f32_e32 v46, 0xbfb8aa3b, v40
	v_add_f32_e32 v45, 1.0, v47
	v_mul_f32_e32 v47, 0xbfb8aa3b, v41
	v_exp_f32_e32 v46, v46
; DI unsigned pk2(float lo, float hi) { f32x2 v = {lo, hi}; bf16x2_t b = __builtin_convertvector(v, bf16x2_t); return __builtin_bit_cast(unsigned, b); }
; DI float siluf_(float x) { return x * sigmoidf_(x); }
;     DI void operator()(const f32x4 (&acc)[2][2][4][2], const pg8::Unit& u, int wr, int wc, int fr, int fq) const {
;         const int row0 = u.pm * 256 + wr * 64 + fr, col0 = u.pn * 128 + wc * 32 + 8 * fq;
; #pragma unroll
;         for (int ai = 0; ai < 2; ++ai)
; #pragma unroll
;             for (int m = 0; m < 4; ++m) {
;                 const f32x4 g0 = acc[ai][0][m][0], g1 = acc[ai][0][m][1], u0 = acc[ai][1][m][0], u1 = acc[ai][1][m][1];
;                 u32x4 w;
;                 w.x = pk2(siluf_(g0[0]) * u0[0], siluf_(g0[1]) * u0[1]); w.y = pk2(siluf_(g0[2]) * u0[2], siluf_(g0[3]) * u0[3]);
;                 w.z = pk2(siluf_(g1[0]) * u1[0], siluf_(g1[1]) * u1[1]); w.w = pk2(siluf_(g1[2]) * u1[2], siluf_(g1[3]) * u1[3]);
;                 *(u32x4*)(H + (size_t)(row0 + ai * 128 + m * 16) * DFF + col0) = w;
;             }
	v_exp_f32_e32 v47, v47
	v_rcp_f32_e32 v44, v44
	v_rcp_f32_e32 v45, v45
	v_add_f32_e32 v46, 1.0, v46
	v_add_f32_e32 v47, 1.0, v47
	v_rcp_f32_e32 v46, v46
	v_rcp_f32_e32 v47, v47
	v_pk_mul_f32 v[38:39], v[38:39], v[44:45]
	s_nop 0
	v_pk_mul_f32 v[34:35], v[38:39], v[34:35]
	s_nop 0
	v_cvt_pk_bf16_f32 v44, v34, v35
	v_pk_mul_f32 v[34:35], v[40:41], v[46:47]
	s_nop 0
	v_pk_mul_f32 v[34:35], v[34:35], v[36:37]
	v_mul_f32_e32 v36, 0xbfb8aa3b, v30
	v_mul_f32_e32 v37, 0xbfb8aa3b, v31
	v_exp_f32_e32 v36, v36
	v_exp_f32_e32 v37, v37
	v_cvt_pk_bf16_f32 v45, v34, v35
	v_add_u32_e32 v34, 0x90, v152
	v_mad_i64_i32 v[34:35], s[22:23], v34, s42, v[114:115]
	v_lshl_add_u64 v[34:35], v[34:35], 0, v[116:117]
	global_store_dwordx4 v[34:35], v[42:45], off
	v_add_f32_e32 v34, 1.0, v36
	v_add_f32_e32 v35, 1.0, v37
	v_mul_f32_e32 v36, 0xbfb8aa3b, v32
	v_mul_f32_e32 v37, 0xbfb8aa3b, v33
	v_exp_f32_e32 v36, v36
	v_exp_f32_e32 v37, v37
	v_rcp_f32_e32 v34, v34
	v_rcp_f32_e32 v35, v35
	v_add_f32_e32 v36, 1.0, v36
	v_add_f32_e32 v37, 1.0, v37
	v_rcp_f32_e32 v36, v36
	v_rcp_f32_e32 v37, v37
	v_pk_mul_f32 v[30:31], v[30:31], v[34:35]
	s_nop 0
	v_pk_mul_f32 v[26:27], v[30:31], v[26:27]
	v_pk_mul_f32 v[30:31], v[32:33], v[36:37]
	v_cvt_pk_bf16_f32 v26, v26, v27
	v_mul_f32_e32 v27, 0xbfb8aa3b, v22
	v_pk_mul_f32 v[28:29], v[30:31], v[28:29]
	v_exp_f32_e32 v30, v27
	v_mul_f32_e32 v27, 0xbfb8aa3b, v23
	v_exp_f32_e32 v31, v27
	v_cvt_pk_bf16_f32 v27, v28, v29
	v_add_f32_e32 v28, 1.0, v30
	v_mul_f32_e32 v30, 0xbfb8aa3b, v24
	v_add_f32_e32 v29, 1.0, v31
	v_mul_f32_e32 v31, 0xbfb8aa3b, v25
	v_exp_f32_e32 v30, v30
	v_exp_f32_e32 v31, v31
	v_rcp_f32_e32 v28, v28
	v_rcp_f32_e32 v29, v29
	v_add_f32_e32 v30, 1.0, v30
	v_add_f32_e32 v31, 1.0, v31
	v_rcp_f32_e32 v30, v30
	v_rcp_f32_e32 v31, v31
	v_pk_mul_f32 v[22:23], v[22:23], v[28:29]
	s_nop 0
	v_pk_mul_f32 v[18:19], v[22:23], v[18:19]
	s_nop 0
	v_cvt_pk_bf16_f32 v28, v18, v19
	v_pk_mul_f32 v[18:19], v[24:25], v[30:31]
	s_nop 0
	v_pk_mul_f32 v[18:19], v[18:19], v[20:21]
	v_mul_f32_e32 v20, 0xbfb8aa3b, v14
	v_mul_f32_e32 v21, 0xbfb8aa3b, v15
	v_exp_f32_e32 v20, v20
	v_exp_f32_e32 v21, v21
	v_cvt_pk_bf16_f32 v29, v18, v19
	v_add_u32_e32 v18, 0xa0, v152
	v_mad_i64_i32 v[18:19], s[22:23], v18, s42, v[114:115]
	v_lshl_add_u64 v[18:19], v[18:19], 0, v[116:117]
	global_store_dwordx4 v[18:19], v[26:29], off
	v_add_f32_e32 v18, 1.0, v20
	v_add_f32_e32 v19, 1.0, v21
	v_mul_f32_e32 v20, 0xbfb8aa3b, v16
	v_mul_f32_e32 v21, 0xbfb8aa3b, v17
	v_exp_f32_e32 v20, v20
	v_exp_f32_e32 v21, v21
	v_rcp_f32_e32 v18, v18
	v_rcp_f32_e32 v19, v19
	v_add_f32_e32 v20, 1.0, v20
	v_add_f32_e32 v21, 1.0, v21
	v_rcp_f32_e32 v20, v20
	v_rcp_f32_e32 v21, v21
	v_pk_mul_f32 v[14:15], v[14:15], v[18:19]
	s_nop 0
	v_pk_mul_f32 v[10:11], v[14:15], v[10:11]
	v_pk_mul_f32 v[14:15], v[16:17], v[20:21]
	v_cvt_pk_bf16_f32 v10, v10, v11
	v_mul_f32_e32 v11, 0xbfb8aa3b, v6
	v_pk_mul_f32 v[12:13], v[14:15], v[12:13]
	v_exp_f32_e32 v14, v11
	v_mul_f32_e32 v11, 0xbfb8aa3b, v7
	v_exp_f32_e32 v15, v11
	v_cvt_pk_bf16_f32 v11, v12, v13
	v_add_f32_e32 v12, 1.0, v14
	v_mul_f32_e32 v14, 0xbfb8aa3b, v8
	v_add_f32_e32 v13, 1.0, v15
	v_mul_f32_e32 v15, 0xbfb8aa3b, v9
	v_exp_f32_e32 v14, v14
	v_exp_f32_e32 v15, v15
	v_rcp_f32_e32 v12, v12
	v_rcp_f32_e32 v13, v13
	v_add_f32_e32 v14, 1.0, v14
	v_add_f32_e32 v15, 1.0, v15
	v_rcp_f32_e32 v14, v14
	v_rcp_f32_e32 v15, v15
	v_pk_mul_f32 v[6:7], v[6:7], v[12:13]
	s_nop 0
	v_pk_mul_f32 v[2:3], v[6:7], v[2:3]
	s_nop 0
	v_cvt_pk_bf16_f32 v12, v2, v3
	v_pk_mul_f32 v[2:3], v[8:9], v[14:15]
	s_nop 0
	v_pk_mul_f32 v[2:3], v[2:3], v[4:5]
	s_nop 0
	v_cvt_pk_bf16_f32 v13, v2, v3
	v_add_u32_e32 v2, 0xb0, v152
	v_mad_i64_i32 v[2:3], s[22:23], v2, s42, v[114:115]
	v_lshl_add_u64 v[2:3], v[2:3], 0, v[116:117]
	global_store_dwordx4 v[2:3], v[10:13], off
	s_mov_b32 s98, 1
	s_cbranch_vccnz .LBB0_1967
	s_andn2_b64 vcc, exec, s[2:3]
	s_cbranch_vccnz .LBB0_1966
	s_barrier
	s_branch .LBB0_1966
